# all 7 big GEMM K-loops: swizzled LDS, decoupled loads, ks1 fragment prefetch under ks0 MFMAs, LDS writes under ks1 MFMAs
# speedup vs baseline: 1.0583x; 1.0207x over previous
.LBB0_466:
	s_bitcmp1_b32 s4, 0
	s_cselect_b32 s21, 0x12000, 0
	v_or_b32_e32 v184, s21, v206
	v_add_u32_e32 v185, v184, v0
	v_add_u32_e32 v184, v184, v167
	ds_read_b128 v[210:213], v185
	ds_read_b128 v[214:217], v185 offset:2048
	ds_read_b128 v[218:221], v185 offset:4096
	ds_read_b128 v[222:225], v185 offset:6144
	ds_read_b128 v[226:229], v184 offset:32768
	ds_read_b128 v[230:233], v184 offset:34816
	ds_read_b128 v[234:237], v184 offset:36864
	ds_read_b128 v[238:241], v184 offset:38912
	ds_read_b128 v[242:245], v184 offset:40960
	ds_read_b128 v[246:249], v184 offset:43008
	ds_read_b128 v[198:201], v184 offset:45056
	ds_read_b128 v[184:187], v184 offset:47104
	s_add_i32 s10, s4, 1
	s_bitcmp1_b32 s10, 0
	s_cselect_b32 s23, 0x12000, 0
	v_add_u32_e32 v171, s23, v166
	v_xor_b32_e32 v169, 64, v206
	v_add3_u32 v169, s21, v167, v169
	s_waitcnt lgkmcnt(7)
	v_mfma_f32_16x16x32_bf16 v[158:161], v[226:229], v[210:213], v[158:161]
	v_mfma_f32_16x16x32_bf16 v[94:97], v[226:229], v[214:217], v[94:97]
	v_mfma_f32_16x16x32_bf16 v[62:65], v[226:229], v[218:221], v[62:65]
	v_mfma_f32_16x16x32_bf16 v[30:33], v[226:229], v[222:225], v[30:33]
	ds_read_b128 v[226:229], v169 offset:32768
	s_waitcnt lgkmcnt(7)
	v_mfma_f32_16x16x32_bf16 v[154:157], v[230:233], v[210:213], v[154:157]
	v_mfma_f32_16x16x32_bf16 v[90:93], v[230:233], v[214:217], v[90:93]
	v_mfma_f32_16x16x32_bf16 v[58:61], v[230:233], v[218:221], v[58:61]
	v_mfma_f32_16x16x32_bf16 v[26:29], v[230:233], v[222:225], v[26:29]
	ds_read_b128 v[230:233], v169 offset:34816
	s_waitcnt lgkmcnt(7)
	v_mfma_f32_16x16x32_bf16 v[150:153], v[234:237], v[210:213], v[150:153]
	v_mfma_f32_16x16x32_bf16 v[86:89], v[234:237], v[214:217], v[86:89]
	v_mfma_f32_16x16x32_bf16 v[54:57], v[234:237], v[218:221], v[54:57]
	v_mfma_f32_16x16x32_bf16 v[22:25], v[234:237], v[222:225], v[22:25]
	ds_read_b128 v[234:237], v169 offset:36864
	s_waitcnt lgkmcnt(7)
	v_mfma_f32_16x16x32_bf16 v[146:149], v[238:241], v[210:213], v[146:149]
	v_mfma_f32_16x16x32_bf16 v[82:85], v[238:241], v[214:217], v[82:85]
	v_mfma_f32_16x16x32_bf16 v[50:53], v[238:241], v[218:221], v[50:53]
	v_mfma_f32_16x16x32_bf16 v[18:21], v[238:241], v[222:225], v[18:21]
	ds_read_b128 v[238:241], v169 offset:38912
	s_waitcnt lgkmcnt(7)
	v_mfma_f32_16x16x32_bf16 v[142:145], v[242:245], v[210:213], v[142:145]
	v_mfma_f32_16x16x32_bf16 v[78:81], v[242:245], v[214:217], v[78:81]
	v_mfma_f32_16x16x32_bf16 v[46:49], v[242:245], v[218:221], v[46:49]
	v_mfma_f32_16x16x32_bf16 v[14:17], v[242:245], v[222:225], v[14:17]
	ds_read_b128 v[242:245], v169 offset:40960
	s_waitcnt lgkmcnt(7)
	v_mfma_f32_16x16x32_bf16 v[138:141], v[246:249], v[210:213], v[138:141]
	v_mfma_f32_16x16x32_bf16 v[74:77], v[246:249], v[214:217], v[74:77]
	v_mfma_f32_16x16x32_bf16 v[42:45], v[246:249], v[218:221], v[42:45]
	v_mfma_f32_16x16x32_bf16 v[10:13], v[246:249], v[222:225], v[10:13]
	ds_read_b128 v[246:249], v169 offset:43008
	s_waitcnt lgkmcnt(7)
	v_mfma_f32_16x16x32_bf16 v[102:105], v[198:201], v[210:213], v[102:105]
	v_mfma_f32_16x16x32_bf16 v[70:73], v[198:201], v[214:217], v[70:73]
	v_mfma_f32_16x16x32_bf16 v[38:41], v[198:201], v[218:221], v[38:41]
	v_mfma_f32_16x16x32_bf16 v[6:9], v[198:201], v[222:225], v[6:9]
	ds_read_b128 v[198:201], v169 offset:45056
	s_waitcnt lgkmcnt(7)
	v_mfma_f32_16x16x32_bf16 v[98:101], v[184:187], v[210:213], v[98:101]
	v_mfma_f32_16x16x32_bf16 v[66:69], v[184:187], v[214:217], v[66:69]
	v_xor_b32_e32 v169, 64, v206
	v_add3_u32 v169, s21, v0, v169
	ds_read_b128 v[210:213], v169
	ds_read_b128 v[214:217], v169 offset:2048
	v_mfma_f32_16x16x32_bf16 v[34:37], v[184:187], v[218:221], v[34:37]
	ds_read_b128 v[218:221], v169 offset:4096
	v_mfma_f32_16x16x32_bf16 v[2:5], v[184:187], v[222:225], v[2:5]
	ds_read_b128 v[222:225], v169 offset:6144
	v_xor_b32_e32 v169, 64, v206
	v_add3_u32 v169, s21, v167, v169
	ds_read_b128 v[184:187], v169 offset:47104
	s_waitcnt lgkmcnt(1)
	v_mfma_f32_16x16x32_bf16 v[158:161], v[226:229], v[210:213], v[158:161]
	v_mfma_f32_16x16x32_bf16 v[94:97], v[226:229], v[214:217], v[94:97]
	v_mfma_f32_16x16x32_bf16 v[62:65], v[226:229], v[218:221], v[62:65]
	v_mfma_f32_16x16x32_bf16 v[30:33], v[226:229], v[222:225], v[30:33]
	s_waitcnt vmcnt(7)
	ds_write_b128 v171, v[114:117]
	v_mfma_f32_16x16x32_bf16 v[154:157], v[230:233], v[210:213], v[154:157]
	v_mfma_f32_16x16x32_bf16 v[90:93], v[230:233], v[214:217], v[90:93]
	global_load_dwordx4 v[114:117], v168, vcc offset:256
	v_mfma_f32_16x16x32_bf16 v[58:61], v[230:233], v[218:221], v[58:61]
	v_mfma_f32_16x16x32_bf16 v[26:29], v[230:233], v[222:225], v[26:29]
	s_waitcnt vmcnt(7)
	ds_write_b128 v171, v[106:109] offset:8192
	v_mfma_f32_16x16x32_bf16 v[150:153], v[234:237], v[210:213], v[150:153]
	v_mfma_f32_16x16x32_bf16 v[86:89], v[234:237], v[214:217], v[86:89]
	v_add_u32_e32 v106, s34, v168
	global_load_dwordx4 v[106:109], v106, vcc offset:256
	v_mfma_f32_16x16x32_bf16 v[54:57], v[234:237], v[218:221], v[54:57]
	v_mfma_f32_16x16x32_bf16 v[22:25], v[234:237], v[222:225], v[22:25]
	s_waitcnt vmcnt(7)
	ds_write_b128 v171, v[110:113] offset:16384
	v_mfma_f32_16x16x32_bf16 v[146:149], v[238:241], v[210:213], v[146:149]
	v_mfma_f32_16x16x32_bf16 v[82:85], v[238:241], v[214:217], v[82:85]
	v_add_u32_e32 v110, s35, v168
	global_load_dwordx4 v[110:113], v110, vcc offset:256
	v_mfma_f32_16x16x32_bf16 v[50:53], v[238:241], v[218:221], v[50:53]
	v_mfma_f32_16x16x32_bf16 v[18:21], v[238:241], v[222:225], v[18:21]
	s_waitcnt vmcnt(7)
	ds_write_b128 v171, v[126:129] offset:24576
	v_mfma_f32_16x16x32_bf16 v[142:145], v[242:245], v[210:213], v[142:145]
	v_mfma_f32_16x16x32_bf16 v[78:81], v[242:245], v[214:217], v[78:81]
	v_add_u32_e32 v126, s36, v168
	global_load_dwordx4 v[126:129], v126, vcc offset:256
	v_mfma_f32_16x16x32_bf16 v[46:49], v[242:245], v[218:221], v[46:49]
	v_mfma_f32_16x16x32_bf16 v[14:17], v[242:245], v[222:225], v[14:17]
	s_waitcnt vmcnt(7)
	ds_write_b128 v171, v[122:125] offset:32768
	v_mfma_f32_16x16x32_bf16 v[138:141], v[246:249], v[210:213], v[138:141]
	v_mfma_f32_16x16x32_bf16 v[74:77], v[246:249], v[214:217], v[74:77]
	global_load_dwordx4 v[122:125], v170, s[100:101] offset:256
	v_mfma_f32_16x16x32_bf16 v[42:45], v[246:249], v[218:221], v[42:45]
	v_mfma_f32_16x16x32_bf16 v[10:13], v[246:249], v[222:225], v[10:13]
	s_waitcnt vmcnt(7)
	ds_write_b128 v171, v[118:121] offset:40960
	v_mfma_f32_16x16x32_bf16 v[102:105], v[198:201], v[210:213], v[102:105]
	v_mfma_f32_16x16x32_bf16 v[70:73], v[198:201], v[214:217], v[70:73]
	v_add_u32_e32 v118, s34, v170
	global_load_dwordx4 v[118:121], v118, s[100:101] offset:256
	v_mfma_f32_16x16x32_bf16 v[38:41], v[198:201], v[218:221], v[38:41]
	v_mfma_f32_16x16x32_bf16 v[6:9], v[198:201], v[222:225], v[6:9]
	s_waitcnt vmcnt(7)
	ds_write_b128 v171, v[134:137] offset:49152
	s_waitcnt lgkmcnt(7)
	v_mfma_f32_16x16x32_bf16 v[98:101], v[184:187], v[210:213], v[98:101]
	v_mfma_f32_16x16x32_bf16 v[66:69], v[184:187], v[214:217], v[66:69]
	v_add_u32_e32 v134, s35, v170
	global_load_dwordx4 v[134:137], v134, s[100:101] offset:256
	v_mfma_f32_16x16x32_bf16 v[34:37], v[184:187], v[218:221], v[34:37]
	v_mfma_f32_16x16x32_bf16 v[2:5], v[184:187], v[222:225], v[2:5]
	s_waitcnt vmcnt(7)
	ds_write_b128 v171, v[130:133] offset:57344
	v_add_u32_e32 v130, s36, v170
	global_load_dwordx4 v[130:133], v130, s[100:101] offset:256
	v_add_u32_e32 v168, 0x80, v168
	v_add_u32_e32 v170, 0x80, v170
	s_waitcnt lgkmcnt(0)
	s_barrier
	s_cmp_eq_u32 s10, 16
	s_mov_b32 s4, s10
	s_cbranch_scc0 .LBB0_466
	s_waitcnt vmcnt(6)
	v_mul_f32_e32 v109, 0xbfb8aa3b, v158
	v_exp_f32_e32 v109, v109
	s_waitcnt vmcnt(5)
	v_mul_f32_e32 v111, 0xbfb8aa3b, v159
	v_exp_f32_e32 v111, v111
	v_mul_f32_e32 v115, 0xbfb8aa3b, v161
	v_add_f32_e32 v109, 1.0, v109
	v_rcp_f32_e32 v114, v109
	v_add_f32_e32 v109, 1.0, v111
	v_mul_f32_e32 v111, 0xbfb8aa3b, v160
	v_exp_f32_e32 v111, v111
	v_exp_f32_e32 v117, v115
	v_rcp_f32_e32 v116, v109
	s_waitcnt vmcnt(2)
	v_mov_b32_e32 v118, v158
	v_add_f32_e32 v109, 1.0, v111
	v_rcp_f32_e32 v115, v109
	v_add_f32_e32 v109, 1.0, v117
	v_rcp_f32_e32 v117, v109
	v_mov_b32_e32 v119, v160
	v_pk_mul_f32 v[114:115], v[118:119], v[114:115]
	v_mov_b32_e32 v118, v154
	v_mov_b32_e32 v119, v156
	v_mov_b32_e32 v160, v159
	v_pk_mul_f32 v[114:115], v[118:119], v[114:115]
	v_pk_mul_f32 v[116:117], v[160:161], v[116:117]
	v_mov_b32_e32 v156, v155
	v_pk_mul_f32 v[116:117], v[156:157], v[116:117]
	v_and_b32_sdwa v111, v115, v177 dst_sel:DWORD dst_unused:UNUSED_PAD src0_sel:WORD_1 src1_sel:DWORD
	v_and_b32_sdwa v118, v114, v177 dst_sel:DWORD dst_unused:UNUSED_PAD src0_sel:WORD_1 src1_sel:DWORD
	v_add3_u32 v111, v115, v111, s28
	v_and_b32_sdwa v115, v117, v177 dst_sel:DWORD dst_unused:UNUSED_PAD src0_sel:WORD_1 src1_sel:DWORD
	v_add3_u32 v114, v114, v118, s28
	v_and_b32_sdwa v118, v116, v177 dst_sel:DWORD dst_unused:UNUSED_PAD src0_sel:WORD_1 src1_sel:DWORD
	v_add3_u32 v115, v117, v115, s28
	v_or_b32_e32 v106, s7, v207
	v_add3_u32 v116, v116, v118, s28
	v_and_b32_e32 v115, 0xffff0000, v115
	v_ashrrev_i32_e32 v106, 1, v106
	v_and_b32_e32 v116, 0xffff0000, v116
	v_or_b32_sdwa v115, v115, v111 dst_sel:DWORD dst_unused:UNUSED_PAD src0_sel:DWORD src1_sel:WORD_1
	v_mul_f32_e32 v111, 0xbfb8aa3b, v150
	v_or_b32_e32 v108, v106, v208
	v_or_b32_sdwa v114, v116, v114 dst_sel:DWORD dst_unused:UNUSED_PAD src0_sel:DWORD src1_sel:WORD_1
	v_exp_f32_e32 v111, v111
	v_mul_f32_e32 v116, 0xbfb8aa3b, v151
	v_add_u32_e32 v110, s6, v205
	v_mov_b64_e32 v[106:107], s[14:15]
	v_ashrrev_i32_e32 v109, 31, v108
	v_exp_f32_e32 v116, v116
	v_mad_i64_i32 v[112:113], s[6:7], v110, s52, v[106:107]
	v_lshlrev_b64 v[108:109], 1, v[108:109]
	v_lshl_add_u64 v[112:113], v[112:113], 0, v[108:109]
	s_waitcnt vmcnt(0)
	global_store_dwordx2 v[112:113], v[114:115], off
	v_add_f32_e32 v111, 1.0, v111
	v_mul_f32_e32 v115, 0xbfb8aa3b, v152
	v_rcp_f32_e32 v114, v111
	v_add_f32_e32 v111, 1.0, v116
	v_exp_f32_e32 v115, v115
	v_mul_f32_e32 v116, 0xbfb8aa3b, v153
	v_exp_f32_e32 v117, v116
	v_rcp_f32_e32 v116, v111
	v_add_f32_e32 v111, 1.0, v115
	v_rcp_f32_e32 v115, v111
	v_add_f32_e32 v111, 1.0, v117
	v_rcp_f32_e32 v117, v111
	v_mov_b32_e32 v118, v150
	v_mov_b32_e32 v119, v152
	v_pk_mul_f32 v[114:115], v[118:119], v[114:115]
	v_mov_b32_e32 v118, v146
	v_mov_b32_e32 v119, v148
	v_mov_b32_e32 v152, v151
	v_pk_mul_f32 v[114:115], v[118:119], v[114:115]
	v_pk_mul_f32 v[116:117], v[152:153], v[116:117]
	v_mov_b32_e32 v148, v147
	v_pk_mul_f32 v[116:117], v[148:149], v[116:117]
	v_and_b32_sdwa v111, v115, v177 dst_sel:DWORD dst_unused:UNUSED_PAD src0_sel:WORD_1 src1_sel:DWORD
	v_and_b32_sdwa v118, v114, v177 dst_sel:DWORD dst_unused:UNUSED_PAD src0_sel:WORD_1 src1_sel:DWORD
	v_add3_u32 v111, v115, v111, s28
	v_and_b32_sdwa v115, v117, v177 dst_sel:DWORD dst_unused:UNUSED_PAD src0_sel:WORD_1 src1_sel:DWORD
	v_add3_u32 v114, v114, v118, s28
	v_and_b32_sdwa v118, v116, v177 dst_sel:DWORD dst_unused:UNUSED_PAD src0_sel:WORD_1 src1_sel:DWORD
	v_add3_u32 v115, v117, v115, s28
	v_add3_u32 v116, v116, v118, s28
	v_and_b32_e32 v115, 0xffff0000, v115
	v_and_b32_e32 v116, 0xffff0000, v116
	v_or_b32_sdwa v115, v115, v111 dst_sel:DWORD dst_unused:UNUSED_PAD src0_sel:DWORD src1_sel:WORD_1
	v_mul_f32_e32 v111, 0xbfb8aa3b, v142
	v_or_b32_sdwa v114, v116, v114 dst_sel:DWORD dst_unused:UNUSED_PAD src0_sel:DWORD src1_sel:WORD_1
	v_exp_f32_e32 v111, v111
	v_mul_f32_e32 v116, 0xbfb8aa3b, v143
	v_exp_f32_e32 v116, v116
	global_store_dwordx2 v[112:113], v[114:115], off offset:32
	v_add_f32_e32 v111, 1.0, v111
	v_mul_f32_e32 v115, 0xbfb8aa3b, v144
	v_rcp_f32_e32 v114, v111
	v_add_f32_e32 v111, 1.0, v116
	v_exp_f32_e32 v115, v115
	v_mul_f32_e32 v116, 0xbfb8aa3b, v145
	v_exp_f32_e32 v117, v116
	v_rcp_f32_e32 v116, v111
	v_add_f32_e32 v111, 1.0, v115
	v_rcp_f32_e32 v115, v111
	v_add_f32_e32 v111, 1.0, v117
	v_rcp_f32_e32 v117, v111
	v_mov_b32_e32 v118, v142
	v_mov_b32_e32 v119, v144
	v_pk_mul_f32 v[114:115], v[118:119], v[114:115]
	v_mov_b32_e32 v118, v138
	v_mov_b32_e32 v119, v140
	v_mov_b32_e32 v144, v143
	v_pk_mul_f32 v[114:115], v[118:119], v[114:115]
	v_pk_mul_f32 v[116:117], v[144:145], v[116:117]
	v_mov_b32_e32 v140, v139
	v_pk_mul_f32 v[116:117], v[140:141], v[116:117]
	v_and_b32_sdwa v111, v115, v177 dst_sel:DWORD dst_unused:UNUSED_PAD src0_sel:WORD_1 src1_sel:DWORD
	v_and_b32_sdwa v118, v114, v177 dst_sel:DWORD dst_unused:UNUSED_PAD src0_sel:WORD_1 src1_sel:DWORD
	v_add3_u32 v111, v115, v111, s28
	v_and_b32_sdwa v115, v117, v177 dst_sel:DWORD dst_unused:UNUSED_PAD src0_sel:WORD_1 src1_sel:DWORD
	v_add3_u32 v114, v114, v118, s28
	v_and_b32_sdwa v118, v116, v177 dst_sel:DWORD dst_unused:UNUSED_PAD src0_sel:WORD_1 src1_sel:DWORD
	v_add3_u32 v115, v117, v115, s28
	v_add3_u32 v116, v116, v118, s28
	v_and_b32_e32 v115, 0xffff0000, v115
	v_and_b32_e32 v116, 0xffff0000, v116
	v_or_b32_sdwa v115, v115, v111 dst_sel:DWORD dst_unused:UNUSED_PAD src0_sel:DWORD src1_sel:WORD_1
	v_mul_f32_e32 v111, 0xbfb8aa3b, v102
	v_or_b32_sdwa v114, v116, v114 dst_sel:DWORD dst_unused:UNUSED_PAD src0_sel:DWORD src1_sel:WORD_1
	v_exp_f32_e32 v111, v111
	v_mul_f32_e32 v116, 0xbfb8aa3b, v103
	v_exp_f32_e32 v116, v116
	global_store_dwordx2 v[112:113], v[114:115], off offset:64
	v_add_f32_e32 v111, 1.0, v111
	v_mul_f32_e32 v115, 0xbfb8aa3b, v104
	v_rcp_f32_e32 v114, v111
	v_add_f32_e32 v111, 1.0, v116
	v_exp_f32_e32 v115, v115
	v_mul_f32_e32 v116, 0xbfb8aa3b, v105
	v_exp_f32_e32 v117, v116
	v_rcp_f32_e32 v116, v111
	v_add_f32_e32 v111, 1.0, v115
	v_rcp_f32_e32 v115, v111
	v_add_f32_e32 v111, 1.0, v117
	v_rcp_f32_e32 v117, v111
	v_mov_b32_e32 v118, v102
	v_mov_b32_e32 v119, v104
	v_mov_b32_e32 v104, v103
	v_pk_mul_f32 v[114:115], v[118:119], v[114:115]
	v_mov_b32_e32 v119, v100
	v_pk_mul_f32 v[102:103], v[104:105], v[116:117]
	v_mov_b32_e32 v100, v99
	v_mov_b32_e32 v118, v98
	v_pk_mul_f32 v[98:99], v[100:101], v[102:103]
	v_pk_mul_f32 v[114:115], v[118:119], v[114:115]
	v_and_b32_sdwa v102, v99, v177 dst_sel:DWORD dst_unused:UNUSED_PAD src0_sel:WORD_1 src1_sel:DWORD
	v_and_b32_sdwa v103, v98, v177 dst_sel:DWORD dst_unused:UNUSED_PAD src0_sel:WORD_1 src1_sel:DWORD
	v_and_b32_sdwa v100, v115, v177 dst_sel:DWORD dst_unused:UNUSED_PAD src0_sel:WORD_1 src1_sel:DWORD
	v_and_b32_sdwa v101, v114, v177 dst_sel:DWORD dst_unused:UNUSED_PAD src0_sel:WORD_1 src1_sel:DWORD
	v_add3_u32 v99, v99, v102, s28
	v_add3_u32 v98, v98, v103, s28
	v_add3_u32 v101, v114, v101, s28
	v_add3_u32 v100, v115, v100, s28
	v_and_b32_e32 v99, 0xffff0000, v99
	v_and_b32_e32 v98, 0xffff0000, v98
	v_or_b32_sdwa v99, v99, v100 dst_sel:DWORD dst_unused:UNUSED_PAD src0_sel:DWORD src1_sel:WORD_1
	v_or_b32_sdwa v98, v98, v101 dst_sel:DWORD dst_unused:UNUSED_PAD src0_sel:DWORD src1_sel:WORD_1
	global_store_dwordx2 v[112:113], v[98:99], off offset:96
	v_mul_f32_e32 v99, 0xbfb8aa3b, v94
	v_exp_f32_e32 v100, v99
	v_mul_f32_e32 v99, 0xbfb8aa3b, v95
	v_mul_f32_e32 v102, 0xbfb8aa3b, v96
	v_exp_f32_e32 v101, v99
	v_exp_f32_e32 v103, v102
	v_mul_f32_e32 v102, 0xbfb8aa3b, v97
	v_exp_f32_e32 v104, v102
	v_add_f32_e32 v101, 1.0, v101
	v_add_f32_e32 v100, 1.0, v100
	v_rcp_f32_e32 v102, v101
	v_add_f32_e32 v101, 1.0, v103
	v_add_f32_e32 v103, 1.0, v104
	v_rcp_f32_e32 v100, v100
	v_rcp_f32_e32 v101, v101
	v_rcp_f32_e32 v103, v103
	v_mov_b32_e32 v104, v94
	v_mov_b32_e32 v105, v96
	v_mov_b32_e32 v96, v95
	v_pk_mul_f32 v[100:101], v[104:105], v[100:101]
	v_mov_b32_e32 v105, v92
	v_pk_mul_f32 v[94:95], v[96:97], v[102:103]
	v_mov_b32_e32 v92, v91
	v_mov_b32_e32 v104, v90
	v_pk_mul_f32 v[90:91], v[92:93], v[94:95]
	v_pk_mul_f32 v[100:101], v[104:105], v[100:101]
	v_and_b32_sdwa v94, v91, v177 dst_sel:DWORD dst_unused:UNUSED_PAD src0_sel:WORD_1 src1_sel:DWORD
	v_and_b32_sdwa v92, v101, v177 dst_sel:DWORD dst_unused:UNUSED_PAD src0_sel:WORD_1 src1_sel:DWORD
	v_and_b32_sdwa v95, v90, v177 dst_sel:DWORD dst_unused:UNUSED_PAD src0_sel:WORD_1 src1_sel:DWORD
	v_add3_u32 v91, v91, v94, s28
	v_and_b32_sdwa v93, v100, v177 dst_sel:DWORD dst_unused:UNUSED_PAD src0_sel:WORD_1 src1_sel:DWORD
	v_add3_u32 v92, v101, v92, s28
	v_add3_u32 v90, v90, v95, s28
	v_and_b32_e32 v91, 0xffff0000, v91
	v_add3_u32 v93, v100, v93, s28
	v_and_b32_e32 v90, 0xffff0000, v90
	v_or_b32_sdwa v91, v91, v92 dst_sel:DWORD dst_unused:UNUSED_PAD src0_sel:DWORD src1_sel:WORD_1
	v_mul_f32_e32 v92, 0xbfb8aa3b, v86
	v_or_b32_sdwa v90, v90, v93 dst_sel:DWORD dst_unused:UNUSED_PAD src0_sel:DWORD src1_sel:WORD_1
	v_exp_f32_e32 v92, v92
	v_mul_f32_e32 v93, 0xbfb8aa3b, v87
	v_or_b32_e32 v98, 16, v110
	v_exp_f32_e32 v93, v93
	v_mad_i64_i32 v[98:99], s[6:7], v98, s52, v[106:107]
	v_lshl_add_u64 v[98:99], v[98:99], 0, v[108:109]
	global_store_dwordx2 v[98:99], v[90:91], off
	v_add_f32_e32 v90, 1.0, v92
	v_mul_f32_e32 v92, 0xbfb8aa3b, v88
	v_add_f32_e32 v91, 1.0, v93
	v_exp_f32_e32 v93, v92
	v_mul_f32_e32 v92, 0xbfb8aa3b, v89
	v_exp_f32_e32 v94, v92
	v_rcp_f32_e32 v92, v91
	v_add_f32_e32 v91, 1.0, v93
	v_rcp_f32_e32 v90, v90
	v_add_f32_e32 v93, 1.0, v94
	v_rcp_f32_e32 v91, v91
	v_rcp_f32_e32 v93, v93
	v_mov_b32_e32 v94, v86
	v_mov_b32_e32 v95, v88
	v_mov_b32_e32 v88, v87
	v_pk_mul_f32 v[90:91], v[94:95], v[90:91]
	v_mov_b32_e32 v95, v84
	v_pk_mul_f32 v[86:87], v[88:89], v[92:93]
	v_mov_b32_e32 v84, v83
	v_mov_b32_e32 v94, v82
	v_pk_mul_f32 v[82:83], v[84:85], v[86:87]
	v_pk_mul_f32 v[90:91], v[94:95], v[90:91]
	v_and_b32_sdwa v86, v83, v177 dst_sel:DWORD dst_unused:UNUSED_PAD src0_sel:WORD_1 src1_sel:DWORD
	v_and_b32_sdwa v84, v91, v177 dst_sel:DWORD dst_unused:UNUSED_PAD src0_sel:WORD_1 src1_sel:DWORD
	v_and_b32_sdwa v87, v82, v177 dst_sel:DWORD dst_unused:UNUSED_PAD src0_sel:WORD_1 src1_sel:DWORD
	v_add3_u32 v83, v83, v86, s28
	v_and_b32_sdwa v85, v90, v177 dst_sel:DWORD dst_unused:UNUSED_PAD src0_sel:WORD_1 src1_sel:DWORD
	v_add3_u32 v84, v91, v84, s28
	v_add3_u32 v82, v82, v87, s28
	v_and_b32_e32 v83, 0xffff0000, v83
	v_add3_u32 v85, v90, v85, s28
	v_and_b32_e32 v82, 0xffff0000, v82
	v_or_b32_sdwa v83, v83, v84 dst_sel:DWORD dst_unused:UNUSED_PAD src0_sel:DWORD src1_sel:WORD_1
	v_mul_f32_e32 v84, 0xbfb8aa3b, v78
	v_or_b32_sdwa v82, v82, v85 dst_sel:DWORD dst_unused:UNUSED_PAD src0_sel:DWORD src1_sel:WORD_1
	v_exp_f32_e32 v84, v84
	v_mul_f32_e32 v85, 0xbfb8aa3b, v79
	v_exp_f32_e32 v85, v85
	global_store_dwordx2 v[98:99], v[82:83], off offset:32
	v_add_f32_e32 v82, 1.0, v84
	v_mul_f32_e32 v84, 0xbfb8aa3b, v80
	v_add_f32_e32 v83, 1.0, v85
	v_exp_f32_e32 v85, v84
	v_mul_f32_e32 v84, 0xbfb8aa3b, v81
	v_exp_f32_e32 v86, v84
	v_rcp_f32_e32 v84, v83
	v_add_f32_e32 v83, 1.0, v85
	v_rcp_f32_e32 v82, v82
	v_add_f32_e32 v85, 1.0, v86
	v_rcp_f32_e32 v83, v83
	v_rcp_f32_e32 v85, v85
	v_mov_b32_e32 v86, v78
	v_mov_b32_e32 v87, v80
	v_mov_b32_e32 v80, v79
	v_pk_mul_f32 v[82:83], v[86:87], v[82:83]
	v_mov_b32_e32 v87, v76
	v_pk_mul_f32 v[78:79], v[80:81], v[84:85]
	v_mov_b32_e32 v76, v75
	v_mov_b32_e32 v86, v74
	v_pk_mul_f32 v[74:75], v[76:77], v[78:79]
	v_pk_mul_f32 v[82:83], v[86:87], v[82:83]
	v_and_b32_sdwa v78, v75, v177 dst_sel:DWORD dst_unused:UNUSED_PAD src0_sel:WORD_1 src1_sel:DWORD
	v_and_b32_sdwa v76, v83, v177 dst_sel:DWORD dst_unused:UNUSED_PAD src0_sel:WORD_1 src1_sel:DWORD
	v_and_b32_sdwa v79, v74, v177 dst_sel:DWORD dst_unused:UNUSED_PAD src0_sel:WORD_1 src1_sel:DWORD
	v_add3_u32 v75, v75, v78, s28
	v_and_b32_sdwa v77, v82, v177 dst_sel:DWORD dst_unused:UNUSED_PAD src0_sel:WORD_1 src1_sel:DWORD
	v_add3_u32 v76, v83, v76, s28
	v_add3_u32 v74, v74, v79, s28
	v_and_b32_e32 v75, 0xffff0000, v75
	v_add3_u32 v77, v82, v77, s28
	v_and_b32_e32 v74, 0xffff0000, v74
	v_or_b32_sdwa v75, v75, v76 dst_sel:DWORD dst_unused:UNUSED_PAD src0_sel:DWORD src1_sel:WORD_1
	v_mul_f32_e32 v76, 0xbfb8aa3b, v70
	v_or_b32_sdwa v74, v74, v77 dst_sel:DWORD dst_unused:UNUSED_PAD src0_sel:DWORD src1_sel:WORD_1
	v_exp_f32_e32 v76, v76
	v_mul_f32_e32 v77, 0xbfb8aa3b, v71
	v_exp_f32_e32 v77, v77
	global_store_dwordx2 v[98:99], v[74:75], off offset:64
	v_add_f32_e32 v74, 1.0, v76
	v_mul_f32_e32 v76, 0xbfb8aa3b, v72
	v_add_f32_e32 v75, 1.0, v77
	v_exp_f32_e32 v77, v76
	v_mul_f32_e32 v76, 0xbfb8aa3b, v73
	v_exp_f32_e32 v78, v76
	v_rcp_f32_e32 v76, v75
	v_add_f32_e32 v75, 1.0, v77
	v_rcp_f32_e32 v74, v74
	v_add_f32_e32 v77, 1.0, v78
	v_rcp_f32_e32 v75, v75
	v_rcp_f32_e32 v77, v77
	v_mov_b32_e32 v78, v70
	v_mov_b32_e32 v79, v72
	v_mov_b32_e32 v72, v71
	v_pk_mul_f32 v[74:75], v[78:79], v[74:75]
	v_mov_b32_e32 v79, v68
	v_pk_mul_f32 v[70:71], v[72:73], v[76:77]
	v_mov_b32_e32 v68, v67
	v_mov_b32_e32 v78, v66
	v_pk_mul_f32 v[66:67], v[68:69], v[70:71]
	v_pk_mul_f32 v[74:75], v[78:79], v[74:75]
	v_and_b32_sdwa v70, v67, v177 dst_sel:DWORD dst_unused:UNUSED_PAD src0_sel:WORD_1 src1_sel:DWORD
	v_and_b32_sdwa v71, v66, v177 dst_sel:DWORD dst_unused:UNUSED_PAD src0_sel:WORD_1 src1_sel:DWORD
	v_and_b32_sdwa v68, v75, v177 dst_sel:DWORD dst_unused:UNUSED_PAD src0_sel:WORD_1 src1_sel:DWORD
	v_and_b32_sdwa v69, v74, v177 dst_sel:DWORD dst_unused:UNUSED_PAD src0_sel:WORD_1 src1_sel:DWORD
	v_add3_u32 v67, v67, v70, s28
	v_add3_u32 v66, v66, v71, s28
	v_add3_u32 v69, v74, v69, s28
	v_add3_u32 v68, v75, v68, s28
	v_and_b32_e32 v67, 0xffff0000, v67
	v_and_b32_e32 v66, 0xffff0000, v66
	v_or_b32_sdwa v67, v67, v68 dst_sel:DWORD dst_unused:UNUSED_PAD src0_sel:DWORD src1_sel:WORD_1
	v_or_b32_sdwa v66, v66, v69 dst_sel:DWORD dst_unused:UNUSED_PAD src0_sel:DWORD src1_sel:WORD_1
	global_store_dwordx2 v[98:99], v[66:67], off offset:96
	v_mul_f32_e32 v67, 0xbfb8aa3b, v62
	v_exp_f32_e32 v68, v67
	v_mul_f32_e32 v67, 0xbfb8aa3b, v63
	v_mul_f32_e32 v70, 0xbfb8aa3b, v64
	v_exp_f32_e32 v69, v67
	v_exp_f32_e32 v71, v70
	v_mul_f32_e32 v70, 0xbfb8aa3b, v65
	v_exp_f32_e32 v72, v70
	v_add_f32_e32 v69, 1.0, v69
	v_add_f32_e32 v68, 1.0, v68
	v_rcp_f32_e32 v70, v69
	v_add_f32_e32 v69, 1.0, v71
	v_add_f32_e32 v71, 1.0, v72
	v_rcp_f32_e32 v68, v68
	v_rcp_f32_e32 v69, v69
	v_rcp_f32_e32 v71, v71
	v_mov_b32_e32 v72, v62
	v_mov_b32_e32 v73, v64
	v_mov_b32_e32 v64, v63
	v_pk_mul_f32 v[68:69], v[72:73], v[68:69]
	v_mov_b32_e32 v73, v60
	v_pk_mul_f32 v[62:63], v[64:65], v[70:71]
	v_mov_b32_e32 v60, v59
	v_mov_b32_e32 v72, v58
	v_pk_mul_f32 v[58:59], v[60:61], v[62:63]
	v_pk_mul_f32 v[68:69], v[72:73], v[68:69]
	v_and_b32_sdwa v62, v59, v177 dst_sel:DWORD dst_unused:UNUSED_PAD src0_sel:WORD_1 src1_sel:DWORD
	v_and_b32_sdwa v60, v69, v177 dst_sel:DWORD dst_unused:UNUSED_PAD src0_sel:WORD_1 src1_sel:DWORD
	v_and_b32_sdwa v63, v58, v177 dst_sel:DWORD dst_unused:UNUSED_PAD src0_sel:WORD_1 src1_sel:DWORD
	v_add3_u32 v59, v59, v62, s28
	v_and_b32_sdwa v61, v68, v177 dst_sel:DWORD dst_unused:UNUSED_PAD src0_sel:WORD_1 src1_sel:DWORD
	v_add3_u32 v60, v69, v60, s28
	v_add3_u32 v58, v58, v63, s28
	v_and_b32_e32 v59, 0xffff0000, v59
	v_add3_u32 v61, v68, v61, s28
	v_and_b32_e32 v58, 0xffff0000, v58
	v_or_b32_sdwa v59, v59, v60 dst_sel:DWORD dst_unused:UNUSED_PAD src0_sel:DWORD src1_sel:WORD_1
	v_mul_f32_e32 v60, 0xbfb8aa3b, v54
	v_or_b32_sdwa v58, v58, v61 dst_sel:DWORD dst_unused:UNUSED_PAD src0_sel:DWORD src1_sel:WORD_1
	v_exp_f32_e32 v60, v60
	v_mul_f32_e32 v61, 0xbfb8aa3b, v55
	v_or_b32_e32 v66, 32, v110
	v_exp_f32_e32 v61, v61
	v_mad_i64_i32 v[66:67], s[6:7], v66, s52, v[106:107]
	v_lshl_add_u64 v[66:67], v[66:67], 0, v[108:109]
	global_store_dwordx2 v[66:67], v[58:59], off
	v_add_f32_e32 v58, 1.0, v60
	v_mul_f32_e32 v60, 0xbfb8aa3b, v56
	v_add_f32_e32 v59, 1.0, v61
	v_exp_f32_e32 v61, v60
	v_mul_f32_e32 v60, 0xbfb8aa3b, v57
	v_exp_f32_e32 v62, v60
	v_rcp_f32_e32 v60, v59
	v_add_f32_e32 v59, 1.0, v61
	v_rcp_f32_e32 v58, v58
	v_add_f32_e32 v61, 1.0, v62
	v_rcp_f32_e32 v59, v59
	v_rcp_f32_e32 v61, v61
	v_mov_b32_e32 v62, v54
	v_mov_b32_e32 v63, v56
	v_mov_b32_e32 v56, v55
	v_pk_mul_f32 v[58:59], v[62:63], v[58:59]
	v_mov_b32_e32 v63, v52
	v_pk_mul_f32 v[54:55], v[56:57], v[60:61]
	v_mov_b32_e32 v52, v51
	v_mov_b32_e32 v62, v50
	v_pk_mul_f32 v[50:51], v[52:53], v[54:55]
	v_pk_mul_f32 v[58:59], v[62:63], v[58:59]
	v_and_b32_sdwa v54, v51, v177 dst_sel:DWORD dst_unused:UNUSED_PAD src0_sel:WORD_1 src1_sel:DWORD
	v_and_b32_sdwa v52, v59, v177 dst_sel:DWORD dst_unused:UNUSED_PAD src0_sel:WORD_1 src1_sel:DWORD
	v_and_b32_sdwa v55, v50, v177 dst_sel:DWORD dst_unused:UNUSED_PAD src0_sel:WORD_1 src1_sel:DWORD
	v_add3_u32 v51, v51, v54, s28
	v_and_b32_sdwa v53, v58, v177 dst_sel:DWORD dst_unused:UNUSED_PAD src0_sel:WORD_1 src1_sel:DWORD
	v_add3_u32 v52, v59, v52, s28
	v_add3_u32 v50, v50, v55, s28
	v_and_b32_e32 v51, 0xffff0000, v51
	v_add3_u32 v53, v58, v53, s28
	v_and_b32_e32 v50, 0xffff0000, v50
	v_or_b32_sdwa v51, v51, v52 dst_sel:DWORD dst_unused:UNUSED_PAD src0_sel:DWORD src1_sel:WORD_1
	v_mul_f32_e32 v52, 0xbfb8aa3b, v46
	v_or_b32_sdwa v50, v50, v53 dst_sel:DWORD dst_unused:UNUSED_PAD src0_sel:DWORD src1_sel:WORD_1
	v_exp_f32_e32 v52, v52
	v_mul_f32_e32 v53, 0xbfb8aa3b, v47
	v_exp_f32_e32 v53, v53
	global_store_dwordx2 v[66:67], v[50:51], off offset:32
	v_add_f32_e32 v50, 1.0, v52
	v_mul_f32_e32 v52, 0xbfb8aa3b, v48
	v_add_f32_e32 v51, 1.0, v53
	v_exp_f32_e32 v53, v52
	v_mul_f32_e32 v52, 0xbfb8aa3b, v49
	v_exp_f32_e32 v54, v52
	v_rcp_f32_e32 v52, v51
	v_add_f32_e32 v51, 1.0, v53
	v_rcp_f32_e32 v50, v50
	v_add_f32_e32 v53, 1.0, v54
	v_rcp_f32_e32 v51, v51
	v_rcp_f32_e32 v53, v53
	v_mov_b32_e32 v54, v46
	v_mov_b32_e32 v55, v48
	v_mov_b32_e32 v48, v47
	v_pk_mul_f32 v[50:51], v[54:55], v[50:51]
	v_mov_b32_e32 v55, v44
	v_pk_mul_f32 v[46:47], v[48:49], v[52:53]
	v_mov_b32_e32 v44, v43
	v_mov_b32_e32 v54, v42
	v_pk_mul_f32 v[42:43], v[44:45], v[46:47]
	v_pk_mul_f32 v[50:51], v[54:55], v[50:51]
	v_and_b32_sdwa v46, v43, v177 dst_sel:DWORD dst_unused:UNUSED_PAD src0_sel:WORD_1 src1_sel:DWORD
	v_and_b32_sdwa v44, v51, v177 dst_sel:DWORD dst_unused:UNUSED_PAD src0_sel:WORD_1 src1_sel:DWORD
	v_and_b32_sdwa v47, v42, v177 dst_sel:DWORD dst_unused:UNUSED_PAD src0_sel:WORD_1 src1_sel:DWORD
	v_add3_u32 v43, v43, v46, s28
	v_and_b32_sdwa v45, v50, v177 dst_sel:DWORD dst_unused:UNUSED_PAD src0_sel:WORD_1 src1_sel:DWORD
	v_add3_u32 v44, v51, v44, s28
	v_add3_u32 v42, v42, v47, s28
	v_and_b32_e32 v43, 0xffff0000, v43
	v_add3_u32 v45, v50, v45, s28
	v_and_b32_e32 v42, 0xffff0000, v42
	v_or_b32_sdwa v43, v43, v44 dst_sel:DWORD dst_unused:UNUSED_PAD src0_sel:DWORD src1_sel:WORD_1
	v_mul_f32_e32 v44, 0xbfb8aa3b, v38
	v_or_b32_sdwa v42, v42, v45 dst_sel:DWORD dst_unused:UNUSED_PAD src0_sel:DWORD src1_sel:WORD_1
	v_exp_f32_e32 v44, v44
	v_mul_f32_e32 v45, 0xbfb8aa3b, v39
	v_exp_f32_e32 v45, v45
	global_store_dwordx2 v[66:67], v[42:43], off offset:64
	v_add_f32_e32 v42, 1.0, v44
	v_mul_f32_e32 v44, 0xbfb8aa3b, v40
	v_add_f32_e32 v43, 1.0, v45
	v_exp_f32_e32 v45, v44
	v_mul_f32_e32 v44, 0xbfb8aa3b, v41
	v_exp_f32_e32 v46, v44
	v_rcp_f32_e32 v44, v43
	v_add_f32_e32 v43, 1.0, v45
	v_rcp_f32_e32 v42, v42
	v_add_f32_e32 v45, 1.0, v46
	v_rcp_f32_e32 v43, v43
	v_rcp_f32_e32 v45, v45
	v_mov_b32_e32 v46, v38
	v_mov_b32_e32 v47, v40
	v_mov_b32_e32 v40, v39
	v_pk_mul_f32 v[42:43], v[46:47], v[42:43]
	v_mov_b32_e32 v47, v36
	v_pk_mul_f32 v[38:39], v[40:41], v[44:45]
	v_mov_b32_e32 v36, v35
	v_mov_b32_e32 v46, v34
	v_pk_mul_f32 v[34:35], v[36:37], v[38:39]
	v_pk_mul_f32 v[42:43], v[46:47], v[42:43]
	v_and_b32_sdwa v38, v35, v177 dst_sel:DWORD dst_unused:UNUSED_PAD src0_sel:WORD_1 src1_sel:DWORD
	v_and_b32_sdwa v39, v34, v177 dst_sel:DWORD dst_unused:UNUSED_PAD src0_sel:WORD_1 src1_sel:DWORD
	v_and_b32_sdwa v36, v43, v177 dst_sel:DWORD dst_unused:UNUSED_PAD src0_sel:WORD_1 src1_sel:DWORD
	v_and_b32_sdwa v37, v42, v177 dst_sel:DWORD dst_unused:UNUSED_PAD src0_sel:WORD_1 src1_sel:DWORD
	v_add3_u32 v35, v35, v38, s28
	v_add3_u32 v34, v34, v39, s28
	v_add3_u32 v37, v42, v37, s28
	v_add3_u32 v36, v43, v36, s28
	v_and_b32_e32 v35, 0xffff0000, v35
	v_and_b32_e32 v34, 0xffff0000, v34
	v_or_b32_sdwa v35, v35, v36 dst_sel:DWORD dst_unused:UNUSED_PAD src0_sel:DWORD src1_sel:WORD_1
	v_or_b32_sdwa v34, v34, v37 dst_sel:DWORD dst_unused:UNUSED_PAD src0_sel:DWORD src1_sel:WORD_1
	global_store_dwordx2 v[66:67], v[34:35], off offset:96
	v_mul_f32_e32 v35, 0xbfb8aa3b, v30
	v_exp_f32_e32 v36, v35
	v_mul_f32_e32 v35, 0xbfb8aa3b, v31
	v_mul_f32_e32 v38, 0xbfb8aa3b, v32
	v_exp_f32_e32 v37, v35
	v_exp_f32_e32 v39, v38
	v_mul_f32_e32 v38, 0xbfb8aa3b, v33
	v_exp_f32_e32 v40, v38
	v_add_f32_e32 v37, 1.0, v37
	v_add_f32_e32 v36, 1.0, v36
	v_rcp_f32_e32 v38, v37
	v_add_f32_e32 v37, 1.0, v39
	v_add_f32_e32 v39, 1.0, v40
	v_rcp_f32_e32 v36, v36
	v_rcp_f32_e32 v37, v37
	v_rcp_f32_e32 v39, v39
	v_mov_b32_e32 v40, v30
	v_mov_b32_e32 v41, v32
	v_mov_b32_e32 v32, v31
	v_pk_mul_f32 v[36:37], v[40:41], v[36:37]
	v_mov_b32_e32 v41, v28
	v_pk_mul_f32 v[30:31], v[32:33], v[38:39]
	v_mov_b32_e32 v28, v27
	v_mov_b32_e32 v40, v26
	v_pk_mul_f32 v[26:27], v[28:29], v[30:31]
	v_pk_mul_f32 v[36:37], v[40:41], v[36:37]
	v_and_b32_sdwa v30, v27, v177 dst_sel:DWORD dst_unused:UNUSED_PAD src0_sel:WORD_1 src1_sel:DWORD
	v_and_b32_sdwa v28, v37, v177 dst_sel:DWORD dst_unused:UNUSED_PAD src0_sel:WORD_1 src1_sel:DWORD
	v_and_b32_sdwa v31, v26, v177 dst_sel:DWORD dst_unused:UNUSED_PAD src0_sel:WORD_1 src1_sel:DWORD
	v_add3_u32 v27, v27, v30, s28
	v_and_b32_sdwa v29, v36, v177 dst_sel:DWORD dst_unused:UNUSED_PAD src0_sel:WORD_1 src1_sel:DWORD
	v_add3_u32 v28, v37, v28, s28
	v_add3_u32 v26, v26, v31, s28
	v_and_b32_e32 v27, 0xffff0000, v27
	v_add3_u32 v29, v36, v29, s28
	v_and_b32_e32 v26, 0xffff0000, v26
	v_or_b32_sdwa v27, v27, v28 dst_sel:DWORD dst_unused:UNUSED_PAD src0_sel:DWORD src1_sel:WORD_1
	v_mul_f32_e32 v28, 0xbfb8aa3b, v22
	v_or_b32_sdwa v26, v26, v29 dst_sel:DWORD dst_unused:UNUSED_PAD src0_sel:DWORD src1_sel:WORD_1
	v_exp_f32_e32 v28, v28
	v_mul_f32_e32 v29, 0xbfb8aa3b, v23
	v_or_b32_e32 v34, 48, v110
	v_exp_f32_e32 v29, v29
	v_mad_i64_i32 v[34:35], s[6:7], v34, s52, v[106:107]
	v_lshl_add_u64 v[34:35], v[34:35], 0, v[108:109]
	global_store_dwordx2 v[34:35], v[26:27], off
	v_add_f32_e32 v26, 1.0, v28
	v_mul_f32_e32 v28, 0xbfb8aa3b, v24
	v_add_f32_e32 v27, 1.0, v29
	v_exp_f32_e32 v29, v28
	v_mul_f32_e32 v28, 0xbfb8aa3b, v25
	v_exp_f32_e32 v30, v28
	v_rcp_f32_e32 v28, v27
	v_add_f32_e32 v27, 1.0, v29
	v_rcp_f32_e32 v26, v26
	v_add_f32_e32 v29, 1.0, v30
	v_rcp_f32_e32 v27, v27
	v_rcp_f32_e32 v29, v29
	v_mov_b32_e32 v30, v22
	v_mov_b32_e32 v31, v24
	v_mov_b32_e32 v24, v23
	v_pk_mul_f32 v[26:27], v[30:31], v[26:27]
	v_mov_b32_e32 v31, v20
	v_pk_mul_f32 v[22:23], v[24:25], v[28:29]
	v_mov_b32_e32 v20, v19
	v_mov_b32_e32 v30, v18
	v_pk_mul_f32 v[18:19], v[20:21], v[22:23]
	v_pk_mul_f32 v[26:27], v[30:31], v[26:27]
	v_and_b32_sdwa v22, v19, v177 dst_sel:DWORD dst_unused:UNUSED_PAD src0_sel:WORD_1 src1_sel:DWORD
	v_and_b32_sdwa v20, v27, v177 dst_sel:DWORD dst_unused:UNUSED_PAD src0_sel:WORD_1 src1_sel:DWORD
	v_and_b32_sdwa v23, v18, v177 dst_sel:DWORD dst_unused:UNUSED_PAD src0_sel:WORD_1 src1_sel:DWORD
	v_add3_u32 v19, v19, v22, s28
	v_and_b32_sdwa v21, v26, v177 dst_sel:DWORD dst_unused:UNUSED_PAD src0_sel:WORD_1 src1_sel:DWORD
	v_add3_u32 v20, v27, v20, s28
	v_add3_u32 v18, v18, v23, s28
	v_and_b32_e32 v19, 0xffff0000, v19
	v_add3_u32 v21, v26, v21, s28
	v_and_b32_e32 v18, 0xffff0000, v18
	v_or_b32_sdwa v19, v19, v20 dst_sel:DWORD dst_unused:UNUSED_PAD src0_sel:DWORD src1_sel:WORD_1
	v_mul_f32_e32 v20, 0xbfb8aa3b, v14
	v_or_b32_sdwa v18, v18, v21 dst_sel:DWORD dst_unused:UNUSED_PAD src0_sel:DWORD src1_sel:WORD_1
	v_exp_f32_e32 v20, v20
	v_mul_f32_e32 v21, 0xbfb8aa3b, v15
	v_exp_f32_e32 v21, v21
	global_store_dwordx2 v[34:35], v[18:19], off offset:32
	v_add_f32_e32 v18, 1.0, v20
	v_mul_f32_e32 v20, 0xbfb8aa3b, v16
	v_add_f32_e32 v19, 1.0, v21
	v_exp_f32_e32 v21, v20
	v_mul_f32_e32 v20, 0xbfb8aa3b, v17
	v_exp_f32_e32 v22, v20
	v_rcp_f32_e32 v20, v19
	v_add_f32_e32 v19, 1.0, v21
	v_rcp_f32_e32 v18, v18
	v_add_f32_e32 v21, 1.0, v22
	v_rcp_f32_e32 v19, v19
	v_rcp_f32_e32 v21, v21
	v_mov_b32_e32 v22, v14
	v_mov_b32_e32 v23, v16
	v_mov_b32_e32 v16, v15
	v_pk_mul_f32 v[18:19], v[22:23], v[18:19]
	v_mov_b32_e32 v23, v12
	v_pk_mul_f32 v[14:15], v[16:17], v[20:21]
	v_mov_b32_e32 v12, v11
	v_mov_b32_e32 v22, v10
	v_pk_mul_f32 v[10:11], v[12:13], v[14:15]
	v_pk_mul_f32 v[18:19], v[22:23], v[18:19]
	v_and_b32_sdwa v14, v11, v177 dst_sel:DWORD dst_unused:UNUSED_PAD src0_sel:WORD_1 src1_sel:DWORD
	v_and_b32_sdwa v12, v19, v177 dst_sel:DWORD dst_unused:UNUSED_PAD src0_sel:WORD_1 src1_sel:DWORD
	v_and_b32_sdwa v15, v10, v177 dst_sel:DWORD dst_unused:UNUSED_PAD src0_sel:WORD_1 src1_sel:DWORD
	v_add3_u32 v11, v11, v14, s28
	v_and_b32_sdwa v13, v18, v177 dst_sel:DWORD dst_unused:UNUSED_PAD src0_sel:WORD_1 src1_sel:DWORD
	v_add3_u32 v12, v19, v12, s28
	v_add3_u32 v10, v10, v15, s28
	v_and_b32_e32 v11, 0xffff0000, v11
	v_add3_u32 v13, v18, v13, s28
	v_and_b32_e32 v10, 0xffff0000, v10
	v_or_b32_sdwa v11, v11, v12 dst_sel:DWORD dst_unused:UNUSED_PAD src0_sel:DWORD src1_sel:WORD_1
	v_mul_f32_e32 v12, 0xbfb8aa3b, v6
	v_or_b32_sdwa v10, v10, v13 dst_sel:DWORD dst_unused:UNUSED_PAD src0_sel:DWORD src1_sel:WORD_1
	v_exp_f32_e32 v12, v12
	v_mul_f32_e32 v13, 0xbfb8aa3b, v7
	v_exp_f32_e32 v13, v13
	global_store_dwordx2 v[34:35], v[10:11], off offset:64
	v_add_f32_e32 v10, 1.0, v12
	v_mul_f32_e32 v12, 0xbfb8aa3b, v8
	v_add_f32_e32 v11, 1.0, v13
	v_exp_f32_e32 v13, v12
	v_mul_f32_e32 v12, 0xbfb8aa3b, v9
	v_exp_f32_e32 v14, v12
	v_rcp_f32_e32 v12, v11
	v_add_f32_e32 v11, 1.0, v13
	v_rcp_f32_e32 v10, v10
	v_add_f32_e32 v13, 1.0, v14
	v_rcp_f32_e32 v11, v11
	v_rcp_f32_e32 v13, v13
	v_mov_b32_e32 v14, v6
	v_mov_b32_e32 v15, v8
	v_mov_b32_e32 v8, v7
	v_pk_mul_f32 v[10:11], v[14:15], v[10:11]
	v_mov_b32_e32 v15, v4
	v_pk_mul_f32 v[6:7], v[8:9], v[12:13]
	v_mov_b32_e32 v4, v3
	v_mov_b32_e32 v14, v2
	v_pk_mul_f32 v[2:3], v[4:5], v[6:7]
	v_pk_mul_f32 v[10:11], v[14:15], v[10:11]
	v_and_b32_sdwa v6, v3, v177 dst_sel:DWORD dst_unused:UNUSED_PAD src0_sel:WORD_1 src1_sel:DWORD
	v_and_b32_sdwa v7, v2, v177 dst_sel:DWORD dst_unused:UNUSED_PAD src0_sel:WORD_1 src1_sel:DWORD
	v_and_b32_sdwa v4, v11, v177 dst_sel:DWORD dst_unused:UNUSED_PAD src0_sel:WORD_1 src1_sel:DWORD
	v_and_b32_sdwa v5, v10, v177 dst_sel:DWORD dst_unused:UNUSED_PAD src0_sel:WORD_1 src1_sel:DWORD
	v_add3_u32 v3, v3, v6, s28
	v_add3_u32 v2, v2, v7, s28
	v_add3_u32 v5, v10, v5, s28
	v_add3_u32 v4, v11, v4, s28
	v_and_b32_e32 v3, 0xffff0000, v3
	v_and_b32_e32 v2, 0xffff0000, v2
	s_add_i32 s20, s20, s11
	v_or_b32_sdwa v3, v3, v4 dst_sel:DWORD dst_unused:UNUSED_PAD src0_sel:DWORD src1_sel:WORD_1
	v_or_b32_sdwa v2, v2, v5 dst_sel:DWORD dst_unused:UNUSED_PAD src0_sel:DWORD src1_sel:WORD_1
	s_cmpk_gt_i32 s20, 0x5ff
	global_store_dwordx2 v[34:35], v[2:3], off offset:96
	s_cbranch_scc0 .LBB0_465

.LBB0_534:
	s_bitcmp1_b32 s4, 0
	s_cselect_b32 s21, 0x12000, 0
	v_or_b32_e32 v218, s21, v207
	v_add_u32_e32 v214, v218, v0
	v_add_u32_e32 v246, v218, v167
	ds_read_b128 v[184:187], v214
	ds_read_b128 v[198:201], v214 offset:2048
	ds_read_b128 v[210:213], v214 offset:4096
	ds_read_b128 v[214:217], v214 offset:6144
	ds_read_b128 v[218:221], v246 offset:32768
	ds_read_b128 v[222:225], v246 offset:34816
	ds_read_b128 v[226:229], v246 offset:36864
	ds_read_b128 v[230:233], v246 offset:38912
	ds_read_b128 v[234:237], v246 offset:40960
	ds_read_b128 v[238:241], v246 offset:43008
	ds_read_b128 v[242:245], v246 offset:45056
	ds_read_b128 v[246:249], v246 offset:47104
	s_add_i32 s20, s4, 1
	s_bitcmp1_b32 s20, 0
	s_cselect_b32 s23, 0x12000, 0
	v_add_u32_e32 v171, s23, v166
	v_xor_b32_e32 v169, 64, v207
	v_add3_u32 v169, s21, v167, v169
	s_waitcnt lgkmcnt(7)
	v_mfma_f32_16x16x32_bf16 v[158:161], v[218:221], v[184:187], v[158:161]
	v_mfma_f32_16x16x32_bf16 v[94:97], v[218:221], v[198:201], v[94:97]
	v_mfma_f32_16x16x32_bf16 v[62:65], v[218:221], v[210:213], v[62:65]
	v_mfma_f32_16x16x32_bf16 v[30:33], v[218:221], v[214:217], v[30:33]
	ds_read_b128 v[218:221], v169 offset:32768
	s_waitcnt lgkmcnt(7)
	v_mfma_f32_16x16x32_bf16 v[154:157], v[222:225], v[184:187], v[154:157]
	v_mfma_f32_16x16x32_bf16 v[90:93], v[222:225], v[198:201], v[90:93]
	v_mfma_f32_16x16x32_bf16 v[58:61], v[222:225], v[210:213], v[58:61]
	v_mfma_f32_16x16x32_bf16 v[26:29], v[222:225], v[214:217], v[26:29]
	ds_read_b128 v[222:225], v169 offset:34816
	s_waitcnt lgkmcnt(7)
	v_mfma_f32_16x16x32_bf16 v[150:153], v[226:229], v[184:187], v[150:153]
	v_mfma_f32_16x16x32_bf16 v[86:89], v[226:229], v[198:201], v[86:89]
	v_mfma_f32_16x16x32_bf16 v[54:57], v[226:229], v[210:213], v[54:57]
	v_mfma_f32_16x16x32_bf16 v[22:25], v[226:229], v[214:217], v[22:25]
	ds_read_b128 v[226:229], v169 offset:36864
	s_waitcnt lgkmcnt(7)
	v_mfma_f32_16x16x32_bf16 v[146:149], v[230:233], v[184:187], v[146:149]
	v_mfma_f32_16x16x32_bf16 v[82:85], v[230:233], v[198:201], v[82:85]
	v_mfma_f32_16x16x32_bf16 v[50:53], v[230:233], v[210:213], v[50:53]
	v_mfma_f32_16x16x32_bf16 v[18:21], v[230:233], v[214:217], v[18:21]
	ds_read_b128 v[230:233], v169 offset:38912
	s_waitcnt lgkmcnt(7)
	v_mfma_f32_16x16x32_bf16 v[142:145], v[234:237], v[184:187], v[142:145]
	v_mfma_f32_16x16x32_bf16 v[78:81], v[234:237], v[198:201], v[78:81]
	v_mfma_f32_16x16x32_bf16 v[46:49], v[234:237], v[210:213], v[46:49]
	v_mfma_f32_16x16x32_bf16 v[14:17], v[234:237], v[214:217], v[14:17]
	ds_read_b128 v[234:237], v169 offset:40960
	s_waitcnt lgkmcnt(7)
	v_mfma_f32_16x16x32_bf16 v[138:141], v[238:241], v[184:187], v[138:141]
	v_mfma_f32_16x16x32_bf16 v[74:77], v[238:241], v[198:201], v[74:77]
	v_mfma_f32_16x16x32_bf16 v[42:45], v[238:241], v[210:213], v[42:45]
	v_mfma_f32_16x16x32_bf16 v[10:13], v[238:241], v[214:217], v[10:13]
	ds_read_b128 v[238:241], v169 offset:43008
	s_waitcnt lgkmcnt(7)
	v_mfma_f32_16x16x32_bf16 v[134:137], v[242:245], v[184:187], v[134:137]
	v_mfma_f32_16x16x32_bf16 v[70:73], v[242:245], v[198:201], v[70:73]
	v_mfma_f32_16x16x32_bf16 v[38:41], v[242:245], v[210:213], v[38:41]
	v_mfma_f32_16x16x32_bf16 v[6:9], v[242:245], v[214:217], v[6:9]
	ds_read_b128 v[242:245], v169 offset:45056
	s_waitcnt lgkmcnt(7)
	v_mfma_f32_16x16x32_bf16 v[98:101], v[246:249], v[184:187], v[98:101]
	v_mfma_f32_16x16x32_bf16 v[66:69], v[246:249], v[198:201], v[66:69]
	v_xor_b32_e32 v169, 64, v207
	v_add3_u32 v169, s21, v0, v169
	ds_read_b128 v[184:187], v169
	ds_read_b128 v[198:201], v169 offset:2048
	v_mfma_f32_16x16x32_bf16 v[34:37], v[246:249], v[210:213], v[34:37]
	ds_read_b128 v[210:213], v169 offset:4096
	v_mfma_f32_16x16x32_bf16 v[2:5], v[246:249], v[214:217], v[2:5]
	ds_read_b128 v[214:217], v169 offset:6144
	v_xor_b32_e32 v169, 64, v207
	v_add3_u32 v169, s21, v167, v169
	ds_read_b128 v[246:249], v169 offset:47104
	s_waitcnt lgkmcnt(1)
	v_mfma_f32_16x16x32_bf16 v[158:161], v[218:221], v[184:187], v[158:161]
	v_mfma_f32_16x16x32_bf16 v[94:97], v[218:221], v[198:201], v[94:97]
	v_mfma_f32_16x16x32_bf16 v[62:65], v[218:221], v[210:213], v[62:65]
	v_mfma_f32_16x16x32_bf16 v[30:33], v[218:221], v[214:217], v[30:33]
	s_waitcnt vmcnt(7)
	ds_write_b128 v171, v[110:113]
	v_mfma_f32_16x16x32_bf16 v[154:157], v[222:225], v[184:187], v[154:157]
	v_mfma_f32_16x16x32_bf16 v[90:93], v[222:225], v[198:201], v[90:93]
	global_load_dwordx4 v[110:113], v168, vcc offset:256
	v_mfma_f32_16x16x32_bf16 v[58:61], v[222:225], v[210:213], v[58:61]
	v_mfma_f32_16x16x32_bf16 v[26:29], v[222:225], v[214:217], v[26:29]
	s_waitcnt vmcnt(7)
	ds_write_b128 v171, v[102:105] offset:8192
	v_mfma_f32_16x16x32_bf16 v[150:153], v[226:229], v[184:187], v[150:153]
	v_mfma_f32_16x16x32_bf16 v[86:89], v[226:229], v[198:201], v[86:89]
	v_add_u32_e32 v102, 0x58000, v168
	global_load_dwordx4 v[102:105], v102, vcc offset:256
	v_mfma_f32_16x16x32_bf16 v[54:57], v[226:229], v[210:213], v[54:57]
	v_mfma_f32_16x16x32_bf16 v[22:25], v[226:229], v[214:217], v[22:25]
	s_waitcnt vmcnt(7)
	ds_write_b128 v171, v[106:109] offset:16384
	v_mfma_f32_16x16x32_bf16 v[146:149], v[230:233], v[184:187], v[146:149]
	v_mfma_f32_16x16x32_bf16 v[82:85], v[230:233], v[198:201], v[82:85]
	v_add_u32_e32 v106, 0xb0000, v168
	global_load_dwordx4 v[106:109], v106, vcc offset:256
	v_mfma_f32_16x16x32_bf16 v[50:53], v[230:233], v[210:213], v[50:53]
	v_mfma_f32_16x16x32_bf16 v[18:21], v[230:233], v[214:217], v[18:21]
	s_waitcnt vmcnt(7)
	ds_write_b128 v171, v[122:125] offset:24576
	v_mfma_f32_16x16x32_bf16 v[142:145], v[234:237], v[184:187], v[142:145]
	v_mfma_f32_16x16x32_bf16 v[78:81], v[234:237], v[198:201], v[78:81]
	v_add_u32_e32 v122, 0x108000, v168
	global_load_dwordx4 v[122:125], v122, vcc offset:256
	v_mfma_f32_16x16x32_bf16 v[46:49], v[234:237], v[210:213], v[46:49]
	v_mfma_f32_16x16x32_bf16 v[14:17], v[234:237], v[214:217], v[14:17]
	s_waitcnt vmcnt(7)
	ds_write_b128 v171, v[118:121] offset:32768
	v_mfma_f32_16x16x32_bf16 v[138:141], v[238:241], v[184:187], v[138:141]
	v_mfma_f32_16x16x32_bf16 v[74:77], v[238:241], v[198:201], v[74:77]
	global_load_dwordx4 v[118:121], v170, s[100:101] offset:256
	v_mfma_f32_16x16x32_bf16 v[42:45], v[238:241], v[210:213], v[42:45]
	v_mfma_f32_16x16x32_bf16 v[10:13], v[238:241], v[214:217], v[10:13]
	s_waitcnt vmcnt(7)
	ds_write_b128 v171, v[114:117] offset:40960
	v_mfma_f32_16x16x32_bf16 v[134:137], v[242:245], v[184:187], v[134:137]
	v_mfma_f32_16x16x32_bf16 v[70:73], v[242:245], v[198:201], v[70:73]
	v_add_u32_e32 v114, 0x58000, v170
	global_load_dwordx4 v[114:117], v114, s[100:101] offset:256
	v_mfma_f32_16x16x32_bf16 v[38:41], v[242:245], v[210:213], v[38:41]
	v_mfma_f32_16x16x32_bf16 v[6:9], v[242:245], v[214:217], v[6:9]
	s_waitcnt vmcnt(7)
	ds_write_b128 v171, v[130:133] offset:49152
	s_waitcnt lgkmcnt(7)
	v_mfma_f32_16x16x32_bf16 v[98:101], v[246:249], v[184:187], v[98:101]
	v_mfma_f32_16x16x32_bf16 v[66:69], v[246:249], v[198:201], v[66:69]
	v_add_u32_e32 v130, 0xb0000, v170
	global_load_dwordx4 v[130:133], v130, s[100:101] offset:256
	v_mfma_f32_16x16x32_bf16 v[34:37], v[246:249], v[210:213], v[34:37]
	v_mfma_f32_16x16x32_bf16 v[2:5], v[246:249], v[214:217], v[2:5]
	s_waitcnt vmcnt(7)
	ds_write_b128 v171, v[126:129] offset:57344
	v_add_u32_e32 v126, 0x108000, v170
	global_load_dwordx4 v[126:129], v126, s[100:101] offset:256
	v_add_u32_e32 v168, 0x80, v168
	v_add_u32_e32 v170, 0x80, v170
	s_waitcnt lgkmcnt(0)
	s_barrier
	s_cmp_eq_u32 s20, 44
	s_mov_b32 s4, s20
	s_cbranch_scc0 .LBB0_534
	s_waitcnt vmcnt(4)
	v_add_u32_e32 v102, s7, v206
	v_or_b32_e32 v104, v102, v205
	v_cmp_lt_i32_e32 vcc, s97, v104
	s_waitcnt vmcnt(3)
	v_ashrrev_i32_e32 v106, 31, v104
	v_add_u32_e32 v107, 0xffffc000, v104
	v_ashrrev_i32_e32 v105, 11, v102
	v_cndmask_b32_e64 v111, v106, 0, vcc
	v_cndmask_b32_e32 v110, v104, v107, vcc
	v_mov_b32_e32 v106, s45
	v_mov_b32_e32 v107, s47
	v_mov_b32_e32 v108, s44
	v_mov_b32_e32 v109, s46
	v_or_b32_e32 v102, s6, v208
	s_waitcnt vmcnt(2)
	v_cndmask_b32_e64 v114, v105, 8, vcc
	v_cndmask_b32_e32 v113, v106, v107, vcc
	v_cndmask_b32_e32 v112, v108, v109, vcc
	v_lshlrev_b64 v[122:123], 12, v[110:111]
	v_ashrrev_i32_e32 v103, 31, v102
	v_lshl_add_u64 v[110:111], v[112:113], 0, v[122:123]
	v_mul_hi_i32_i24_e32 v113, 0x9000, v114
	v_mul_i32_i24_e32 v112, 0x9000, v114
	v_lshl_add_u64 v[112:113], s[12:13], 0, v[112:113]
	v_lshlrev_b64 v[102:103], 2, v[102:103]
	s_waitcnt vmcnt(0)
	v_lshl_add_u64 v[124:125], v[112:113], 0, v[102:103]
	global_load_dwordx4 v[114:117], v[124:125], off
	s_waitcnt vmcnt(1)
	v_lshl_add_u64 v[126:127], v[110:111], 0, v[102:103]
	global_load_dwordx4 v[118:121], v[126:127], off
	v_mov_b32_e32 v110, s49
	v_mov_b32_e32 v111, s17
	v_mov_b32_e32 v112, s48
	v_mov_b32_e32 v113, s16
	v_cndmask_b32_e32 v129, v110, v111, vcc
	v_cndmask_b32_e32 v128, v112, v113, vcc
	v_lshl_add_u64 v[122:123], v[128:129], 0, v[122:123]
	v_lshl_add_u64 v[122:123], v[122:123], 0, v[102:103]
	s_waitcnt vmcnt(1)
	v_pk_mul_f32 v[114:115], v[114:115], 0.5 op_sel_hi:[1,0]
	v_pk_mul_f32 v[116:117], v[116:117], 0.5 op_sel_hi:[1,0]
	s_waitcnt vmcnt(0)
	v_pk_fma_f32 v[114:115], v[158:159], v[114:115], v[118:119]
	v_pk_fma_f32 v[116:117], v[160:161], v[116:117], v[120:121]
	global_store_dwordx4 v[122:123], v[114:117], off
	global_load_dwordx4 v[114:117], v[124:125], off offset:64
	s_nop 0
	global_load_dwordx4 v[118:121], v[126:127], off offset:64
	s_waitcnt vmcnt(1)
	v_pk_mul_f32 v[114:115], v[114:115], 0.5 op_sel_hi:[1,0]
	v_pk_mul_f32 v[116:117], v[116:117], 0.5 op_sel_hi:[1,0]
	s_waitcnt vmcnt(0)
	v_pk_fma_f32 v[114:115], v[154:155], v[114:115], v[118:119]
	v_pk_fma_f32 v[116:117], v[156:157], v[116:117], v[120:121]
	global_store_dwordx4 v[122:123], v[114:117], off offset:64
	global_load_dwordx4 v[114:117], v[124:125], off offset:128
	s_nop 0
	global_load_dwordx4 v[118:121], v[126:127], off offset:128
	s_waitcnt vmcnt(1)
	v_pk_mul_f32 v[114:115], v[114:115], 0.5 op_sel_hi:[1,0]
	v_pk_mul_f32 v[116:117], v[116:117], 0.5 op_sel_hi:[1,0]
	s_waitcnt vmcnt(0)
	v_pk_fma_f32 v[114:115], v[150:151], v[114:115], v[118:119]
	v_pk_fma_f32 v[116:117], v[152:153], v[116:117], v[120:121]
	global_store_dwordx4 v[122:123], v[114:117], off offset:128
	global_load_dwordx4 v[114:117], v[124:125], off offset:192
	s_nop 0
	global_load_dwordx4 v[118:121], v[126:127], off offset:192
	s_waitcnt vmcnt(1)
	v_pk_mul_f32 v[114:115], v[114:115], 0.5 op_sel_hi:[1,0]
	v_pk_mul_f32 v[116:117], v[116:117], 0.5 op_sel_hi:[1,0]
	s_waitcnt vmcnt(0)
	v_pk_fma_f32 v[114:115], v[146:147], v[114:115], v[118:119]
	v_pk_fma_f32 v[116:117], v[148:149], v[116:117], v[120:121]
	global_store_dwordx4 v[122:123], v[114:117], off offset:192
	global_load_dwordx4 v[114:117], v[124:125], off offset:256
	s_nop 0
	global_load_dwordx4 v[118:121], v[126:127], off offset:256
	s_waitcnt vmcnt(1)
	v_pk_mul_f32 v[114:115], v[114:115], 0.5 op_sel_hi:[1,0]
	v_pk_mul_f32 v[116:117], v[116:117], 0.5 op_sel_hi:[1,0]
	s_waitcnt vmcnt(0)
	v_pk_fma_f32 v[114:115], v[142:143], v[114:115], v[118:119]
	v_pk_fma_f32 v[116:117], v[144:145], v[116:117], v[120:121]
	global_store_dwordx4 v[122:123], v[114:117], off offset:256
	global_load_dwordx4 v[114:117], v[124:125], off offset:320
	s_nop 0
	global_load_dwordx4 v[118:121], v[126:127], off offset:320
	s_waitcnt vmcnt(1)
	v_pk_mul_f32 v[114:115], v[114:115], 0.5 op_sel_hi:[1,0]
	v_pk_mul_f32 v[116:117], v[116:117], 0.5 op_sel_hi:[1,0]
	s_waitcnt vmcnt(0)
	v_pk_fma_f32 v[114:115], v[138:139], v[114:115], v[118:119]
	v_pk_fma_f32 v[116:117], v[140:141], v[116:117], v[120:121]
	global_store_dwordx4 v[122:123], v[114:117], off offset:320
	global_load_dwordx4 v[114:117], v[124:125], off offset:384
	s_nop 0
	global_load_dwordx4 v[118:121], v[126:127], off offset:384
	s_waitcnt vmcnt(1)
	v_pk_mul_f32 v[114:115], v[114:115], 0.5 op_sel_hi:[1,0]
	v_pk_mul_f32 v[116:117], v[116:117], 0.5 op_sel_hi:[1,0]
	s_waitcnt vmcnt(0)
	v_pk_fma_f32 v[114:115], v[134:135], v[114:115], v[118:119]
	v_pk_fma_f32 v[116:117], v[136:137], v[116:117], v[120:121]
	global_store_dwordx4 v[122:123], v[114:117], off offset:384
	global_load_dwordx4 v[114:117], v[124:125], off offset:448
	s_nop 0
	global_load_dwordx4 v[118:121], v[126:127], off offset:448
	s_waitcnt vmcnt(1)
	v_pk_mul_f32 v[114:115], v[114:115], 0.5 op_sel_hi:[1,0]
	v_pk_mul_f32 v[116:117], v[116:117], 0.5 op_sel_hi:[1,0]
	s_waitcnt vmcnt(0)
	v_pk_fma_f32 v[98:99], v[98:99], v[114:115], v[118:119]
	v_pk_fma_f32 v[100:101], v[100:101], v[116:117], v[120:121]
	global_store_dwordx4 v[122:123], v[98:101], off offset:448
	s_nop 1
	v_or_b32_e32 v98, 16, v104
	v_cmp_lt_i32_e32 vcc, s97, v98
	v_add_u32_e32 v100, 0xffffc010, v104
	v_ashrrev_i32_e32 v99, 31, v98
	v_cndmask_b32_e64 v116, v105, 8, vcc
	v_cndmask_b32_e64 v99, v99, 0, vcc
	v_cndmask_b32_e32 v98, v98, v100, vcc
	v_lshlrev_b64 v[118:119], 12, v[98:99]
	v_mul_hi_i32_i24_e32 v99, 0x9000, v116
	v_mul_i32_i24_e32 v98, 0x9000, v116
	v_cndmask_b32_e32 v101, v106, v107, vcc
	v_cndmask_b32_e32 v100, v108, v109, vcc
	v_lshl_add_u64 v[98:99], s[12:13], 0, v[98:99]
	v_lshl_add_u64 v[114:115], v[100:101], 0, v[118:119]
	v_lshl_add_u64 v[120:121], v[98:99], 0, v[102:103]
	global_load_dwordx4 v[98:101], v[120:121], off
	v_lshl_add_u64 v[122:123], v[114:115], 0, v[102:103]
	global_load_dwordx4 v[114:117], v[122:123], off
	v_cndmask_b32_e32 v125, v110, v111, vcc
	v_cndmask_b32_e32 v124, v112, v113, vcc
	v_lshl_add_u64 v[118:119], v[124:125], 0, v[118:119]
	v_lshl_add_u64 v[118:119], v[118:119], 0, v[102:103]
	s_waitcnt vmcnt(1)
	v_pk_mul_f32 v[98:99], v[98:99], 0.5 op_sel_hi:[1,0]
	v_pk_mul_f32 v[100:101], v[100:101], 0.5 op_sel_hi:[1,0]
	s_waitcnt vmcnt(0)
	v_pk_fma_f32 v[94:95], v[94:95], v[98:99], v[114:115]
	v_pk_fma_f32 v[96:97], v[96:97], v[100:101], v[116:117]
	global_store_dwordx4 v[118:119], v[94:97], off
	global_load_dwordx4 v[94:97], v[120:121], off offset:64
	s_nop 0
	global_load_dwordx4 v[98:101], v[122:123], off offset:64
	s_waitcnt vmcnt(1)
	v_pk_mul_f32 v[94:95], v[94:95], 0.5 op_sel_hi:[1,0]
	v_pk_mul_f32 v[96:97], v[96:97], 0.5 op_sel_hi:[1,0]
	s_waitcnt vmcnt(0)
	v_pk_fma_f32 v[90:91], v[90:91], v[94:95], v[98:99]
	v_pk_fma_f32 v[92:93], v[92:93], v[96:97], v[100:101]
	global_store_dwordx4 v[118:119], v[90:93], off offset:64
	global_load_dwordx4 v[90:93], v[120:121], off offset:128
	s_nop 0
	global_load_dwordx4 v[94:97], v[122:123], off offset:128
	s_waitcnt vmcnt(1)
	v_pk_mul_f32 v[90:91], v[90:91], 0.5 op_sel_hi:[1,0]
	v_pk_mul_f32 v[92:93], v[92:93], 0.5 op_sel_hi:[1,0]
	s_waitcnt vmcnt(0)
	v_pk_fma_f32 v[86:87], v[86:87], v[90:91], v[94:95]
	v_pk_fma_f32 v[88:89], v[88:89], v[92:93], v[96:97]
	global_store_dwordx4 v[118:119], v[86:89], off offset:128
	global_load_dwordx4 v[86:89], v[120:121], off offset:192
	s_nop 0
	global_load_dwordx4 v[90:93], v[122:123], off offset:192
	s_waitcnt vmcnt(1)
	v_pk_mul_f32 v[86:87], v[86:87], 0.5 op_sel_hi:[1,0]
	v_pk_mul_f32 v[88:89], v[88:89], 0.5 op_sel_hi:[1,0]
	s_waitcnt vmcnt(0)
	v_pk_fma_f32 v[82:83], v[82:83], v[86:87], v[90:91]
	v_pk_fma_f32 v[84:85], v[84:85], v[88:89], v[92:93]
	global_store_dwordx4 v[118:119], v[82:85], off offset:192
	global_load_dwordx4 v[82:85], v[120:121], off offset:256
	s_nop 0
	global_load_dwordx4 v[86:89], v[122:123], off offset:256
	s_waitcnt vmcnt(1)
	v_pk_mul_f32 v[82:83], v[82:83], 0.5 op_sel_hi:[1,0]
	v_pk_mul_f32 v[84:85], v[84:85], 0.5 op_sel_hi:[1,0]
	s_waitcnt vmcnt(0)
	v_pk_fma_f32 v[78:79], v[78:79], v[82:83], v[86:87]
	v_pk_fma_f32 v[80:81], v[80:81], v[84:85], v[88:89]
	global_store_dwordx4 v[118:119], v[78:81], off offset:256
	global_load_dwordx4 v[78:81], v[120:121], off offset:320
	s_nop 0
	global_load_dwordx4 v[82:85], v[122:123], off offset:320
	s_waitcnt vmcnt(1)
	v_pk_mul_f32 v[78:79], v[78:79], 0.5 op_sel_hi:[1,0]
	v_pk_mul_f32 v[80:81], v[80:81], 0.5 op_sel_hi:[1,0]
	s_waitcnt vmcnt(0)
	v_pk_fma_f32 v[74:75], v[74:75], v[78:79], v[82:83]
	v_pk_fma_f32 v[76:77], v[76:77], v[80:81], v[84:85]
	global_store_dwordx4 v[118:119], v[74:77], off offset:320
	global_load_dwordx4 v[74:77], v[120:121], off offset:384
	s_nop 0
	global_load_dwordx4 v[78:81], v[122:123], off offset:384
	s_waitcnt vmcnt(1)
	v_pk_mul_f32 v[74:75], v[74:75], 0.5 op_sel_hi:[1,0]
	v_pk_mul_f32 v[76:77], v[76:77], 0.5 op_sel_hi:[1,0]
	s_waitcnt vmcnt(0)
	v_pk_fma_f32 v[70:71], v[70:71], v[74:75], v[78:79]
	v_pk_fma_f32 v[72:73], v[72:73], v[76:77], v[80:81]
	global_store_dwordx4 v[118:119], v[70:73], off offset:384
	global_load_dwordx4 v[70:73], v[120:121], off offset:448
	s_nop 0
	global_load_dwordx4 v[74:77], v[122:123], off offset:448
	s_waitcnt vmcnt(1)
	v_pk_mul_f32 v[70:71], v[70:71], 0.5 op_sel_hi:[1,0]
	v_pk_mul_f32 v[72:73], v[72:73], 0.5 op_sel_hi:[1,0]
	s_waitcnt vmcnt(0)
	v_pk_fma_f32 v[66:67], v[66:67], v[70:71], v[74:75]
	v_pk_fma_f32 v[68:69], v[68:69], v[72:73], v[76:77]
	global_store_dwordx4 v[118:119], v[66:69], off offset:448
	s_nop 1
	v_or_b32_e32 v66, 32, v104
	v_cmp_lt_i32_e32 vcc, s97, v66
	v_add_u32_e32 v68, 0xffffc020, v104
	v_ashrrev_i32_e32 v67, 31, v66
	v_cndmask_b32_e64 v72, v105, 8, vcc
	v_cndmask_b32_e64 v67, v67, 0, vcc
	v_cndmask_b32_e32 v66, v66, v68, vcc
	v_lshlrev_b64 v[74:75], 12, v[66:67]
	v_mul_hi_i32_i24_e32 v67, 0x9000, v72
	v_mul_i32_i24_e32 v66, 0x9000, v72
	v_cndmask_b32_e32 v69, v106, v107, vcc
	v_cndmask_b32_e32 v68, v108, v109, vcc
	v_lshl_add_u64 v[66:67], s[12:13], 0, v[66:67]
	v_lshl_add_u64 v[70:71], v[68:69], 0, v[74:75]
	v_lshl_add_u64 v[76:77], v[66:67], 0, v[102:103]
	global_load_dwordx4 v[66:69], v[76:77], off
	v_lshl_add_u64 v[78:79], v[70:71], 0, v[102:103]
	global_load_dwordx4 v[70:73], v[78:79], off
	v_cndmask_b32_e32 v81, v110, v111, vcc
	v_cndmask_b32_e32 v80, v112, v113, vcc
	v_lshl_add_u64 v[74:75], v[80:81], 0, v[74:75]
	v_lshl_add_u64 v[74:75], v[74:75], 0, v[102:103]
	s_waitcnt vmcnt(1)
	v_pk_mul_f32 v[66:67], v[66:67], 0.5 op_sel_hi:[1,0]
	v_pk_mul_f32 v[68:69], v[68:69], 0.5 op_sel_hi:[1,0]
	s_waitcnt vmcnt(0)
	v_pk_fma_f32 v[62:63], v[62:63], v[66:67], v[70:71]
	v_pk_fma_f32 v[64:65], v[64:65], v[68:69], v[72:73]
	global_store_dwordx4 v[74:75], v[62:65], off
	global_load_dwordx4 v[62:65], v[76:77], off offset:64
	s_nop 0
	global_load_dwordx4 v[66:69], v[78:79], off offset:64
	s_waitcnt vmcnt(1)
	v_pk_mul_f32 v[62:63], v[62:63], 0.5 op_sel_hi:[1,0]
	v_pk_mul_f32 v[64:65], v[64:65], 0.5 op_sel_hi:[1,0]
	s_waitcnt vmcnt(0)
	v_pk_fma_f32 v[58:59], v[58:59], v[62:63], v[66:67]
	v_pk_fma_f32 v[60:61], v[60:61], v[64:65], v[68:69]
	global_store_dwordx4 v[74:75], v[58:61], off offset:64
	global_load_dwordx4 v[58:61], v[76:77], off offset:128
	s_nop 0
	global_load_dwordx4 v[62:65], v[78:79], off offset:128
	s_waitcnt vmcnt(1)
	v_pk_mul_f32 v[58:59], v[58:59], 0.5 op_sel_hi:[1,0]
	v_pk_mul_f32 v[60:61], v[60:61], 0.5 op_sel_hi:[1,0]
	s_waitcnt vmcnt(0)
	v_pk_fma_f32 v[54:55], v[54:55], v[58:59], v[62:63]
	v_pk_fma_f32 v[56:57], v[56:57], v[60:61], v[64:65]
	global_store_dwordx4 v[74:75], v[54:57], off offset:128
	global_load_dwordx4 v[54:57], v[76:77], off offset:192
	s_nop 0
	global_load_dwordx4 v[58:61], v[78:79], off offset:192
	s_waitcnt vmcnt(1)
	v_pk_mul_f32 v[54:55], v[54:55], 0.5 op_sel_hi:[1,0]
	v_pk_mul_f32 v[56:57], v[56:57], 0.5 op_sel_hi:[1,0]
	s_waitcnt vmcnt(0)
	v_pk_fma_f32 v[50:51], v[50:51], v[54:55], v[58:59]
	v_pk_fma_f32 v[52:53], v[52:53], v[56:57], v[60:61]
	global_store_dwordx4 v[74:75], v[50:53], off offset:192
	global_load_dwordx4 v[50:53], v[76:77], off offset:256
	s_nop 0
	global_load_dwordx4 v[54:57], v[78:79], off offset:256
	s_waitcnt vmcnt(1)
	v_pk_mul_f32 v[50:51], v[50:51], 0.5 op_sel_hi:[1,0]
	v_pk_mul_f32 v[52:53], v[52:53], 0.5 op_sel_hi:[1,0]
	s_waitcnt vmcnt(0)
	v_pk_fma_f32 v[46:47], v[46:47], v[50:51], v[54:55]
	v_pk_fma_f32 v[48:49], v[48:49], v[52:53], v[56:57]
	global_store_dwordx4 v[74:75], v[46:49], off offset:256
	global_load_dwordx4 v[46:49], v[76:77], off offset:320
	s_nop 0
	global_load_dwordx4 v[50:53], v[78:79], off offset:320
	s_waitcnt vmcnt(1)
	v_pk_mul_f32 v[46:47], v[46:47], 0.5 op_sel_hi:[1,0]
	v_pk_mul_f32 v[48:49], v[48:49], 0.5 op_sel_hi:[1,0]
	s_waitcnt vmcnt(0)
	v_pk_fma_f32 v[42:43], v[42:43], v[46:47], v[50:51]
	v_pk_fma_f32 v[44:45], v[44:45], v[48:49], v[52:53]
	global_store_dwordx4 v[74:75], v[42:45], off offset:320
	global_load_dwordx4 v[42:45], v[76:77], off offset:384
	s_nop 0
	global_load_dwordx4 v[46:49], v[78:79], off offset:384
	s_waitcnt vmcnt(1)
	v_pk_mul_f32 v[42:43], v[42:43], 0.5 op_sel_hi:[1,0]
	v_pk_mul_f32 v[44:45], v[44:45], 0.5 op_sel_hi:[1,0]
	s_waitcnt vmcnt(0)
	v_pk_fma_f32 v[38:39], v[38:39], v[42:43], v[46:47]
	v_pk_fma_f32 v[40:41], v[40:41], v[44:45], v[48:49]
	global_store_dwordx4 v[74:75], v[38:41], off offset:384
	global_load_dwordx4 v[38:41], v[76:77], off offset:448
	s_nop 0
	global_load_dwordx4 v[42:45], v[78:79], off offset:448
	s_waitcnt vmcnt(1)
	v_pk_mul_f32 v[38:39], v[38:39], 0.5 op_sel_hi:[1,0]
	v_pk_mul_f32 v[40:41], v[40:41], 0.5 op_sel_hi:[1,0]
	s_waitcnt vmcnt(0)
	v_pk_fma_f32 v[34:35], v[34:35], v[38:39], v[42:43]
	v_pk_fma_f32 v[36:37], v[36:37], v[40:41], v[44:45]
	global_store_dwordx4 v[74:75], v[34:37], off offset:448
	s_nop 1
	v_or_b32_e32 v34, 48, v104
	v_cmp_lt_i32_e32 vcc, s97, v34
	v_add_u32_e32 v36, 0xffffc030, v104
	v_ashrrev_i32_e32 v35, 31, v34
	v_cndmask_b32_e64 v35, v35, 0, vcc
	v_cndmask_b32_e32 v34, v34, v36, vcc
	v_cndmask_b32_e64 v40, v105, 8, vcc
	v_cndmask_b32_e32 v37, v106, v107, vcc
	v_cndmask_b32_e32 v36, v108, v109, vcc
	v_lshlrev_b64 v[34:35], 12, v[34:35]
	v_cndmask_b32_e32 v39, v110, v111, vcc
	v_cndmask_b32_e32 v38, v112, v113, vcc
	v_lshl_add_u64 v[36:37], v[36:37], 0, v[34:35]
	v_lshl_add_u64 v[34:35], v[38:39], 0, v[34:35]
	v_mul_hi_i32_i24_e32 v39, 0x9000, v40
	v_mul_i32_i24_e32 v38, 0x9000, v40
	v_lshl_add_u64 v[38:39], s[12:13], 0, v[38:39]
	v_lshl_add_u64 v[42:43], v[38:39], 0, v[102:103]
	v_lshl_add_u64 v[44:45], v[36:37], 0, v[102:103]
	v_lshl_add_u64 v[46:47], v[34:35], 0, v[102:103]
	global_load_dwordx4 v[34:37], v[42:43], off
	global_load_dwordx4 v[38:41], v[44:45], off
	s_waitcnt vmcnt(1)
	v_pk_mul_f32 v[34:35], v[34:35], 0.5 op_sel_hi:[1,0]
	s_waitcnt vmcnt(0)
	v_pk_fma_f32 v[30:31], v[30:31], v[34:35], v[38:39]
	v_pk_mul_f32 v[34:35], v[36:37], 0.5 op_sel_hi:[1,0]
	s_nop 0
	v_pk_fma_f32 v[32:33], v[32:33], v[34:35], v[40:41]
	global_store_dwordx4 v[46:47], v[30:33], off
	global_load_dwordx4 v[30:33], v[42:43], off offset:64
	s_nop 0
	global_load_dwordx4 v[34:37], v[44:45], off offset:64
	s_waitcnt vmcnt(1)
	v_pk_mul_f32 v[30:31], v[30:31], 0.5 op_sel_hi:[1,0]
	s_waitcnt vmcnt(0)
	v_pk_fma_f32 v[26:27], v[26:27], v[30:31], v[34:35]
	v_pk_mul_f32 v[30:31], v[32:33], 0.5 op_sel_hi:[1,0]
	s_nop 0
	v_pk_fma_f32 v[28:29], v[28:29], v[30:31], v[36:37]
	global_store_dwordx4 v[46:47], v[26:29], off offset:64
	global_load_dwordx4 v[26:29], v[42:43], off offset:128
	s_nop 0
	global_load_dwordx4 v[30:33], v[44:45], off offset:128
	s_waitcnt vmcnt(1)
	v_pk_mul_f32 v[26:27], v[26:27], 0.5 op_sel_hi:[1,0]
	s_waitcnt vmcnt(0)
	v_pk_fma_f32 v[22:23], v[22:23], v[26:27], v[30:31]
	v_pk_mul_f32 v[26:27], v[28:29], 0.5 op_sel_hi:[1,0]
	s_nop 0
	v_pk_fma_f32 v[24:25], v[24:25], v[26:27], v[32:33]
	global_store_dwordx4 v[46:47], v[22:25], off offset:128
	global_load_dwordx4 v[22:25], v[42:43], off offset:192
	s_nop 0
	global_load_dwordx4 v[26:29], v[44:45], off offset:192
	s_waitcnt vmcnt(1)
	v_pk_mul_f32 v[22:23], v[22:23], 0.5 op_sel_hi:[1,0]
	s_waitcnt vmcnt(0)
	v_pk_fma_f32 v[18:19], v[18:19], v[22:23], v[26:27]
	v_pk_mul_f32 v[22:23], v[24:25], 0.5 op_sel_hi:[1,0]
	s_nop 0
	v_pk_fma_f32 v[20:21], v[20:21], v[22:23], v[28:29]
	global_store_dwordx4 v[46:47], v[18:21], off offset:192
	global_load_dwordx4 v[18:21], v[42:43], off offset:256
	s_nop 0
	global_load_dwordx4 v[22:25], v[44:45], off offset:256
	s_waitcnt vmcnt(1)
	v_pk_mul_f32 v[18:19], v[18:19], 0.5 op_sel_hi:[1,0]
	s_waitcnt vmcnt(0)
	v_pk_fma_f32 v[14:15], v[14:15], v[18:19], v[22:23]
	v_pk_mul_f32 v[18:19], v[20:21], 0.5 op_sel_hi:[1,0]
	s_nop 0
	v_pk_fma_f32 v[16:17], v[16:17], v[18:19], v[24:25]
	global_store_dwordx4 v[46:47], v[14:17], off offset:256
	global_load_dwordx4 v[14:17], v[42:43], off offset:320
	s_nop 0
	global_load_dwordx4 v[18:21], v[44:45], off offset:320
	s_waitcnt vmcnt(1)
	v_pk_mul_f32 v[14:15], v[14:15], 0.5 op_sel_hi:[1,0]
	s_waitcnt vmcnt(0)
	v_pk_fma_f32 v[10:11], v[10:11], v[14:15], v[18:19]
	v_pk_mul_f32 v[14:15], v[16:17], 0.5 op_sel_hi:[1,0]
	s_nop 0
	v_pk_fma_f32 v[12:13], v[12:13], v[14:15], v[20:21]
	global_store_dwordx4 v[46:47], v[10:13], off offset:320
	global_load_dwordx4 v[10:13], v[42:43], off offset:384
	s_nop 0
	global_load_dwordx4 v[14:17], v[44:45], off offset:384
	s_waitcnt vmcnt(1)
	v_pk_mul_f32 v[10:11], v[10:11], 0.5 op_sel_hi:[1,0]
	s_waitcnt vmcnt(0)
	v_pk_fma_f32 v[6:7], v[6:7], v[10:11], v[14:15]
	v_pk_mul_f32 v[10:11], v[12:13], 0.5 op_sel_hi:[1,0]
	s_nop 0
	v_pk_fma_f32 v[8:9], v[8:9], v[10:11], v[16:17]
	global_store_dwordx4 v[46:47], v[6:9], off offset:384
	global_load_dwordx4 v[6:9], v[42:43], off offset:448
	s_nop 0
	global_load_dwordx4 v[10:13], v[44:45], off offset:448
	s_waitcnt vmcnt(1)
	v_pk_mul_f32 v[6:7], v[6:7], 0.5 op_sel_hi:[1,0]
	s_waitcnt vmcnt(0)
	v_pk_fma_f32 v[2:3], v[2:3], v[6:7], v[10:11]
	v_pk_mul_f32 v[6:7], v[8:9], 0.5 op_sel_hi:[1,0]
	s_nop 0
	v_pk_fma_f32 v[4:5], v[4:5], v[6:7], v[12:13]
	global_store_dwordx4 v[46:47], v[2:5], off offset:448
	s_add_i32 s11, s11, s10
	s_cmpk_gt_i32 s11, 0xff
	s_cbranch_scc0 .LBB0_533

.LBB0_665:
	s_bitcmp1_b32 s4, 0
	s_cselect_b32 s15, 0x12000, 0
	v_or_b32_e32 v208, s15, v206
	v_add_u32_e32 v214, v208, v0
	v_add_u32_e32 v208, v208, v167
	ds_read_b128 v[184:187], v214
	ds_read_b128 v[198:201], v214 offset:2048
	ds_read_b128 v[210:213], v214 offset:4096
	ds_read_b128 v[214:217], v214 offset:6144
	ds_read_b128 v[218:221], v208 offset:32768
	ds_read_b128 v[222:225], v208 offset:34816
	ds_read_b128 v[226:229], v208 offset:36864
	ds_read_b128 v[230:233], v208 offset:38912
	ds_read_b128 v[234:237], v208 offset:40960
	ds_read_b128 v[238:241], v208 offset:43008
	ds_read_b128 v[242:245], v208 offset:45056
	ds_read_b128 v[246:249], v208 offset:47104
	s_add_i32 s14, s4, 1
	s_bitcmp1_b32 s14, 0
	s_cselect_b32 s16, 0x12000, 0
	v_add_u32_e32 v208, s16, v166
	v_add_u32_e32 v171, s16, v166
	v_xor_b32_e32 v169, 64, v206
	v_add3_u32 v169, s15, v167, v169
	s_waitcnt lgkmcnt(7)
	v_mfma_f32_16x16x32_bf16 v[158:161], v[218:221], v[184:187], v[158:161]
	v_mfma_f32_16x16x32_bf16 v[130:133], v[218:221], v[198:201], v[130:133]
	v_mfma_f32_16x16x32_bf16 v[66:69], v[218:221], v[210:213], v[66:69]
	v_mfma_f32_16x16x32_bf16 v[34:37], v[218:221], v[214:217], v[34:37]
	ds_read_b128 v[218:221], v169 offset:32768
	s_waitcnt lgkmcnt(7)
	v_mfma_f32_16x16x32_bf16 v[154:157], v[222:225], v[184:187], v[154:157]
	v_mfma_f32_16x16x32_bf16 v[122:125], v[222:225], v[198:201], v[122:125]
	v_mfma_f32_16x16x32_bf16 v[58:61], v[222:225], v[210:213], v[58:61]
	v_mfma_f32_16x16x32_bf16 v[26:29], v[222:225], v[214:217], v[26:29]
	ds_read_b128 v[222:225], v169 offset:34816
	s_waitcnt lgkmcnt(7)
	v_mfma_f32_16x16x32_bf16 v[150:153], v[226:229], v[184:187], v[150:153]
	v_mfma_f32_16x16x32_bf16 v[114:117], v[226:229], v[198:201], v[114:117]
	v_mfma_f32_16x16x32_bf16 v[54:57], v[226:229], v[210:213], v[54:57]
	v_mfma_f32_16x16x32_bf16 v[22:25], v[226:229], v[214:217], v[22:25]
	ds_read_b128 v[226:229], v169 offset:36864
	s_waitcnt lgkmcnt(7)
	v_mfma_f32_16x16x32_bf16 v[146:149], v[230:233], v[184:187], v[146:149]
	v_mfma_f32_16x16x32_bf16 v[82:85], v[230:233], v[198:201], v[82:85]
	v_mfma_f32_16x16x32_bf16 v[50:53], v[230:233], v[210:213], v[50:53]
	v_mfma_f32_16x16x32_bf16 v[18:21], v[230:233], v[214:217], v[18:21]
	ds_read_b128 v[230:233], v169 offset:38912
	s_waitcnt lgkmcnt(7)
	v_mfma_f32_16x16x32_bf16 v[142:145], v[234:237], v[184:187], v[142:145]
	v_mfma_f32_16x16x32_bf16 v[78:81], v[234:237], v[198:201], v[78:81]
	v_mfma_f32_16x16x32_bf16 v[46:49], v[234:237], v[210:213], v[46:49]
	v_mfma_f32_16x16x32_bf16 v[14:17], v[234:237], v[214:217], v[14:17]
	ds_read_b128 v[234:237], v169 offset:40960
	s_waitcnt lgkmcnt(7)
	v_mfma_f32_16x16x32_bf16 v[138:141], v[238:241], v[184:187], v[138:141]
	v_mfma_f32_16x16x32_bf16 v[74:77], v[238:241], v[198:201], v[74:77]
	v_mfma_f32_16x16x32_bf16 v[42:45], v[238:241], v[210:213], v[42:45]
	v_mfma_f32_16x16x32_bf16 v[10:13], v[238:241], v[214:217], v[10:13]
	ds_read_b128 v[238:241], v169 offset:43008
	s_waitcnt lgkmcnt(7)
	v_mfma_f32_16x16x32_bf16 v[134:137], v[242:245], v[184:187], v[134:137]
	v_mfma_f32_16x16x32_bf16 v[70:73], v[242:245], v[198:201], v[70:73]
	v_mfma_f32_16x16x32_bf16 v[38:41], v[242:245], v[210:213], v[38:41]
	v_mfma_f32_16x16x32_bf16 v[6:9], v[242:245], v[214:217], v[6:9]
	ds_read_b128 v[242:245], v169 offset:45056
	s_waitcnt lgkmcnt(7)
	v_mfma_f32_16x16x32_bf16 v[126:129], v[246:249], v[184:187], v[126:129]
	v_mfma_f32_16x16x32_bf16 v[62:65], v[246:249], v[198:201], v[62:65]
	v_xor_b32_e32 v169, 64, v206
	v_add3_u32 v169, s15, v0, v169
	ds_read_b128 v[184:187], v169
	ds_read_b128 v[198:201], v169 offset:2048
	v_mfma_f32_16x16x32_bf16 v[30:33], v[246:249], v[210:213], v[30:33]
	ds_read_b128 v[210:213], v169 offset:4096
	v_mfma_f32_16x16x32_bf16 v[2:5], v[246:249], v[214:217], v[2:5]
	ds_read_b128 v[214:217], v169 offset:6144
	v_xor_b32_e32 v169, 64, v206
	v_add3_u32 v169, s15, v167, v169
	ds_read_b128 v[246:249], v169 offset:47104
	s_waitcnt lgkmcnt(1)
	v_mfma_f32_16x16x32_bf16 v[158:161], v[218:221], v[184:187], v[158:161]
	v_mfma_f32_16x16x32_bf16 v[130:133], v[218:221], v[198:201], v[130:133]
	v_mfma_f32_16x16x32_bf16 v[66:69], v[218:221], v[210:213], v[66:69]
	v_mfma_f32_16x16x32_bf16 v[34:37], v[218:221], v[214:217], v[34:37]
	s_waitcnt vmcnt(7)
	ds_write_b128 v171, v[94:97]
	v_mfma_f32_16x16x32_bf16 v[154:157], v[222:225], v[184:187], v[154:157]
	v_mfma_f32_16x16x32_bf16 v[122:125], v[222:225], v[198:201], v[122:125]
	global_load_dwordx4 v[94:97], v168, vcc offset:256
	v_mfma_f32_16x16x32_bf16 v[58:61], v[222:225], v[210:213], v[58:61]
	v_mfma_f32_16x16x32_bf16 v[26:29], v[222:225], v[214:217], v[26:29]
	s_waitcnt vmcnt(7)
	ds_write_b128 v171, v[86:89] offset:8192
	v_mfma_f32_16x16x32_bf16 v[150:153], v[226:229], v[184:187], v[150:153]
	v_mfma_f32_16x16x32_bf16 v[114:117], v[226:229], v[198:201], v[114:117]
	v_add_u32_e32 v86, s34, v168
	global_load_dwordx4 v[86:89], v86, vcc offset:256
	v_mfma_f32_16x16x32_bf16 v[54:57], v[226:229], v[210:213], v[54:57]
	v_mfma_f32_16x16x32_bf16 v[22:25], v[226:229], v[214:217], v[22:25]
	s_waitcnt vmcnt(7)
	ds_write_b128 v171, v[90:93] offset:16384
	v_mfma_f32_16x16x32_bf16 v[146:149], v[230:233], v[184:187], v[146:149]
	v_mfma_f32_16x16x32_bf16 v[82:85], v[230:233], v[198:201], v[82:85]
	v_add_u32_e32 v90, s35, v168
	global_load_dwordx4 v[90:93], v90, vcc offset:256
	v_mfma_f32_16x16x32_bf16 v[50:53], v[230:233], v[210:213], v[50:53]
	v_mfma_f32_16x16x32_bf16 v[18:21], v[230:233], v[214:217], v[18:21]
	s_waitcnt vmcnt(7)
	ds_write_b128 v171, v[106:109] offset:24576
	v_mfma_f32_16x16x32_bf16 v[142:145], v[234:237], v[184:187], v[142:145]
	v_mfma_f32_16x16x32_bf16 v[78:81], v[234:237], v[198:201], v[78:81]
	v_add_u32_e32 v106, s36, v168
	global_load_dwordx4 v[106:109], v106, vcc offset:256
	v_mfma_f32_16x16x32_bf16 v[46:49], v[234:237], v[210:213], v[46:49]
	v_mfma_f32_16x16x32_bf16 v[14:17], v[234:237], v[214:217], v[14:17]
	s_waitcnt vmcnt(7)
	ds_write_b128 v171, v[102:105] offset:32768
	v_mfma_f32_16x16x32_bf16 v[138:141], v[238:241], v[184:187], v[138:141]
	v_mfma_f32_16x16x32_bf16 v[74:77], v[238:241], v[198:201], v[74:77]
	global_load_dwordx4 v[102:105], v170, s[100:101] offset:256
	v_mfma_f32_16x16x32_bf16 v[42:45], v[238:241], v[210:213], v[42:45]
	v_mfma_f32_16x16x32_bf16 v[10:13], v[238:241], v[214:217], v[10:13]
	s_waitcnt vmcnt(7)
	ds_write_b128 v171, v[98:101] offset:40960
	v_mfma_f32_16x16x32_bf16 v[134:137], v[242:245], v[184:187], v[134:137]
	v_mfma_f32_16x16x32_bf16 v[70:73], v[242:245], v[198:201], v[70:73]
	v_add_u32_e32 v98, s34, v170
	global_load_dwordx4 v[98:101], v98, s[100:101] offset:256
	v_mfma_f32_16x16x32_bf16 v[38:41], v[242:245], v[210:213], v[38:41]
	v_mfma_f32_16x16x32_bf16 v[6:9], v[242:245], v[214:217], v[6:9]
	s_waitcnt vmcnt(7)
	ds_write_b128 v171, v[118:121] offset:49152
	s_waitcnt lgkmcnt(7)
	v_mfma_f32_16x16x32_bf16 v[126:129], v[246:249], v[184:187], v[126:129]
	v_mfma_f32_16x16x32_bf16 v[62:65], v[246:249], v[198:201], v[62:65]
	v_add_u32_e32 v118, s35, v170
	global_load_dwordx4 v[118:121], v118, s[100:101] offset:256
	v_mfma_f32_16x16x32_bf16 v[30:33], v[246:249], v[210:213], v[30:33]
	v_mfma_f32_16x16x32_bf16 v[2:5], v[246:249], v[214:217], v[2:5]
	s_waitcnt vmcnt(7)
	ds_write_b128 v171, v[110:113] offset:57344
	v_add_u32_e32 v110, s36, v170
	global_load_dwordx4 v[110:113], v110, s[100:101] offset:256
	v_add_u32_e32 v168, 0x80, v168
	v_add_u32_e32 v170, 0x80, v170
	s_waitcnt lgkmcnt(0)
	s_barrier
	s_cmp_eq_u32 s14, 16
	s_mov_b32 s4, s14
	s_cbranch_scc0 .LBB0_665
	s_waitcnt vmcnt(3)
	v_and_b32_sdwa v93, v158, v177 dst_sel:DWORD dst_unused:UNUSED_PAD src0_sel:WORD_1 src1_sel:DWORD
	v_or_b32_e32 v88, s7, v207
	v_add3_u32 v95, v158, v93, s28
	v_and_b32_sdwa v93, v161, v177 dst_sel:DWORD dst_unused:UNUSED_PAD src0_sel:WORD_1 src1_sel:DWORD
	v_and_b32_sdwa v96, v159, v177 dst_sel:DWORD dst_unused:UNUSED_PAD src0_sel:WORD_1 src1_sel:DWORD
	v_add_u32_e32 v94, s6, v205
	v_mov_b64_e32 v[86:87], s[12:13]
	v_ashrrev_i32_e32 v89, 31, v88
	v_and_b32_sdwa v92, v160, v177 dst_sel:DWORD dst_unused:UNUSED_PAD src0_sel:WORD_1 src1_sel:DWORD
	v_add3_u32 v93, v161, v93, s28
	v_add3_u32 v96, v159, v96, s28
	v_mad_i64_i32 v[90:91], s[6:7], v94, s8, v[86:87]
	v_lshlrev_b64 v[88:89], 1, v[88:89]
	v_add3_u32 v92, v160, v92, s28
	v_and_b32_e32 v93, 0xffff0000, v93
	v_and_b32_e32 v96, 0xffff0000, v96
	v_lshl_add_u64 v[90:91], v[90:91], 0, v[88:89]
	v_or_b32_sdwa v93, v93, v92 dst_sel:DWORD dst_unused:UNUSED_PAD src0_sel:DWORD src1_sel:WORD_1
	v_or_b32_sdwa v92, v96, v95 dst_sel:DWORD dst_unused:UNUSED_PAD src0_sel:DWORD src1_sel:WORD_1
	s_waitcnt vmcnt(0)
	global_store_dwordx2 v[90:91], v[92:93], off
	v_and_b32_sdwa v93, v154, v177 dst_sel:DWORD dst_unused:UNUSED_PAD src0_sel:WORD_1 src1_sel:DWORD
	v_add3_u32 v95, v154, v93, s28
	v_and_b32_sdwa v93, v157, v177 dst_sel:DWORD dst_unused:UNUSED_PAD src0_sel:WORD_1 src1_sel:DWORD
	v_and_b32_sdwa v96, v155, v177 dst_sel:DWORD dst_unused:UNUSED_PAD src0_sel:WORD_1 src1_sel:DWORD
	v_and_b32_sdwa v92, v156, v177 dst_sel:DWORD dst_unused:UNUSED_PAD src0_sel:WORD_1 src1_sel:DWORD
	v_add3_u32 v93, v157, v93, s28
	v_add3_u32 v96, v155, v96, s28
	v_add3_u32 v92, v156, v92, s28
	v_and_b32_e32 v93, 0xffff0000, v93
	v_and_b32_e32 v96, 0xffff0000, v96
	v_or_b32_sdwa v93, v93, v92 dst_sel:DWORD dst_unused:UNUSED_PAD src0_sel:DWORD src1_sel:WORD_1
	v_or_b32_sdwa v92, v96, v95 dst_sel:DWORD dst_unused:UNUSED_PAD src0_sel:DWORD src1_sel:WORD_1
	global_store_dwordx2 v[90:91], v[92:93], off offset:32
	v_and_b32_sdwa v93, v150, v177 dst_sel:DWORD dst_unused:UNUSED_PAD src0_sel:WORD_1 src1_sel:DWORD
	v_add3_u32 v95, v150, v93, s28
	v_and_b32_sdwa v93, v153, v177 dst_sel:DWORD dst_unused:UNUSED_PAD src0_sel:WORD_1 src1_sel:DWORD
	v_and_b32_sdwa v96, v151, v177 dst_sel:DWORD dst_unused:UNUSED_PAD src0_sel:WORD_1 src1_sel:DWORD
	v_and_b32_sdwa v92, v152, v177 dst_sel:DWORD dst_unused:UNUSED_PAD src0_sel:WORD_1 src1_sel:DWORD
	v_add3_u32 v93, v153, v93, s28
	v_add3_u32 v96, v151, v96, s28
	v_add3_u32 v92, v152, v92, s28
	v_and_b32_e32 v93, 0xffff0000, v93
	v_and_b32_e32 v96, 0xffff0000, v96
	v_or_b32_sdwa v93, v93, v92 dst_sel:DWORD dst_unused:UNUSED_PAD src0_sel:DWORD src1_sel:WORD_1
	v_or_b32_sdwa v92, v96, v95 dst_sel:DWORD dst_unused:UNUSED_PAD src0_sel:DWORD src1_sel:WORD_1
	global_store_dwordx2 v[90:91], v[92:93], off offset:64
	v_and_b32_sdwa v93, v146, v177 dst_sel:DWORD dst_unused:UNUSED_PAD src0_sel:WORD_1 src1_sel:DWORD
	v_add3_u32 v95, v146, v93, s28
	v_and_b32_sdwa v93, v149, v177 dst_sel:DWORD dst_unused:UNUSED_PAD src0_sel:WORD_1 src1_sel:DWORD
	v_and_b32_sdwa v96, v147, v177 dst_sel:DWORD dst_unused:UNUSED_PAD src0_sel:WORD_1 src1_sel:DWORD
	v_and_b32_sdwa v92, v148, v177 dst_sel:DWORD dst_unused:UNUSED_PAD src0_sel:WORD_1 src1_sel:DWORD
	v_add3_u32 v93, v149, v93, s28
	v_add3_u32 v96, v147, v96, s28
	v_add3_u32 v92, v148, v92, s28
	v_and_b32_e32 v93, 0xffff0000, v93
	v_and_b32_e32 v96, 0xffff0000, v96
	v_or_b32_sdwa v93, v93, v92 dst_sel:DWORD dst_unused:UNUSED_PAD src0_sel:DWORD src1_sel:WORD_1
	v_or_b32_sdwa v92, v96, v95 dst_sel:DWORD dst_unused:UNUSED_PAD src0_sel:DWORD src1_sel:WORD_1
	global_store_dwordx2 v[90:91], v[92:93], off offset:96
	v_and_b32_sdwa v93, v142, v177 dst_sel:DWORD dst_unused:UNUSED_PAD src0_sel:WORD_1 src1_sel:DWORD
	v_add3_u32 v95, v142, v93, s28
	v_and_b32_sdwa v93, v145, v177 dst_sel:DWORD dst_unused:UNUSED_PAD src0_sel:WORD_1 src1_sel:DWORD
	v_and_b32_sdwa v96, v143, v177 dst_sel:DWORD dst_unused:UNUSED_PAD src0_sel:WORD_1 src1_sel:DWORD
	v_and_b32_sdwa v92, v144, v177 dst_sel:DWORD dst_unused:UNUSED_PAD src0_sel:WORD_1 src1_sel:DWORD
	v_add3_u32 v93, v145, v93, s28
	v_add3_u32 v96, v143, v96, s28
	v_add3_u32 v92, v144, v92, s28
	v_and_b32_e32 v93, 0xffff0000, v93
	v_and_b32_e32 v96, 0xffff0000, v96
	v_or_b32_sdwa v93, v93, v92 dst_sel:DWORD dst_unused:UNUSED_PAD src0_sel:DWORD src1_sel:WORD_1
	v_or_b32_sdwa v92, v96, v95 dst_sel:DWORD dst_unused:UNUSED_PAD src0_sel:DWORD src1_sel:WORD_1
	global_store_dwordx2 v[90:91], v[92:93], off offset:128
	v_and_b32_sdwa v93, v138, v177 dst_sel:DWORD dst_unused:UNUSED_PAD src0_sel:WORD_1 src1_sel:DWORD
	v_add3_u32 v95, v138, v93, s28
	v_and_b32_sdwa v93, v141, v177 dst_sel:DWORD dst_unused:UNUSED_PAD src0_sel:WORD_1 src1_sel:DWORD
	v_and_b32_sdwa v96, v139, v177 dst_sel:DWORD dst_unused:UNUSED_PAD src0_sel:WORD_1 src1_sel:DWORD
	v_and_b32_sdwa v92, v140, v177 dst_sel:DWORD dst_unused:UNUSED_PAD src0_sel:WORD_1 src1_sel:DWORD
	v_add3_u32 v93, v141, v93, s28
	v_add3_u32 v96, v139, v96, s28
	v_add3_u32 v92, v140, v92, s28
	v_and_b32_e32 v93, 0xffff0000, v93
	v_and_b32_e32 v96, 0xffff0000, v96
	v_or_b32_sdwa v93, v93, v92 dst_sel:DWORD dst_unused:UNUSED_PAD src0_sel:DWORD src1_sel:WORD_1
	v_or_b32_sdwa v92, v96, v95 dst_sel:DWORD dst_unused:UNUSED_PAD src0_sel:DWORD src1_sel:WORD_1
	global_store_dwordx2 v[90:91], v[92:93], off offset:160
	v_and_b32_sdwa v93, v134, v177 dst_sel:DWORD dst_unused:UNUSED_PAD src0_sel:WORD_1 src1_sel:DWORD
	v_add3_u32 v95, v134, v93, s28
	v_and_b32_sdwa v93, v137, v177 dst_sel:DWORD dst_unused:UNUSED_PAD src0_sel:WORD_1 src1_sel:DWORD
	v_and_b32_sdwa v96, v135, v177 dst_sel:DWORD dst_unused:UNUSED_PAD src0_sel:WORD_1 src1_sel:DWORD
	v_and_b32_sdwa v92, v136, v177 dst_sel:DWORD dst_unused:UNUSED_PAD src0_sel:WORD_1 src1_sel:DWORD
	v_add3_u32 v93, v137, v93, s28
	v_add3_u32 v96, v135, v96, s28
	v_add3_u32 v92, v136, v92, s28
	v_and_b32_e32 v93, 0xffff0000, v93
	v_and_b32_e32 v96, 0xffff0000, v96
	v_or_b32_sdwa v93, v93, v92 dst_sel:DWORD dst_unused:UNUSED_PAD src0_sel:DWORD src1_sel:WORD_1
	v_or_b32_sdwa v92, v96, v95 dst_sel:DWORD dst_unused:UNUSED_PAD src0_sel:DWORD src1_sel:WORD_1
	global_store_dwordx2 v[90:91], v[92:93], off offset:192
	v_and_b32_sdwa v93, v126, v177 dst_sel:DWORD dst_unused:UNUSED_PAD src0_sel:WORD_1 src1_sel:DWORD
	v_add3_u32 v95, v126, v93, s28
	v_and_b32_sdwa v93, v129, v177 dst_sel:DWORD dst_unused:UNUSED_PAD src0_sel:WORD_1 src1_sel:DWORD
	v_and_b32_sdwa v96, v127, v177 dst_sel:DWORD dst_unused:UNUSED_PAD src0_sel:WORD_1 src1_sel:DWORD
	v_and_b32_sdwa v92, v128, v177 dst_sel:DWORD dst_unused:UNUSED_PAD src0_sel:WORD_1 src1_sel:DWORD
	v_add3_u32 v93, v129, v93, s28
	v_add3_u32 v96, v127, v96, s28
	v_add3_u32 v92, v128, v92, s28
	v_and_b32_e32 v93, 0xffff0000, v93
	v_and_b32_e32 v96, 0xffff0000, v96
	v_or_b32_sdwa v93, v93, v92 dst_sel:DWORD dst_unused:UNUSED_PAD src0_sel:DWORD src1_sel:WORD_1
	v_or_b32_sdwa v92, v96, v95 dst_sel:DWORD dst_unused:UNUSED_PAD src0_sel:DWORD src1_sel:WORD_1
	global_store_dwordx2 v[90:91], v[92:93], off offset:224
	v_and_b32_sdwa v93, v130, v177 dst_sel:DWORD dst_unused:UNUSED_PAD src0_sel:WORD_1 src1_sel:DWORD
	v_add3_u32 v95, v130, v93, s28
	v_and_b32_sdwa v93, v133, v177 dst_sel:DWORD dst_unused:UNUSED_PAD src0_sel:WORD_1 src1_sel:DWORD
	v_and_b32_sdwa v96, v131, v177 dst_sel:DWORD dst_unused:UNUSED_PAD src0_sel:WORD_1 src1_sel:DWORD
	v_or_b32_e32 v90, 16, v94
	v_and_b32_sdwa v92, v132, v177 dst_sel:DWORD dst_unused:UNUSED_PAD src0_sel:WORD_1 src1_sel:DWORD
	v_add3_u32 v93, v133, v93, s28
	v_add3_u32 v96, v131, v96, s28
	v_mad_i64_i32 v[90:91], s[6:7], v90, s8, v[86:87]
	v_add3_u32 v92, v132, v92, s28
	v_and_b32_e32 v93, 0xffff0000, v93
	v_and_b32_e32 v96, 0xffff0000, v96
	v_lshl_add_u64 v[90:91], v[90:91], 0, v[88:89]
	v_or_b32_sdwa v93, v93, v92 dst_sel:DWORD dst_unused:UNUSED_PAD src0_sel:DWORD src1_sel:WORD_1
	v_or_b32_sdwa v92, v96, v95 dst_sel:DWORD dst_unused:UNUSED_PAD src0_sel:DWORD src1_sel:WORD_1
	global_store_dwordx2 v[90:91], v[92:93], off
	v_and_b32_sdwa v93, v122, v177 dst_sel:DWORD dst_unused:UNUSED_PAD src0_sel:WORD_1 src1_sel:DWORD
	v_add3_u32 v95, v122, v93, s28
	v_and_b32_sdwa v93, v125, v177 dst_sel:DWORD dst_unused:UNUSED_PAD src0_sel:WORD_1 src1_sel:DWORD
	v_and_b32_sdwa v96, v123, v177 dst_sel:DWORD dst_unused:UNUSED_PAD src0_sel:WORD_1 src1_sel:DWORD
	v_and_b32_sdwa v92, v124, v177 dst_sel:DWORD dst_unused:UNUSED_PAD src0_sel:WORD_1 src1_sel:DWORD
	v_add3_u32 v93, v125, v93, s28
	v_add3_u32 v96, v123, v96, s28
	v_add3_u32 v92, v124, v92, s28
	v_and_b32_e32 v93, 0xffff0000, v93
	v_and_b32_e32 v96, 0xffff0000, v96
	v_or_b32_sdwa v93, v93, v92 dst_sel:DWORD dst_unused:UNUSED_PAD src0_sel:DWORD src1_sel:WORD_1
	v_or_b32_sdwa v92, v96, v95 dst_sel:DWORD dst_unused:UNUSED_PAD src0_sel:DWORD src1_sel:WORD_1
	global_store_dwordx2 v[90:91], v[92:93], off offset:32
	v_and_b32_sdwa v93, v114, v177 dst_sel:DWORD dst_unused:UNUSED_PAD src0_sel:WORD_1 src1_sel:DWORD
	v_add3_u32 v95, v114, v93, s28
	v_and_b32_sdwa v93, v117, v177 dst_sel:DWORD dst_unused:UNUSED_PAD src0_sel:WORD_1 src1_sel:DWORD
	v_and_b32_sdwa v96, v115, v177 dst_sel:DWORD dst_unused:UNUSED_PAD src0_sel:WORD_1 src1_sel:DWORD
	v_and_b32_sdwa v92, v116, v177 dst_sel:DWORD dst_unused:UNUSED_PAD src0_sel:WORD_1 src1_sel:DWORD
	v_add3_u32 v93, v117, v93, s28
	v_add3_u32 v96, v115, v96, s28
	v_add3_u32 v92, v116, v92, s28
	v_and_b32_e32 v93, 0xffff0000, v93
	v_and_b32_e32 v96, 0xffff0000, v96
	v_or_b32_sdwa v93, v93, v92 dst_sel:DWORD dst_unused:UNUSED_PAD src0_sel:DWORD src1_sel:WORD_1
	v_or_b32_sdwa v92, v96, v95 dst_sel:DWORD dst_unused:UNUSED_PAD src0_sel:DWORD src1_sel:WORD_1
	global_store_dwordx2 v[90:91], v[92:93], off offset:64
	v_and_b32_sdwa v92, v84, v177 dst_sel:DWORD dst_unused:UNUSED_PAD src0_sel:WORD_1 src1_sel:DWORD
	v_and_b32_sdwa v93, v82, v177 dst_sel:DWORD dst_unused:UNUSED_PAD src0_sel:WORD_1 src1_sel:DWORD
	v_add3_u32 v82, v82, v93, s28
	v_add3_u32 v84, v84, v92, s28
	v_and_b32_sdwa v92, v85, v177 dst_sel:DWORD dst_unused:UNUSED_PAD src0_sel:WORD_1 src1_sel:DWORD
	v_and_b32_sdwa v93, v83, v177 dst_sel:DWORD dst_unused:UNUSED_PAD src0_sel:WORD_1 src1_sel:DWORD
	v_add3_u32 v85, v85, v92, s28
	v_add3_u32 v83, v83, v93, s28
	v_and_b32_e32 v85, 0xffff0000, v85
	v_and_b32_e32 v92, 0xffff0000, v83
	v_or_b32_sdwa v83, v85, v84 dst_sel:DWORD dst_unused:UNUSED_PAD src0_sel:DWORD src1_sel:WORD_1
	v_or_b32_sdwa v82, v92, v82 dst_sel:DWORD dst_unused:UNUSED_PAD src0_sel:DWORD src1_sel:WORD_1
	global_store_dwordx2 v[90:91], v[82:83], off offset:96
	v_and_b32_sdwa v82, v80, v177 dst_sel:DWORD dst_unused:UNUSED_PAD src0_sel:WORD_1 src1_sel:DWORD
	v_and_b32_sdwa v83, v78, v177 dst_sel:DWORD dst_unused:UNUSED_PAD src0_sel:WORD_1 src1_sel:DWORD
	v_add3_u32 v78, v78, v83, s28
	v_add3_u32 v80, v80, v82, s28
	v_and_b32_sdwa v82, v81, v177 dst_sel:DWORD dst_unused:UNUSED_PAD src0_sel:WORD_1 src1_sel:DWORD
	v_and_b32_sdwa v83, v79, v177 dst_sel:DWORD dst_unused:UNUSED_PAD src0_sel:WORD_1 src1_sel:DWORD
	v_add3_u32 v81, v81, v82, s28
	v_add3_u32 v79, v79, v83, s28
	v_and_b32_e32 v81, 0xffff0000, v81
	v_and_b32_e32 v82, 0xffff0000, v79
	v_or_b32_sdwa v79, v81, v80 dst_sel:DWORD dst_unused:UNUSED_PAD src0_sel:DWORD src1_sel:WORD_1
	v_or_b32_sdwa v78, v82, v78 dst_sel:DWORD dst_unused:UNUSED_PAD src0_sel:DWORD src1_sel:WORD_1
	global_store_dwordx2 v[90:91], v[78:79], off offset:128
	v_and_b32_sdwa v78, v76, v177 dst_sel:DWORD dst_unused:UNUSED_PAD src0_sel:WORD_1 src1_sel:DWORD
	v_and_b32_sdwa v79, v74, v177 dst_sel:DWORD dst_unused:UNUSED_PAD src0_sel:WORD_1 src1_sel:DWORD
	v_add3_u32 v74, v74, v79, s28
	v_add3_u32 v76, v76, v78, s28
	v_and_b32_sdwa v78, v77, v177 dst_sel:DWORD dst_unused:UNUSED_PAD src0_sel:WORD_1 src1_sel:DWORD
	v_and_b32_sdwa v79, v75, v177 dst_sel:DWORD dst_unused:UNUSED_PAD src0_sel:WORD_1 src1_sel:DWORD
	v_add3_u32 v77, v77, v78, s28
	v_add3_u32 v75, v75, v79, s28
	v_and_b32_e32 v77, 0xffff0000, v77
	v_and_b32_e32 v78, 0xffff0000, v75
	v_or_b32_sdwa v75, v77, v76 dst_sel:DWORD dst_unused:UNUSED_PAD src0_sel:DWORD src1_sel:WORD_1
	v_or_b32_sdwa v74, v78, v74 dst_sel:DWORD dst_unused:UNUSED_PAD src0_sel:DWORD src1_sel:WORD_1
	global_store_dwordx2 v[90:91], v[74:75], off offset:160
	v_and_b32_sdwa v74, v72, v177 dst_sel:DWORD dst_unused:UNUSED_PAD src0_sel:WORD_1 src1_sel:DWORD
	v_and_b32_sdwa v75, v70, v177 dst_sel:DWORD dst_unused:UNUSED_PAD src0_sel:WORD_1 src1_sel:DWORD
	v_add3_u32 v70, v70, v75, s28
	v_add3_u32 v72, v72, v74, s28
	v_and_b32_sdwa v74, v73, v177 dst_sel:DWORD dst_unused:UNUSED_PAD src0_sel:WORD_1 src1_sel:DWORD
	v_and_b32_sdwa v75, v71, v177 dst_sel:DWORD dst_unused:UNUSED_PAD src0_sel:WORD_1 src1_sel:DWORD
	v_add3_u32 v73, v73, v74, s28
	v_add3_u32 v71, v71, v75, s28
	v_and_b32_e32 v73, 0xffff0000, v73
	v_and_b32_e32 v74, 0xffff0000, v71
	v_or_b32_sdwa v71, v73, v72 dst_sel:DWORD dst_unused:UNUSED_PAD src0_sel:DWORD src1_sel:WORD_1
	v_or_b32_sdwa v70, v74, v70 dst_sel:DWORD dst_unused:UNUSED_PAD src0_sel:DWORD src1_sel:WORD_1
	global_store_dwordx2 v[90:91], v[70:71], off offset:192
	v_and_b32_sdwa v70, v64, v177 dst_sel:DWORD dst_unused:UNUSED_PAD src0_sel:WORD_1 src1_sel:DWORD
	v_and_b32_sdwa v71, v62, v177 dst_sel:DWORD dst_unused:UNUSED_PAD src0_sel:WORD_1 src1_sel:DWORD
	v_add3_u32 v64, v64, v70, s28
	v_and_b32_sdwa v70, v65, v177 dst_sel:DWORD dst_unused:UNUSED_PAD src0_sel:WORD_1 src1_sel:DWORD
	v_add3_u32 v62, v62, v71, s28
	v_and_b32_sdwa v71, v63, v177 dst_sel:DWORD dst_unused:UNUSED_PAD src0_sel:WORD_1 src1_sel:DWORD
	v_add3_u32 v65, v65, v70, s28
	v_add3_u32 v63, v63, v71, s28
	v_and_b32_e32 v65, 0xffff0000, v65
	v_and_b32_e32 v70, 0xffff0000, v63
	v_or_b32_sdwa v63, v65, v64 dst_sel:DWORD dst_unused:UNUSED_PAD src0_sel:DWORD src1_sel:WORD_1
	v_and_b32_sdwa v64, v68, v177 dst_sel:DWORD dst_unused:UNUSED_PAD src0_sel:WORD_1 src1_sel:DWORD
	v_and_b32_sdwa v65, v66, v177 dst_sel:DWORD dst_unused:UNUSED_PAD src0_sel:WORD_1 src1_sel:DWORD
	v_or_b32_sdwa v62, v70, v62 dst_sel:DWORD dst_unused:UNUSED_PAD src0_sel:DWORD src1_sel:WORD_1
	v_add3_u32 v66, v66, v65, s28
	v_add3_u32 v64, v68, v64, s28
	v_and_b32_sdwa v65, v69, v177 dst_sel:DWORD dst_unused:UNUSED_PAD src0_sel:WORD_1 src1_sel:DWORD
	v_and_b32_sdwa v68, v67, v177 dst_sel:DWORD dst_unused:UNUSED_PAD src0_sel:WORD_1 src1_sel:DWORD
	global_store_dwordx2 v[90:91], v[62:63], off offset:224
	v_or_b32_e32 v62, 32, v94
	v_add3_u32 v65, v69, v65, s28
	v_add3_u32 v67, v67, v68, s28
	v_mad_i64_i32 v[62:63], s[6:7], v62, s8, v[86:87]
	v_and_b32_e32 v65, 0xffff0000, v65
	v_and_b32_e32 v67, 0xffff0000, v67
	v_lshl_add_u64 v[62:63], v[62:63], 0, v[88:89]
	v_or_b32_sdwa v65, v65, v64 dst_sel:DWORD dst_unused:UNUSED_PAD src0_sel:DWORD src1_sel:WORD_1
	v_or_b32_sdwa v64, v67, v66 dst_sel:DWORD dst_unused:UNUSED_PAD src0_sel:DWORD src1_sel:WORD_1
	global_store_dwordx2 v[62:63], v[64:65], off
	v_and_b32_sdwa v64, v60, v177 dst_sel:DWORD dst_unused:UNUSED_PAD src0_sel:WORD_1 src1_sel:DWORD
	v_and_b32_sdwa v65, v58, v177 dst_sel:DWORD dst_unused:UNUSED_PAD src0_sel:WORD_1 src1_sel:DWORD
	v_add3_u32 v58, v58, v65, s28
	v_add3_u32 v60, v60, v64, s28
	v_and_b32_sdwa v64, v61, v177 dst_sel:DWORD dst_unused:UNUSED_PAD src0_sel:WORD_1 src1_sel:DWORD
	v_and_b32_sdwa v65, v59, v177 dst_sel:DWORD dst_unused:UNUSED_PAD src0_sel:WORD_1 src1_sel:DWORD
	v_add3_u32 v61, v61, v64, s28
	v_add3_u32 v59, v59, v65, s28
	v_and_b32_e32 v61, 0xffff0000, v61
	v_and_b32_e32 v64, 0xffff0000, v59
	v_or_b32_sdwa v59, v61, v60 dst_sel:DWORD dst_unused:UNUSED_PAD src0_sel:DWORD src1_sel:WORD_1
	v_or_b32_sdwa v58, v64, v58 dst_sel:DWORD dst_unused:UNUSED_PAD src0_sel:DWORD src1_sel:WORD_1
	global_store_dwordx2 v[62:63], v[58:59], off offset:32
	v_and_b32_sdwa v58, v56, v177 dst_sel:DWORD dst_unused:UNUSED_PAD src0_sel:WORD_1 src1_sel:DWORD
	v_and_b32_sdwa v59, v54, v177 dst_sel:DWORD dst_unused:UNUSED_PAD src0_sel:WORD_1 src1_sel:DWORD
	v_add3_u32 v54, v54, v59, s28
	v_add3_u32 v56, v56, v58, s28
	v_and_b32_sdwa v58, v57, v177 dst_sel:DWORD dst_unused:UNUSED_PAD src0_sel:WORD_1 src1_sel:DWORD
	v_and_b32_sdwa v59, v55, v177 dst_sel:DWORD dst_unused:UNUSED_PAD src0_sel:WORD_1 src1_sel:DWORD
	v_add3_u32 v57, v57, v58, s28
	v_add3_u32 v55, v55, v59, s28
	v_and_b32_e32 v57, 0xffff0000, v57
	v_and_b32_e32 v58, 0xffff0000, v55
	v_or_b32_sdwa v55, v57, v56 dst_sel:DWORD dst_unused:UNUSED_PAD src0_sel:DWORD src1_sel:WORD_1
	v_or_b32_sdwa v54, v58, v54 dst_sel:DWORD dst_unused:UNUSED_PAD src0_sel:DWORD src1_sel:WORD_1
	global_store_dwordx2 v[62:63], v[54:55], off offset:64
	v_and_b32_sdwa v54, v52, v177 dst_sel:DWORD dst_unused:UNUSED_PAD src0_sel:WORD_1 src1_sel:DWORD
	v_and_b32_sdwa v55, v50, v177 dst_sel:DWORD dst_unused:UNUSED_PAD src0_sel:WORD_1 src1_sel:DWORD
	v_add3_u32 v50, v50, v55, s28
	v_add3_u32 v52, v52, v54, s28
	v_and_b32_sdwa v54, v53, v177 dst_sel:DWORD dst_unused:UNUSED_PAD src0_sel:WORD_1 src1_sel:DWORD
	v_and_b32_sdwa v55, v51, v177 dst_sel:DWORD dst_unused:UNUSED_PAD src0_sel:WORD_1 src1_sel:DWORD
	v_add3_u32 v53, v53, v54, s28
	v_add3_u32 v51, v51, v55, s28
	v_and_b32_e32 v53, 0xffff0000, v53
	v_and_b32_e32 v54, 0xffff0000, v51
	v_or_b32_sdwa v51, v53, v52 dst_sel:DWORD dst_unused:UNUSED_PAD src0_sel:DWORD src1_sel:WORD_1
	v_or_b32_sdwa v50, v54, v50 dst_sel:DWORD dst_unused:UNUSED_PAD src0_sel:DWORD src1_sel:WORD_1
	global_store_dwordx2 v[62:63], v[50:51], off offset:96
	v_and_b32_sdwa v50, v48, v177 dst_sel:DWORD dst_unused:UNUSED_PAD src0_sel:WORD_1 src1_sel:DWORD
	v_and_b32_sdwa v51, v46, v177 dst_sel:DWORD dst_unused:UNUSED_PAD src0_sel:WORD_1 src1_sel:DWORD
	v_add3_u32 v46, v46, v51, s28
	v_add3_u32 v48, v48, v50, s28
	v_and_b32_sdwa v50, v49, v177 dst_sel:DWORD dst_unused:UNUSED_PAD src0_sel:WORD_1 src1_sel:DWORD
	v_and_b32_sdwa v51, v47, v177 dst_sel:DWORD dst_unused:UNUSED_PAD src0_sel:WORD_1 src1_sel:DWORD
	v_add3_u32 v49, v49, v50, s28
	v_add3_u32 v47, v47, v51, s28
	v_and_b32_e32 v49, 0xffff0000, v49
	v_and_b32_e32 v50, 0xffff0000, v47
	v_or_b32_sdwa v47, v49, v48 dst_sel:DWORD dst_unused:UNUSED_PAD src0_sel:DWORD src1_sel:WORD_1
	v_or_b32_sdwa v46, v50, v46 dst_sel:DWORD dst_unused:UNUSED_PAD src0_sel:DWORD src1_sel:WORD_1
	global_store_dwordx2 v[62:63], v[46:47], off offset:128
	v_and_b32_sdwa v46, v44, v177 dst_sel:DWORD dst_unused:UNUSED_PAD src0_sel:WORD_1 src1_sel:DWORD
	v_and_b32_sdwa v47, v42, v177 dst_sel:DWORD dst_unused:UNUSED_PAD src0_sel:WORD_1 src1_sel:DWORD
	v_add3_u32 v42, v42, v47, s28
	v_add3_u32 v44, v44, v46, s28
	v_and_b32_sdwa v46, v45, v177 dst_sel:DWORD dst_unused:UNUSED_PAD src0_sel:WORD_1 src1_sel:DWORD
	v_and_b32_sdwa v47, v43, v177 dst_sel:DWORD dst_unused:UNUSED_PAD src0_sel:WORD_1 src1_sel:DWORD
	v_add3_u32 v45, v45, v46, s28
	v_add3_u32 v43, v43, v47, s28
	v_and_b32_e32 v45, 0xffff0000, v45
	v_and_b32_e32 v46, 0xffff0000, v43
	v_or_b32_sdwa v43, v45, v44 dst_sel:DWORD dst_unused:UNUSED_PAD src0_sel:DWORD src1_sel:WORD_1
	v_or_b32_sdwa v42, v46, v42 dst_sel:DWORD dst_unused:UNUSED_PAD src0_sel:DWORD src1_sel:WORD_1
	global_store_dwordx2 v[62:63], v[42:43], off offset:160
	v_and_b32_sdwa v42, v40, v177 dst_sel:DWORD dst_unused:UNUSED_PAD src0_sel:WORD_1 src1_sel:DWORD
	v_and_b32_sdwa v43, v38, v177 dst_sel:DWORD dst_unused:UNUSED_PAD src0_sel:WORD_1 src1_sel:DWORD
	v_add3_u32 v38, v38, v43, s28
	v_add3_u32 v40, v40, v42, s28
	v_and_b32_sdwa v42, v41, v177 dst_sel:DWORD dst_unused:UNUSED_PAD src0_sel:WORD_1 src1_sel:DWORD
	v_and_b32_sdwa v43, v39, v177 dst_sel:DWORD dst_unused:UNUSED_PAD src0_sel:WORD_1 src1_sel:DWORD
	v_add3_u32 v41, v41, v42, s28
	v_add3_u32 v39, v39, v43, s28
	v_and_b32_e32 v41, 0xffff0000, v41
	v_and_b32_e32 v42, 0xffff0000, v39
	v_or_b32_sdwa v39, v41, v40 dst_sel:DWORD dst_unused:UNUSED_PAD src0_sel:DWORD src1_sel:WORD_1
	v_or_b32_sdwa v38, v42, v38 dst_sel:DWORD dst_unused:UNUSED_PAD src0_sel:DWORD src1_sel:WORD_1
	global_store_dwordx2 v[62:63], v[38:39], off offset:192
	v_and_b32_sdwa v38, v32, v177 dst_sel:DWORD dst_unused:UNUSED_PAD src0_sel:WORD_1 src1_sel:DWORD
	v_and_b32_sdwa v39, v30, v177 dst_sel:DWORD dst_unused:UNUSED_PAD src0_sel:WORD_1 src1_sel:DWORD
	v_add3_u32 v32, v32, v38, s28
	v_and_b32_sdwa v38, v33, v177 dst_sel:DWORD dst_unused:UNUSED_PAD src0_sel:WORD_1 src1_sel:DWORD
	v_add3_u32 v30, v30, v39, s28
	v_and_b32_sdwa v39, v31, v177 dst_sel:DWORD dst_unused:UNUSED_PAD src0_sel:WORD_1 src1_sel:DWORD
	v_add3_u32 v33, v33, v38, s28
	v_add3_u32 v31, v31, v39, s28
	v_and_b32_e32 v33, 0xffff0000, v33
	v_and_b32_e32 v38, 0xffff0000, v31
	v_or_b32_sdwa v31, v33, v32 dst_sel:DWORD dst_unused:UNUSED_PAD src0_sel:DWORD src1_sel:WORD_1
	v_and_b32_sdwa v32, v36, v177 dst_sel:DWORD dst_unused:UNUSED_PAD src0_sel:WORD_1 src1_sel:DWORD
	v_and_b32_sdwa v33, v34, v177 dst_sel:DWORD dst_unused:UNUSED_PAD src0_sel:WORD_1 src1_sel:DWORD
	v_or_b32_sdwa v30, v38, v30 dst_sel:DWORD dst_unused:UNUSED_PAD src0_sel:DWORD src1_sel:WORD_1
	v_add3_u32 v34, v34, v33, s28
	v_add3_u32 v32, v36, v32, s28
	v_and_b32_sdwa v33, v37, v177 dst_sel:DWORD dst_unused:UNUSED_PAD src0_sel:WORD_1 src1_sel:DWORD
	v_and_b32_sdwa v36, v35, v177 dst_sel:DWORD dst_unused:UNUSED_PAD src0_sel:WORD_1 src1_sel:DWORD
	global_store_dwordx2 v[62:63], v[30:31], off offset:224
	v_or_b32_e32 v30, 48, v94
	v_add3_u32 v33, v37, v33, s28
	v_add3_u32 v35, v35, v36, s28
	v_mad_i64_i32 v[30:31], s[6:7], v30, s8, v[86:87]
	v_and_b32_e32 v33, 0xffff0000, v33
	v_and_b32_e32 v35, 0xffff0000, v35
	v_lshl_add_u64 v[30:31], v[30:31], 0, v[88:89]
	v_or_b32_sdwa v33, v33, v32 dst_sel:DWORD dst_unused:UNUSED_PAD src0_sel:DWORD src1_sel:WORD_1
	v_or_b32_sdwa v32, v35, v34 dst_sel:DWORD dst_unused:UNUSED_PAD src0_sel:DWORD src1_sel:WORD_1
	global_store_dwordx2 v[30:31], v[32:33], off
	v_and_b32_sdwa v32, v28, v177 dst_sel:DWORD dst_unused:UNUSED_PAD src0_sel:WORD_1 src1_sel:DWORD
	v_and_b32_sdwa v33, v26, v177 dst_sel:DWORD dst_unused:UNUSED_PAD src0_sel:WORD_1 src1_sel:DWORD
	v_add3_u32 v26, v26, v33, s28
	v_add3_u32 v28, v28, v32, s28
	v_and_b32_sdwa v32, v29, v177 dst_sel:DWORD dst_unused:UNUSED_PAD src0_sel:WORD_1 src1_sel:DWORD
	v_and_b32_sdwa v33, v27, v177 dst_sel:DWORD dst_unused:UNUSED_PAD src0_sel:WORD_1 src1_sel:DWORD
	v_add3_u32 v29, v29, v32, s28
	v_add3_u32 v27, v27, v33, s28
	v_and_b32_e32 v29, 0xffff0000, v29
	v_and_b32_e32 v32, 0xffff0000, v27
	v_or_b32_sdwa v27, v29, v28 dst_sel:DWORD dst_unused:UNUSED_PAD src0_sel:DWORD src1_sel:WORD_1
	v_or_b32_sdwa v26, v32, v26 dst_sel:DWORD dst_unused:UNUSED_PAD src0_sel:DWORD src1_sel:WORD_1
	global_store_dwordx2 v[30:31], v[26:27], off offset:32
	v_and_b32_sdwa v26, v24, v177 dst_sel:DWORD dst_unused:UNUSED_PAD src0_sel:WORD_1 src1_sel:DWORD
	v_and_b32_sdwa v27, v22, v177 dst_sel:DWORD dst_unused:UNUSED_PAD src0_sel:WORD_1 src1_sel:DWORD
	v_add3_u32 v22, v22, v27, s28
	v_add3_u32 v24, v24, v26, s28
	v_and_b32_sdwa v26, v25, v177 dst_sel:DWORD dst_unused:UNUSED_PAD src0_sel:WORD_1 src1_sel:DWORD
	v_and_b32_sdwa v27, v23, v177 dst_sel:DWORD dst_unused:UNUSED_PAD src0_sel:WORD_1 src1_sel:DWORD
	v_add3_u32 v25, v25, v26, s28
	v_add3_u32 v23, v23, v27, s28
	v_and_b32_e32 v25, 0xffff0000, v25
	v_and_b32_e32 v26, 0xffff0000, v23
	v_or_b32_sdwa v23, v25, v24 dst_sel:DWORD dst_unused:UNUSED_PAD src0_sel:DWORD src1_sel:WORD_1
	v_or_b32_sdwa v22, v26, v22 dst_sel:DWORD dst_unused:UNUSED_PAD src0_sel:DWORD src1_sel:WORD_1
	global_store_dwordx2 v[30:31], v[22:23], off offset:64
	v_and_b32_sdwa v22, v20, v177 dst_sel:DWORD dst_unused:UNUSED_PAD src0_sel:WORD_1 src1_sel:DWORD
	v_and_b32_sdwa v23, v18, v177 dst_sel:DWORD dst_unused:UNUSED_PAD src0_sel:WORD_1 src1_sel:DWORD
	v_add3_u32 v18, v18, v23, s28
	v_add3_u32 v20, v20, v22, s28
	v_and_b32_sdwa v22, v21, v177 dst_sel:DWORD dst_unused:UNUSED_PAD src0_sel:WORD_1 src1_sel:DWORD
	v_and_b32_sdwa v23, v19, v177 dst_sel:DWORD dst_unused:UNUSED_PAD src0_sel:WORD_1 src1_sel:DWORD
	v_add3_u32 v21, v21, v22, s28
	v_add3_u32 v19, v19, v23, s28
	v_and_b32_e32 v21, 0xffff0000, v21
	v_and_b32_e32 v22, 0xffff0000, v19
	v_or_b32_sdwa v19, v21, v20 dst_sel:DWORD dst_unused:UNUSED_PAD src0_sel:DWORD src1_sel:WORD_1
	v_or_b32_sdwa v18, v22, v18 dst_sel:DWORD dst_unused:UNUSED_PAD src0_sel:DWORD src1_sel:WORD_1
	global_store_dwordx2 v[30:31], v[18:19], off offset:96
	v_and_b32_sdwa v18, v16, v177 dst_sel:DWORD dst_unused:UNUSED_PAD src0_sel:WORD_1 src1_sel:DWORD
	v_and_b32_sdwa v19, v14, v177 dst_sel:DWORD dst_unused:UNUSED_PAD src0_sel:WORD_1 src1_sel:DWORD
	v_add3_u32 v14, v14, v19, s28
	v_add3_u32 v16, v16, v18, s28
	v_and_b32_sdwa v18, v17, v177 dst_sel:DWORD dst_unused:UNUSED_PAD src0_sel:WORD_1 src1_sel:DWORD
	v_and_b32_sdwa v19, v15, v177 dst_sel:DWORD dst_unused:UNUSED_PAD src0_sel:WORD_1 src1_sel:DWORD
	v_add3_u32 v17, v17, v18, s28
	v_add3_u32 v15, v15, v19, s28
	v_and_b32_e32 v17, 0xffff0000, v17
	v_and_b32_e32 v18, 0xffff0000, v15
	v_or_b32_sdwa v15, v17, v16 dst_sel:DWORD dst_unused:UNUSED_PAD src0_sel:DWORD src1_sel:WORD_1
	v_or_b32_sdwa v14, v18, v14 dst_sel:DWORD dst_unused:UNUSED_PAD src0_sel:DWORD src1_sel:WORD_1
	global_store_dwordx2 v[30:31], v[14:15], off offset:128
	v_and_b32_sdwa v14, v12, v177 dst_sel:DWORD dst_unused:UNUSED_PAD src0_sel:WORD_1 src1_sel:DWORD
	v_and_b32_sdwa v15, v10, v177 dst_sel:DWORD dst_unused:UNUSED_PAD src0_sel:WORD_1 src1_sel:DWORD
	v_add3_u32 v10, v10, v15, s28
	v_add3_u32 v12, v12, v14, s28
	v_and_b32_sdwa v14, v13, v177 dst_sel:DWORD dst_unused:UNUSED_PAD src0_sel:WORD_1 src1_sel:DWORD
	v_and_b32_sdwa v15, v11, v177 dst_sel:DWORD dst_unused:UNUSED_PAD src0_sel:WORD_1 src1_sel:DWORD
	v_add3_u32 v13, v13, v14, s28
	v_add3_u32 v11, v11, v15, s28
	v_and_b32_e32 v13, 0xffff0000, v13
	v_and_b32_e32 v14, 0xffff0000, v11
	v_or_b32_sdwa v11, v13, v12 dst_sel:DWORD dst_unused:UNUSED_PAD src0_sel:DWORD src1_sel:WORD_1
	v_or_b32_sdwa v10, v14, v10 dst_sel:DWORD dst_unused:UNUSED_PAD src0_sel:DWORD src1_sel:WORD_1
	global_store_dwordx2 v[30:31], v[10:11], off offset:160
	v_and_b32_sdwa v10, v8, v177 dst_sel:DWORD dst_unused:UNUSED_PAD src0_sel:WORD_1 src1_sel:DWORD
	v_and_b32_sdwa v11, v6, v177 dst_sel:DWORD dst_unused:UNUSED_PAD src0_sel:WORD_1 src1_sel:DWORD
	v_add3_u32 v6, v6, v11, s28
	v_add3_u32 v8, v8, v10, s28
	v_and_b32_sdwa v10, v9, v177 dst_sel:DWORD dst_unused:UNUSED_PAD src0_sel:WORD_1 src1_sel:DWORD
	v_and_b32_sdwa v11, v7, v177 dst_sel:DWORD dst_unused:UNUSED_PAD src0_sel:WORD_1 src1_sel:DWORD
	v_add3_u32 v9, v9, v10, s28
	v_add3_u32 v7, v7, v11, s28
	v_and_b32_e32 v9, 0xffff0000, v9
	v_and_b32_e32 v10, 0xffff0000, v7
	v_or_b32_sdwa v7, v9, v8 dst_sel:DWORD dst_unused:UNUSED_PAD src0_sel:DWORD src1_sel:WORD_1
	v_or_b32_sdwa v6, v10, v6 dst_sel:DWORD dst_unused:UNUSED_PAD src0_sel:DWORD src1_sel:WORD_1
	global_store_dwordx2 v[30:31], v[6:7], off offset:192
	v_and_b32_sdwa v6, v4, v177 dst_sel:DWORD dst_unused:UNUSED_PAD src0_sel:WORD_1 src1_sel:DWORD
	v_and_b32_sdwa v7, v2, v177 dst_sel:DWORD dst_unused:UNUSED_PAD src0_sel:WORD_1 src1_sel:DWORD
	v_add3_u32 v2, v2, v7, s28
	v_add3_u32 v4, v4, v6, s28
	v_and_b32_sdwa v6, v5, v177 dst_sel:DWORD dst_unused:UNUSED_PAD src0_sel:WORD_1 src1_sel:DWORD
	v_and_b32_sdwa v7, v3, v177 dst_sel:DWORD dst_unused:UNUSED_PAD src0_sel:WORD_1 src1_sel:DWORD
	v_add3_u32 v5, v5, v6, s28
	v_add3_u32 v3, v3, v7, s28
	v_and_b32_e32 v5, 0xffff0000, v5
	v_and_b32_e32 v6, 0xffff0000, v3
	s_add_i32 s11, s11, s10
	v_or_b32_sdwa v3, v5, v4 dst_sel:DWORD dst_unused:UNUSED_PAD src0_sel:DWORD src1_sel:WORD_1
	v_or_b32_sdwa v2, v6, v2 dst_sel:DWORD dst_unused:UNUSED_PAD src0_sel:DWORD src1_sel:WORD_1
	s_cmpk_gt_i32 s11, 0x3ef
	global_store_dwordx2 v[30:31], v[2:3], off offset:224
	s_cbranch_scc0 .LBB0_664

.LBB0_1308:
	s_bitcmp1_b32 s4, 0
	s_cselect_b32 s2, 0x12000, 0
	v_or_b32_e32 v218, s2, v207
	v_add_u32_e32 v214, v218, v0
	v_add_u32_e32 v246, v218, v167
	ds_read_b128 v[184:187], v214
	ds_read_b128 v[198:201], v214 offset:2048
	ds_read_b128 v[210:213], v214 offset:4096
	ds_read_b128 v[214:217], v214 offset:6144
	ds_read_b128 v[218:221], v246 offset:32768
	ds_read_b128 v[222:225], v246 offset:34816
	ds_read_b128 v[226:229], v246 offset:36864
	ds_read_b128 v[230:233], v246 offset:38912
	ds_read_b128 v[234:237], v246 offset:40960
	ds_read_b128 v[238:241], v246 offset:43008
	ds_read_b128 v[242:245], v246 offset:45056
	ds_read_b128 v[246:249], v246 offset:47104
	s_add_i32 s10, s4, 1
	s_bitcmp1_b32 s10, 0
	s_cselect_b32 s3, 0x12000, 0
	v_add_u32_e32 v171, s3, v166
	v_xor_b32_e32 v169, 64, v207
	v_add3_u32 v169, s2, v167, v169
	s_waitcnt lgkmcnt(7)
	v_mfma_f32_16x16x32_bf16 v[158:161], v[218:221], v[184:187], v[158:161]
	v_mfma_f32_16x16x32_bf16 v[98:101], v[218:221], v[198:201], v[98:101]
	v_mfma_f32_16x16x32_bf16 v[66:69], v[218:221], v[210:213], v[66:69]
	v_mfma_f32_16x16x32_bf16 v[34:37], v[218:221], v[214:217], v[34:37]
	ds_read_b128 v[218:221], v169 offset:32768
	s_waitcnt lgkmcnt(7)
	v_mfma_f32_16x16x32_bf16 v[154:157], v[222:225], v[184:187], v[154:157]
	v_mfma_f32_16x16x32_bf16 v[90:93], v[222:225], v[198:201], v[90:93]
	v_mfma_f32_16x16x32_bf16 v[58:61], v[222:225], v[210:213], v[58:61]
	v_mfma_f32_16x16x32_bf16 v[26:29], v[222:225], v[214:217], v[26:29]
	ds_read_b128 v[222:225], v169 offset:34816
	s_waitcnt lgkmcnt(7)
	v_mfma_f32_16x16x32_bf16 v[150:153], v[226:229], v[184:187], v[150:153]
	v_mfma_f32_16x16x32_bf16 v[86:89], v[226:229], v[198:201], v[86:89]
	v_mfma_f32_16x16x32_bf16 v[54:57], v[226:229], v[210:213], v[54:57]
	v_mfma_f32_16x16x32_bf16 v[22:25], v[226:229], v[214:217], v[22:25]
	ds_read_b128 v[226:229], v169 offset:36864
	s_waitcnt lgkmcnt(7)
	v_mfma_f32_16x16x32_bf16 v[146:149], v[230:233], v[184:187], v[146:149]
	v_mfma_f32_16x16x32_bf16 v[82:85], v[230:233], v[198:201], v[82:85]
	v_mfma_f32_16x16x32_bf16 v[50:53], v[230:233], v[210:213], v[50:53]
	v_mfma_f32_16x16x32_bf16 v[18:21], v[230:233], v[214:217], v[18:21]
	ds_read_b128 v[230:233], v169 offset:38912
	s_waitcnt lgkmcnt(7)
	v_mfma_f32_16x16x32_bf16 v[142:145], v[234:237], v[184:187], v[142:145]
	v_mfma_f32_16x16x32_bf16 v[78:81], v[234:237], v[198:201], v[78:81]
	v_mfma_f32_16x16x32_bf16 v[46:49], v[234:237], v[210:213], v[46:49]
	v_mfma_f32_16x16x32_bf16 v[14:17], v[234:237], v[214:217], v[14:17]
	ds_read_b128 v[234:237], v169 offset:40960
	s_waitcnt lgkmcnt(7)
	v_mfma_f32_16x16x32_bf16 v[106:109], v[238:241], v[184:187], v[106:109]
	v_mfma_f32_16x16x32_bf16 v[74:77], v[238:241], v[198:201], v[74:77]
	v_mfma_f32_16x16x32_bf16 v[42:45], v[238:241], v[210:213], v[42:45]
	v_mfma_f32_16x16x32_bf16 v[10:13], v[238:241], v[214:217], v[10:13]
	ds_read_b128 v[238:241], v169 offset:43008
	s_waitcnt lgkmcnt(7)
	v_mfma_f32_16x16x32_bf16 v[102:105], v[242:245], v[184:187], v[102:105]
	v_mfma_f32_16x16x32_bf16 v[70:73], v[242:245], v[198:201], v[70:73]
	v_mfma_f32_16x16x32_bf16 v[38:41], v[242:245], v[210:213], v[38:41]
	v_mfma_f32_16x16x32_bf16 v[6:9], v[242:245], v[214:217], v[6:9]
	ds_read_b128 v[242:245], v169 offset:45056
	s_waitcnt lgkmcnt(7)
	v_mfma_f32_16x16x32_bf16 v[94:97], v[246:249], v[184:187], v[94:97]
	v_mfma_f32_16x16x32_bf16 v[62:65], v[246:249], v[198:201], v[62:65]
	v_xor_b32_e32 v169, 64, v207
	v_add3_u32 v169, s2, v0, v169
	ds_read_b128 v[184:187], v169
	ds_read_b128 v[198:201], v169 offset:2048
	v_mfma_f32_16x16x32_bf16 v[30:33], v[246:249], v[210:213], v[30:33]
	ds_read_b128 v[210:213], v169 offset:4096
	v_mfma_f32_16x16x32_bf16 v[2:5], v[246:249], v[214:217], v[2:5]
	ds_read_b128 v[214:217], v169 offset:6144
	v_xor_b32_e32 v169, 64, v207
	v_add3_u32 v169, s2, v167, v169
	ds_read_b128 v[246:249], v169 offset:47104
	s_waitcnt lgkmcnt(1)
	v_mfma_f32_16x16x32_bf16 v[158:161], v[218:221], v[184:187], v[158:161]
	v_mfma_f32_16x16x32_bf16 v[98:101], v[218:221], v[198:201], v[98:101]
	v_mfma_f32_16x16x32_bf16 v[66:69], v[218:221], v[210:213], v[66:69]
	v_mfma_f32_16x16x32_bf16 v[34:37], v[218:221], v[214:217], v[34:37]
	s_waitcnt vmcnt(7)
	ds_write_b128 v171, v[118:121]
	v_mfma_f32_16x16x32_bf16 v[154:157], v[222:225], v[184:187], v[154:157]
	v_mfma_f32_16x16x32_bf16 v[90:93], v[222:225], v[198:201], v[90:93]
	global_load_dwordx4 v[118:121], v168, vcc offset:256
	v_mfma_f32_16x16x32_bf16 v[58:61], v[222:225], v[210:213], v[58:61]
	v_mfma_f32_16x16x32_bf16 v[26:29], v[222:225], v[214:217], v[26:29]
	s_waitcnt vmcnt(7)
	ds_write_b128 v171, v[110:113] offset:8192
	v_mfma_f32_16x16x32_bf16 v[150:153], v[226:229], v[184:187], v[150:153]
	v_mfma_f32_16x16x32_bf16 v[86:89], v[226:229], v[198:201], v[86:89]
	v_add_u32_e32 v110, s34, v168
	global_load_dwordx4 v[110:113], v110, vcc offset:256
	v_mfma_f32_16x16x32_bf16 v[54:57], v[226:229], v[210:213], v[54:57]
	v_mfma_f32_16x16x32_bf16 v[22:25], v[226:229], v[214:217], v[22:25]
	s_waitcnt vmcnt(7)
	ds_write_b128 v171, v[114:117] offset:16384
	v_mfma_f32_16x16x32_bf16 v[146:149], v[230:233], v[184:187], v[146:149]
	v_mfma_f32_16x16x32_bf16 v[82:85], v[230:233], v[198:201], v[82:85]
	v_add_u32_e32 v114, s35, v168
	global_load_dwordx4 v[114:117], v114, vcc offset:256
	v_mfma_f32_16x16x32_bf16 v[50:53], v[230:233], v[210:213], v[50:53]
	v_mfma_f32_16x16x32_bf16 v[18:21], v[230:233], v[214:217], v[18:21]
	s_waitcnt vmcnt(7)
	ds_write_b128 v171, v[130:133] offset:24576
	v_mfma_f32_16x16x32_bf16 v[142:145], v[234:237], v[184:187], v[142:145]
	v_mfma_f32_16x16x32_bf16 v[78:81], v[234:237], v[198:201], v[78:81]
	v_add_u32_e32 v130, s36, v168
	global_load_dwordx4 v[130:133], v130, vcc offset:256
	v_mfma_f32_16x16x32_bf16 v[46:49], v[234:237], v[210:213], v[46:49]
	v_mfma_f32_16x16x32_bf16 v[14:17], v[234:237], v[214:217], v[14:17]
	s_waitcnt vmcnt(7)
	ds_write_b128 v171, v[126:129] offset:32768
	v_mfma_f32_16x16x32_bf16 v[106:109], v[238:241], v[184:187], v[106:109]
	v_mfma_f32_16x16x32_bf16 v[74:77], v[238:241], v[198:201], v[74:77]
	global_load_dwordx4 v[126:129], v170, s[100:101] offset:256
	v_mfma_f32_16x16x32_bf16 v[42:45], v[238:241], v[210:213], v[42:45]
	v_mfma_f32_16x16x32_bf16 v[10:13], v[238:241], v[214:217], v[10:13]
	s_waitcnt vmcnt(7)
	ds_write_b128 v171, v[122:125] offset:40960
	v_mfma_f32_16x16x32_bf16 v[102:105], v[242:245], v[184:187], v[102:105]
	v_mfma_f32_16x16x32_bf16 v[70:73], v[242:245], v[198:201], v[70:73]
	v_add_u32_e32 v122, s34, v170
	global_load_dwordx4 v[122:125], v122, s[100:101] offset:256
	v_mfma_f32_16x16x32_bf16 v[38:41], v[242:245], v[210:213], v[38:41]
	v_mfma_f32_16x16x32_bf16 v[6:9], v[242:245], v[214:217], v[6:9]
	s_waitcnt vmcnt(7)
	ds_write_b128 v171, v[138:141] offset:49152
	s_waitcnt lgkmcnt(7)
	v_mfma_f32_16x16x32_bf16 v[94:97], v[246:249], v[184:187], v[94:97]
	v_mfma_f32_16x16x32_bf16 v[62:65], v[246:249], v[198:201], v[62:65]
	v_add_u32_e32 v138, s35, v170
	global_load_dwordx4 v[138:141], v138, s[100:101] offset:256
	v_mfma_f32_16x16x32_bf16 v[30:33], v[246:249], v[210:213], v[30:33]
	v_mfma_f32_16x16x32_bf16 v[2:5], v[246:249], v[214:217], v[2:5]
	s_waitcnt vmcnt(7)
	ds_write_b128 v171, v[134:137] offset:57344
	v_add_u32_e32 v134, s36, v170
	global_load_dwordx4 v[134:137], v134, s[100:101] offset:256
	v_add_u32_e32 v168, 0x80, v168
	v_add_u32_e32 v170, 0x80, v170
	s_waitcnt lgkmcnt(0)
	s_barrier
	s_cmp_eq_u32 s10, 16
	s_mov_b32 s4, s10
	s_cbranch_scc0 .LBB0_1308
	s_waitcnt vmcnt(4)
	v_add_u32_e32 v110, s7, v206
	s_waitcnt vmcnt(3)
	v_or_b32_e32 v114, v110, v205
	v_cmp_lt_i32_e32 vcc, s97, v114
	v_ashrrev_i32_e32 v112, 31, v114
	v_add_u32_e32 v116, 0xffffc000, v114
	v_ashrrev_i32_e32 v115, 11, v110
	v_cndmask_b32_e64 v113, v112, 0, vcc
	v_cndmask_b32_e32 v112, v114, v116, vcc
	v_mov_b32_e32 v116, s45
	v_mov_b32_e32 v117, s13
	v_mov_b32_e32 v118, s44
	v_mov_b32_e32 v119, s12
	v_or_b32_e32 v110, s6, v208
	s_waitcnt vmcnt(2)
	v_cndmask_b32_e64 v122, v115, 8, vcc
	v_cndmask_b32_e32 v121, v116, v117, vcc
	v_cndmask_b32_e32 v120, v118, v119, vcc
	v_lshlrev_b64 v[112:113], 12, v[112:113]
	v_ashrrev_i32_e32 v111, 31, v110
	v_lshl_add_u64 v[112:113], v[120:121], 0, v[112:113]
	v_mul_hi_i32_i24_e32 v121, 0x9000, v122
	v_mul_i32_i24_e32 v120, 0x9000, v122
	v_lshl_add_u64 v[120:121], s[14:15], 0, v[120:121]
	v_lshlrev_b64 v[110:111], 2, v[110:111]
	s_waitcnt vmcnt(0)
	v_lshl_add_u64 v[128:129], v[120:121], 0, v[110:111]
	v_lshl_add_u64 v[112:113], v[112:113], 0, v[110:111]
	global_load_dwordx4 v[120:123], v[128:129], off
	global_load_dwordx4 v[124:127], v[112:113], off
	s_waitcnt vmcnt(0)
	v_pk_fma_f32 v[120:121], v[158:159], v[120:121], v[124:125]
	v_pk_fma_f32 v[122:123], v[160:161], v[122:123], v[126:127]
	global_store_dwordx4 v[112:113], v[120:123], off
	global_load_dwordx4 v[120:123], v[128:129], off offset:64
	s_nop 0
	global_load_dwordx4 v[124:127], v[112:113], off offset:64
	s_waitcnt vmcnt(0)
	v_pk_fma_f32 v[120:121], v[154:155], v[120:121], v[124:125]
	v_pk_fma_f32 v[122:123], v[156:157], v[122:123], v[126:127]
	global_store_dwordx4 v[112:113], v[120:123], off offset:64
	global_load_dwordx4 v[120:123], v[128:129], off offset:128
	s_nop 0
	global_load_dwordx4 v[124:127], v[112:113], off offset:128
	s_waitcnt vmcnt(0)
	v_pk_fma_f32 v[120:121], v[150:151], v[120:121], v[124:125]
	v_pk_fma_f32 v[122:123], v[152:153], v[122:123], v[126:127]
	global_store_dwordx4 v[112:113], v[120:123], off offset:128
	global_load_dwordx4 v[120:123], v[128:129], off offset:192
	s_nop 0
	global_load_dwordx4 v[124:127], v[112:113], off offset:192
	s_waitcnt vmcnt(0)
	v_pk_fma_f32 v[120:121], v[146:147], v[120:121], v[124:125]
	v_pk_fma_f32 v[122:123], v[148:149], v[122:123], v[126:127]
	global_store_dwordx4 v[112:113], v[120:123], off offset:192
	global_load_dwordx4 v[120:123], v[128:129], off offset:256
	s_nop 0
	global_load_dwordx4 v[124:127], v[112:113], off offset:256
	s_waitcnt vmcnt(0)
	v_pk_fma_f32 v[120:121], v[142:143], v[120:121], v[124:125]
	v_pk_fma_f32 v[122:123], v[144:145], v[122:123], v[126:127]
	global_store_dwordx4 v[112:113], v[120:123], off offset:256
	global_load_dwordx4 v[120:123], v[128:129], off offset:320
	s_nop 0
	global_load_dwordx4 v[124:127], v[112:113], off offset:320
	s_waitcnt vmcnt(0)
	v_pk_fma_f32 v[106:107], v[106:107], v[120:121], v[124:125]
	v_pk_fma_f32 v[108:109], v[108:109], v[122:123], v[126:127]
	global_store_dwordx4 v[112:113], v[106:109], off offset:320
	global_load_dwordx4 v[106:109], v[128:129], off offset:384
	s_nop 0
	global_load_dwordx4 v[120:123], v[112:113], off offset:384
	s_waitcnt vmcnt(0)
	v_pk_fma_f32 v[102:103], v[102:103], v[106:107], v[120:121]
	v_pk_fma_f32 v[104:105], v[104:105], v[108:109], v[122:123]
	global_store_dwordx4 v[112:113], v[102:105], off offset:384
	global_load_dwordx4 v[102:105], v[128:129], off offset:448
	s_nop 0
	global_load_dwordx4 v[106:109], v[112:113], off offset:448
	s_waitcnt vmcnt(0)
	v_pk_fma_f32 v[94:95], v[94:95], v[102:103], v[106:107]
	v_pk_fma_f32 v[96:97], v[96:97], v[104:105], v[108:109]
	global_store_dwordx4 v[112:113], v[94:97], off offset:448
	s_nop 1
	v_or_b32_e32 v94, 16, v114
	v_cmp_lt_i32_e32 vcc, s97, v94
	v_add_u32_e32 v96, 0xffffc010, v114
	v_ashrrev_i32_e32 v95, 31, v94
	v_cndmask_b32_e64 v95, v95, 0, vcc
	v_cndmask_b32_e32 v94, v94, v96, vcc
	v_cndmask_b32_e64 v102, v115, 8, vcc
	v_cndmask_b32_e32 v97, v116, v117, vcc
	v_cndmask_b32_e32 v96, v118, v119, vcc
	v_lshlrev_b64 v[94:95], 12, v[94:95]
	v_lshl_add_u64 v[94:95], v[96:97], 0, v[94:95]
	v_mul_hi_i32_i24_e32 v97, 0x9000, v102
	v_mul_i32_i24_e32 v96, 0x9000, v102
	v_lshl_add_u64 v[96:97], s[14:15], 0, v[96:97]
	v_lshl_add_u64 v[112:113], v[96:97], 0, v[110:111]
	v_lshl_add_u64 v[94:95], v[94:95], 0, v[110:111]
	global_load_dwordx4 v[102:105], v[112:113], off
	global_load_dwordx4 v[106:109], v[94:95], off
	s_waitcnt vmcnt(0)
	v_pk_fma_f32 v[96:97], v[98:99], v[102:103], v[106:107]
	v_pk_fma_f32 v[98:99], v[100:101], v[104:105], v[108:109]
	global_store_dwordx4 v[94:95], v[96:99], off
	global_load_dwordx4 v[96:99], v[112:113], off offset:64
	s_nop 0
	global_load_dwordx4 v[100:103], v[94:95], off offset:64
	s_waitcnt vmcnt(0)
	v_pk_fma_f32 v[90:91], v[90:91], v[96:97], v[100:101]
	v_pk_fma_f32 v[92:93], v[92:93], v[98:99], v[102:103]
	global_store_dwordx4 v[94:95], v[90:93], off offset:64
	global_load_dwordx4 v[90:93], v[112:113], off offset:128
	s_nop 0
	global_load_dwordx4 v[96:99], v[94:95], off offset:128
	s_waitcnt vmcnt(0)
	v_pk_fma_f32 v[86:87], v[86:87], v[90:91], v[96:97]
	v_pk_fma_f32 v[88:89], v[88:89], v[92:93], v[98:99]
	global_store_dwordx4 v[94:95], v[86:89], off offset:128
	global_load_dwordx4 v[86:89], v[112:113], off offset:192
	s_nop 0
	global_load_dwordx4 v[90:93], v[94:95], off offset:192
	s_waitcnt vmcnt(0)
	v_pk_fma_f32 v[82:83], v[82:83], v[86:87], v[90:91]
	v_pk_fma_f32 v[84:85], v[84:85], v[88:89], v[92:93]
	global_store_dwordx4 v[94:95], v[82:85], off offset:192
	global_load_dwordx4 v[82:85], v[112:113], off offset:256
	s_nop 0
	global_load_dwordx4 v[86:89], v[94:95], off offset:256
	s_waitcnt vmcnt(0)
	v_pk_fma_f32 v[78:79], v[78:79], v[82:83], v[86:87]
	v_pk_fma_f32 v[80:81], v[80:81], v[84:85], v[88:89]
	global_store_dwordx4 v[94:95], v[78:81], off offset:256
	global_load_dwordx4 v[78:81], v[112:113], off offset:320
	s_nop 0
	global_load_dwordx4 v[82:85], v[94:95], off offset:320
	s_waitcnt vmcnt(0)
	v_pk_fma_f32 v[74:75], v[74:75], v[78:79], v[82:83]
	v_pk_fma_f32 v[76:77], v[76:77], v[80:81], v[84:85]
	global_store_dwordx4 v[94:95], v[74:77], off offset:320
	global_load_dwordx4 v[74:77], v[112:113], off offset:384
	s_nop 0
	global_load_dwordx4 v[78:81], v[94:95], off offset:384
	s_waitcnt vmcnt(0)
	v_pk_fma_f32 v[70:71], v[70:71], v[74:75], v[78:79]
	v_pk_fma_f32 v[72:73], v[72:73], v[76:77], v[80:81]
	global_store_dwordx4 v[94:95], v[70:73], off offset:384
	global_load_dwordx4 v[70:73], v[112:113], off offset:448
	s_nop 0
	global_load_dwordx4 v[74:77], v[94:95], off offset:448
	s_waitcnt vmcnt(0)
	v_pk_fma_f32 v[62:63], v[62:63], v[70:71], v[74:75]
	v_pk_fma_f32 v[64:65], v[64:65], v[72:73], v[76:77]
	global_store_dwordx4 v[94:95], v[62:65], off offset:448
	s_nop 1
	v_or_b32_e32 v62, 32, v114
	v_cmp_lt_i32_e32 vcc, s97, v62
	v_add_u32_e32 v64, 0xffffc020, v114
	v_ashrrev_i32_e32 v63, 31, v62
	v_cndmask_b32_e64 v63, v63, 0, vcc
	v_cndmask_b32_e32 v62, v62, v64, vcc
	v_cndmask_b32_e64 v70, v115, 8, vcc
	v_cndmask_b32_e32 v65, v116, v117, vcc
	v_cndmask_b32_e32 v64, v118, v119, vcc
	v_lshlrev_b64 v[62:63], 12, v[62:63]
	v_lshl_add_u64 v[62:63], v[64:65], 0, v[62:63]
	v_mul_hi_i32_i24_e32 v65, 0x9000, v70
	v_mul_i32_i24_e32 v64, 0x9000, v70
	v_lshl_add_u64 v[64:65], s[14:15], 0, v[64:65]
	v_lshl_add_u64 v[78:79], v[64:65], 0, v[110:111]
	v_lshl_add_u64 v[62:63], v[62:63], 0, v[110:111]
	global_load_dwordx4 v[70:73], v[78:79], off
	global_load_dwordx4 v[74:77], v[62:63], off
	s_waitcnt vmcnt(0)
	v_pk_fma_f32 v[64:65], v[66:67], v[70:71], v[74:75]
	v_pk_fma_f32 v[66:67], v[68:69], v[72:73], v[76:77]
	global_store_dwordx4 v[62:63], v[64:67], off
	global_load_dwordx4 v[64:67], v[78:79], off offset:64
	s_nop 0
	global_load_dwordx4 v[68:71], v[62:63], off offset:64
	s_waitcnt vmcnt(0)
	v_pk_fma_f32 v[58:59], v[58:59], v[64:65], v[68:69]
	v_pk_fma_f32 v[60:61], v[60:61], v[66:67], v[70:71]
	global_store_dwordx4 v[62:63], v[58:61], off offset:64
	global_load_dwordx4 v[58:61], v[78:79], off offset:128
	s_nop 0
	global_load_dwordx4 v[64:67], v[62:63], off offset:128
	s_waitcnt vmcnt(0)
	v_pk_fma_f32 v[54:55], v[54:55], v[58:59], v[64:65]
	v_pk_fma_f32 v[56:57], v[56:57], v[60:61], v[66:67]
	global_store_dwordx4 v[62:63], v[54:57], off offset:128
	global_load_dwordx4 v[54:57], v[78:79], off offset:192
	s_nop 0
	global_load_dwordx4 v[58:61], v[62:63], off offset:192
	s_waitcnt vmcnt(0)
	v_pk_fma_f32 v[50:51], v[50:51], v[54:55], v[58:59]
	v_pk_fma_f32 v[52:53], v[52:53], v[56:57], v[60:61]
	global_store_dwordx4 v[62:63], v[50:53], off offset:192
	global_load_dwordx4 v[50:53], v[78:79], off offset:256
	s_nop 0
	global_load_dwordx4 v[54:57], v[62:63], off offset:256
	s_waitcnt vmcnt(0)
	v_pk_fma_f32 v[46:47], v[46:47], v[50:51], v[54:55]
	v_pk_fma_f32 v[48:49], v[48:49], v[52:53], v[56:57]
	global_store_dwordx4 v[62:63], v[46:49], off offset:256
	global_load_dwordx4 v[46:49], v[78:79], off offset:320
	s_nop 0
	global_load_dwordx4 v[50:53], v[62:63], off offset:320
	s_waitcnt vmcnt(0)
	v_pk_fma_f32 v[42:43], v[42:43], v[46:47], v[50:51]
	v_pk_fma_f32 v[44:45], v[44:45], v[48:49], v[52:53]
	global_store_dwordx4 v[62:63], v[42:45], off offset:320
	global_load_dwordx4 v[42:45], v[78:79], off offset:384
	s_nop 0
	global_load_dwordx4 v[46:49], v[62:63], off offset:384
	s_waitcnt vmcnt(0)
	v_pk_fma_f32 v[38:39], v[38:39], v[42:43], v[46:47]
	v_pk_fma_f32 v[40:41], v[40:41], v[44:45], v[48:49]
	global_store_dwordx4 v[62:63], v[38:41], off offset:384
	global_load_dwordx4 v[38:41], v[78:79], off offset:448
	s_nop 0
	global_load_dwordx4 v[42:45], v[62:63], off offset:448
	s_waitcnt vmcnt(0)
	v_pk_fma_f32 v[30:31], v[30:31], v[38:39], v[42:43]
	v_pk_fma_f32 v[32:33], v[32:33], v[40:41], v[44:45]
	global_store_dwordx4 v[62:63], v[30:33], off offset:448
	s_nop 1
	v_or_b32_e32 v30, 48, v114
	v_cmp_lt_i32_e32 vcc, s97, v30
	v_add_u32_e32 v32, 0xffffc030, v114
	v_ashrrev_i32_e32 v31, 31, v30
	v_cndmask_b32_e64 v31, v31, 0, vcc
	v_cndmask_b32_e32 v30, v30, v32, vcc
	v_cndmask_b32_e64 v38, v115, 8, vcc
	v_cndmask_b32_e32 v33, v116, v117, vcc
	v_cndmask_b32_e32 v32, v118, v119, vcc
	v_lshlrev_b64 v[30:31], 12, v[30:31]
	v_lshl_add_u64 v[30:31], v[32:33], 0, v[30:31]
	v_mul_hi_i32_i24_e32 v33, 0x9000, v38
	v_mul_i32_i24_e32 v32, 0x9000, v38
	v_lshl_add_u64 v[32:33], s[14:15], 0, v[32:33]
	v_lshl_add_u64 v[46:47], v[32:33], 0, v[110:111]
	v_lshl_add_u64 v[30:31], v[30:31], 0, v[110:111]
	global_load_dwordx4 v[38:41], v[46:47], off
	global_load_dwordx4 v[42:45], v[30:31], off
	s_waitcnt vmcnt(0)
	v_pk_fma_f32 v[32:33], v[34:35], v[38:39], v[42:43]
	v_pk_fma_f32 v[34:35], v[36:37], v[40:41], v[44:45]
	global_store_dwordx4 v[30:31], v[32:35], off
	global_load_dwordx4 v[32:35], v[46:47], off offset:64
	s_nop 0
	global_load_dwordx4 v[36:39], v[30:31], off offset:64
	s_waitcnt vmcnt(0)
	v_pk_fma_f32 v[26:27], v[26:27], v[32:33], v[36:37]
	v_pk_fma_f32 v[28:29], v[28:29], v[34:35], v[38:39]
	global_store_dwordx4 v[30:31], v[26:29], off offset:64
	global_load_dwordx4 v[26:29], v[46:47], off offset:128
	s_nop 0
	global_load_dwordx4 v[32:35], v[30:31], off offset:128
	s_waitcnt vmcnt(0)
	v_pk_fma_f32 v[22:23], v[22:23], v[26:27], v[32:33]
	v_pk_fma_f32 v[24:25], v[24:25], v[28:29], v[34:35]
	global_store_dwordx4 v[30:31], v[22:25], off offset:128
	global_load_dwordx4 v[22:25], v[46:47], off offset:192
	s_nop 0
	global_load_dwordx4 v[26:29], v[30:31], off offset:192
	s_waitcnt vmcnt(0)
	v_pk_fma_f32 v[18:19], v[18:19], v[22:23], v[26:27]
	v_pk_fma_f32 v[20:21], v[20:21], v[24:25], v[28:29]
	global_store_dwordx4 v[30:31], v[18:21], off offset:192
	global_load_dwordx4 v[18:21], v[46:47], off offset:256
	s_nop 0
	global_load_dwordx4 v[22:25], v[30:31], off offset:256
	s_waitcnt vmcnt(0)
	v_pk_fma_f32 v[14:15], v[14:15], v[18:19], v[22:23]
	v_pk_fma_f32 v[16:17], v[16:17], v[20:21], v[24:25]
	global_store_dwordx4 v[30:31], v[14:17], off offset:256
	global_load_dwordx4 v[14:17], v[46:47], off offset:320
	s_nop 0
	global_load_dwordx4 v[18:21], v[30:31], off offset:320
	s_waitcnt vmcnt(0)
	v_pk_fma_f32 v[10:11], v[10:11], v[14:15], v[18:19]
	v_pk_fma_f32 v[12:13], v[12:13], v[16:17], v[20:21]
	global_store_dwordx4 v[30:31], v[10:13], off offset:320
	global_load_dwordx4 v[10:13], v[46:47], off offset:384
	s_nop 0
	global_load_dwordx4 v[14:17], v[30:31], off offset:384
	s_waitcnt vmcnt(0)
	v_pk_fma_f32 v[6:7], v[6:7], v[10:11], v[14:15]
	v_pk_fma_f32 v[8:9], v[8:9], v[12:13], v[16:17]
	global_store_dwordx4 v[30:31], v[6:9], off offset:384
	global_load_dwordx4 v[6:9], v[46:47], off offset:448
	s_nop 0
	global_load_dwordx4 v[10:13], v[30:31], off offset:448
	s_waitcnt vmcnt(0)
	v_pk_fma_f32 v[2:3], v[2:3], v[6:7], v[10:11]
	v_pk_fma_f32 v[4:5], v[4:5], v[8:9], v[12:13]
	global_store_dwordx4 v[30:31], v[2:5], off offset:448
	s_add_i32 s19, s19, s18
	s_cmpk_gt_i32 s19, 0xff
	s_cbranch_scc0 .LBB0_1307

.LBB0_1441:
	s_bitcmp1_b32 s4, 0
	s_cselect_b32 s2, 0x12000, 0
	v_or_b32_e32 v218, s2, v206
	v_add_u32_e32 v214, v218, v0
	v_add_u32_e32 v246, v218, v167
	ds_read_b128 v[184:187], v214
	ds_read_b128 v[198:201], v214 offset:2048
	ds_read_b128 v[210:213], v214 offset:4096
	ds_read_b128 v[214:217], v214 offset:6144
	ds_read_b128 v[218:221], v246 offset:32768
	ds_read_b128 v[222:225], v246 offset:34816
	ds_read_b128 v[226:229], v246 offset:36864
	ds_read_b128 v[230:233], v246 offset:38912
	ds_read_b128 v[234:237], v246 offset:40960
	ds_read_b128 v[238:241], v246 offset:43008
	ds_read_b128 v[242:245], v246 offset:45056
	ds_read_b128 v[246:249], v246 offset:47104
	s_add_i32 s10, s4, 1
	s_bitcmp1_b32 s10, 0
	s_cselect_b32 s3, 0x12000, 0
	v_add_u32_e32 v171, s3, v166
	v_xor_b32_e32 v169, 64, v206
	v_add3_u32 v169, s2, v167, v169
	s_waitcnt lgkmcnt(7)
	v_mfma_f32_16x16x32_bf16 v[158:161], v[218:221], v[184:187], v[158:161]
	v_mfma_f32_16x16x32_bf16 v[94:97], v[218:221], v[198:201], v[94:97]
	v_mfma_f32_16x16x32_bf16 v[62:65], v[218:221], v[210:213], v[62:65]
	v_mfma_f32_16x16x32_bf16 v[30:33], v[218:221], v[214:217], v[30:33]
	ds_read_b128 v[218:221], v169 offset:32768
	s_waitcnt lgkmcnt(7)
	v_mfma_f32_16x16x32_bf16 v[154:157], v[222:225], v[184:187], v[154:157]
	v_mfma_f32_16x16x32_bf16 v[90:93], v[222:225], v[198:201], v[90:93]
	v_mfma_f32_16x16x32_bf16 v[58:61], v[222:225], v[210:213], v[58:61]
	v_mfma_f32_16x16x32_bf16 v[26:29], v[222:225], v[214:217], v[26:29]
	ds_read_b128 v[222:225], v169 offset:34816
	s_waitcnt lgkmcnt(7)
	v_mfma_f32_16x16x32_bf16 v[150:153], v[226:229], v[184:187], v[150:153]
	v_mfma_f32_16x16x32_bf16 v[86:89], v[226:229], v[198:201], v[86:89]
	v_mfma_f32_16x16x32_bf16 v[54:57], v[226:229], v[210:213], v[54:57]
	v_mfma_f32_16x16x32_bf16 v[22:25], v[226:229], v[214:217], v[22:25]
	ds_read_b128 v[226:229], v169 offset:36864
	s_waitcnt lgkmcnt(7)
	v_mfma_f32_16x16x32_bf16 v[146:149], v[230:233], v[184:187], v[146:149]
	v_mfma_f32_16x16x32_bf16 v[82:85], v[230:233], v[198:201], v[82:85]
	v_mfma_f32_16x16x32_bf16 v[50:53], v[230:233], v[210:213], v[50:53]
	v_mfma_f32_16x16x32_bf16 v[18:21], v[230:233], v[214:217], v[18:21]
	ds_read_b128 v[230:233], v169 offset:38912
	s_waitcnt lgkmcnt(7)
	v_mfma_f32_16x16x32_bf16 v[142:145], v[234:237], v[184:187], v[142:145]
	v_mfma_f32_16x16x32_bf16 v[78:81], v[234:237], v[198:201], v[78:81]
	v_mfma_f32_16x16x32_bf16 v[46:49], v[234:237], v[210:213], v[46:49]
	v_mfma_f32_16x16x32_bf16 v[14:17], v[234:237], v[214:217], v[14:17]
	ds_read_b128 v[234:237], v169 offset:40960
	s_waitcnt lgkmcnt(7)
	v_mfma_f32_16x16x32_bf16 v[138:141], v[238:241], v[184:187], v[138:141]
	v_mfma_f32_16x16x32_bf16 v[74:77], v[238:241], v[198:201], v[74:77]
	v_mfma_f32_16x16x32_bf16 v[42:45], v[238:241], v[210:213], v[42:45]
	v_mfma_f32_16x16x32_bf16 v[10:13], v[238:241], v[214:217], v[10:13]
	ds_read_b128 v[238:241], v169 offset:43008
	s_waitcnt lgkmcnt(7)
	v_mfma_f32_16x16x32_bf16 v[102:105], v[242:245], v[184:187], v[102:105]
	v_mfma_f32_16x16x32_bf16 v[70:73], v[242:245], v[198:201], v[70:73]
	v_mfma_f32_16x16x32_bf16 v[38:41], v[242:245], v[210:213], v[38:41]
	v_mfma_f32_16x16x32_bf16 v[6:9], v[242:245], v[214:217], v[6:9]
	ds_read_b128 v[242:245], v169 offset:45056
	s_waitcnt lgkmcnt(7)
	v_mfma_f32_16x16x32_bf16 v[98:101], v[246:249], v[184:187], v[98:101]
	v_mfma_f32_16x16x32_bf16 v[66:69], v[246:249], v[198:201], v[66:69]
	v_xor_b32_e32 v169, 64, v206
	v_add3_u32 v169, s2, v0, v169
	ds_read_b128 v[184:187], v169
	ds_read_b128 v[198:201], v169 offset:2048
	v_mfma_f32_16x16x32_bf16 v[34:37], v[246:249], v[210:213], v[34:37]
	ds_read_b128 v[210:213], v169 offset:4096
	v_mfma_f32_16x16x32_bf16 v[2:5], v[246:249], v[214:217], v[2:5]
	ds_read_b128 v[214:217], v169 offset:6144
	v_xor_b32_e32 v169, 64, v206
	v_add3_u32 v169, s2, v167, v169
	ds_read_b128 v[246:249], v169 offset:47104
	s_waitcnt lgkmcnt(1)
	v_mfma_f32_16x16x32_bf16 v[158:161], v[218:221], v[184:187], v[158:161]
	v_mfma_f32_16x16x32_bf16 v[94:97], v[218:221], v[198:201], v[94:97]
	v_mfma_f32_16x16x32_bf16 v[62:65], v[218:221], v[210:213], v[62:65]
	v_mfma_f32_16x16x32_bf16 v[30:33], v[218:221], v[214:217], v[30:33]
	s_waitcnt vmcnt(7)
	ds_write_b128 v171, v[114:117]
	v_mfma_f32_16x16x32_bf16 v[154:157], v[222:225], v[184:187], v[154:157]
	v_mfma_f32_16x16x32_bf16 v[90:93], v[222:225], v[198:201], v[90:93]
	global_load_dwordx4 v[114:117], v168, vcc offset:256
	v_mfma_f32_16x16x32_bf16 v[58:61], v[222:225], v[210:213], v[58:61]
	v_mfma_f32_16x16x32_bf16 v[26:29], v[222:225], v[214:217], v[26:29]
	s_waitcnt vmcnt(7)
	ds_write_b128 v171, v[106:109] offset:8192
	v_mfma_f32_16x16x32_bf16 v[150:153], v[226:229], v[184:187], v[150:153]
	v_mfma_f32_16x16x32_bf16 v[86:89], v[226:229], v[198:201], v[86:89]
	v_add_u32_e32 v106, s34, v168
	global_load_dwordx4 v[106:109], v106, vcc offset:256
	v_mfma_f32_16x16x32_bf16 v[54:57], v[226:229], v[210:213], v[54:57]
	v_mfma_f32_16x16x32_bf16 v[22:25], v[226:229], v[214:217], v[22:25]
	s_waitcnt vmcnt(7)
	ds_write_b128 v171, v[110:113] offset:16384
	v_mfma_f32_16x16x32_bf16 v[146:149], v[230:233], v[184:187], v[146:149]
	v_mfma_f32_16x16x32_bf16 v[82:85], v[230:233], v[198:201], v[82:85]
	v_add_u32_e32 v110, s35, v168
	global_load_dwordx4 v[110:113], v110, vcc offset:256
	v_mfma_f32_16x16x32_bf16 v[50:53], v[230:233], v[210:213], v[50:53]
	v_mfma_f32_16x16x32_bf16 v[18:21], v[230:233], v[214:217], v[18:21]
	s_waitcnt vmcnt(7)
	ds_write_b128 v171, v[126:129] offset:24576
	v_mfma_f32_16x16x32_bf16 v[142:145], v[234:237], v[184:187], v[142:145]
	v_mfma_f32_16x16x32_bf16 v[78:81], v[234:237], v[198:201], v[78:81]
	v_add_u32_e32 v126, s36, v168
	global_load_dwordx4 v[126:129], v126, vcc offset:256
	v_mfma_f32_16x16x32_bf16 v[46:49], v[234:237], v[210:213], v[46:49]
	v_mfma_f32_16x16x32_bf16 v[14:17], v[234:237], v[214:217], v[14:17]
	s_waitcnt vmcnt(7)
	ds_write_b128 v171, v[122:125] offset:32768
	v_mfma_f32_16x16x32_bf16 v[138:141], v[238:241], v[184:187], v[138:141]
	v_mfma_f32_16x16x32_bf16 v[74:77], v[238:241], v[198:201], v[74:77]
	global_load_dwordx4 v[122:125], v170, s[100:101] offset:256
	v_mfma_f32_16x16x32_bf16 v[42:45], v[238:241], v[210:213], v[42:45]
	v_mfma_f32_16x16x32_bf16 v[10:13], v[238:241], v[214:217], v[10:13]
	s_waitcnt vmcnt(7)
	ds_write_b128 v171, v[118:121] offset:40960
	v_mfma_f32_16x16x32_bf16 v[102:105], v[242:245], v[184:187], v[102:105]
	v_mfma_f32_16x16x32_bf16 v[70:73], v[242:245], v[198:201], v[70:73]
	v_add_u32_e32 v118, s34, v170
	global_load_dwordx4 v[118:121], v118, s[100:101] offset:256
	v_mfma_f32_16x16x32_bf16 v[38:41], v[242:245], v[210:213], v[38:41]
	v_mfma_f32_16x16x32_bf16 v[6:9], v[242:245], v[214:217], v[6:9]
	s_waitcnt vmcnt(7)
	ds_write_b128 v171, v[134:137] offset:49152
	s_waitcnt lgkmcnt(7)
	v_mfma_f32_16x16x32_bf16 v[98:101], v[246:249], v[184:187], v[98:101]
	v_mfma_f32_16x16x32_bf16 v[66:69], v[246:249], v[198:201], v[66:69]
	v_add_u32_e32 v134, s35, v170
	global_load_dwordx4 v[134:137], v134, s[100:101] offset:256
	v_mfma_f32_16x16x32_bf16 v[34:37], v[246:249], v[210:213], v[34:37]
	v_mfma_f32_16x16x32_bf16 v[2:5], v[246:249], v[214:217], v[2:5]
	s_waitcnt vmcnt(7)
	ds_write_b128 v171, v[130:133] offset:57344
	v_add_u32_e32 v130, s36, v170
	global_load_dwordx4 v[130:133], v130, s[100:101] offset:256
	v_add_u32_e32 v168, 0x80, v168
	v_add_u32_e32 v170, 0x80, v170
	s_waitcnt lgkmcnt(0)
	s_barrier
	s_cmp_eq_u32 s10, 16
	s_mov_b32 s4, s10
	s_cbranch_scc0 .LBB0_1441
	s_waitcnt vmcnt(4)
	v_mul_f32_e32 v109, 0xbfb8aa3b, v158
	v_exp_f32_e32 v109, v109
	s_waitcnt vmcnt(3)
	v_mul_f32_e32 v111, 0xbfb8aa3b, v159
	v_exp_f32_e32 v111, v111
	v_mul_f32_e32 v115, 0xbfb8aa3b, v161
	v_add_f32_e32 v109, 1.0, v109
	v_rcp_f32_e32 v114, v109
	v_add_f32_e32 v109, 1.0, v111
	v_mul_f32_e32 v111, 0xbfb8aa3b, v160
	v_exp_f32_e32 v111, v111
	v_exp_f32_e32 v117, v115
	v_rcp_f32_e32 v116, v109
	s_waitcnt vmcnt(2)
	v_mov_b32_e32 v118, v158
	v_add_f32_e32 v109, 1.0, v111
	v_rcp_f32_e32 v115, v109
	v_add_f32_e32 v109, 1.0, v117
	v_rcp_f32_e32 v117, v109
	v_mov_b32_e32 v119, v160
	v_pk_mul_f32 v[114:115], v[118:119], v[114:115]
	v_mov_b32_e32 v118, v154
	v_mov_b32_e32 v119, v156
	v_mov_b32_e32 v160, v159
	v_pk_mul_f32 v[114:115], v[118:119], v[114:115]
	v_pk_mul_f32 v[116:117], v[160:161], v[116:117]
	v_mov_b32_e32 v156, v155
	v_pk_mul_f32 v[116:117], v[156:157], v[116:117]
	v_and_b32_sdwa v111, v115, v177 dst_sel:DWORD dst_unused:UNUSED_PAD src0_sel:WORD_1 src1_sel:DWORD
	v_and_b32_sdwa v118, v114, v177 dst_sel:DWORD dst_unused:UNUSED_PAD src0_sel:WORD_1 src1_sel:DWORD
	v_add3_u32 v111, v115, v111, s28
	v_and_b32_sdwa v115, v117, v177 dst_sel:DWORD dst_unused:UNUSED_PAD src0_sel:WORD_1 src1_sel:DWORD
	v_add3_u32 v114, v114, v118, s28
	v_and_b32_sdwa v118, v116, v177 dst_sel:DWORD dst_unused:UNUSED_PAD src0_sel:WORD_1 src1_sel:DWORD
	v_add3_u32 v115, v117, v115, s28
	v_or_b32_e32 v106, s7, v207
	v_add3_u32 v116, v116, v118, s28
	v_and_b32_e32 v115, 0xffff0000, v115
	v_ashrrev_i32_e32 v106, 1, v106
	v_and_b32_e32 v116, 0xffff0000, v116
	v_or_b32_sdwa v115, v115, v111 dst_sel:DWORD dst_unused:UNUSED_PAD src0_sel:DWORD src1_sel:WORD_1
	v_mul_f32_e32 v111, 0xbfb8aa3b, v150
	v_or_b32_e32 v108, v106, v208
	v_or_b32_sdwa v114, v116, v114 dst_sel:DWORD dst_unused:UNUSED_PAD src0_sel:DWORD src1_sel:WORD_1
	v_exp_f32_e32 v111, v111
	v_mul_f32_e32 v116, 0xbfb8aa3b, v151
	v_add_u32_e32 v110, s6, v205
	v_mov_b64_e32 v[106:107], s[12:13]
	v_ashrrev_i32_e32 v109, 31, v108
	v_exp_f32_e32 v116, v116
	v_mad_i64_i32 v[112:113], s[6:7], v110, s52, v[106:107]
	v_lshlrev_b64 v[108:109], 1, v[108:109]
	v_lshl_add_u64 v[112:113], v[112:113], 0, v[108:109]
	s_waitcnt vmcnt(0)
	global_store_dwordx2 v[112:113], v[114:115], off
	v_add_f32_e32 v111, 1.0, v111
	v_mul_f32_e32 v115, 0xbfb8aa3b, v152
	v_rcp_f32_e32 v114, v111
	v_add_f32_e32 v111, 1.0, v116
	v_exp_f32_e32 v115, v115
	v_mul_f32_e32 v116, 0xbfb8aa3b, v153
	v_exp_f32_e32 v117, v116
	v_rcp_f32_e32 v116, v111
	v_add_f32_e32 v111, 1.0, v115
	v_rcp_f32_e32 v115, v111
	v_add_f32_e32 v111, 1.0, v117
	v_rcp_f32_e32 v117, v111
	v_mov_b32_e32 v118, v150
	v_mov_b32_e32 v119, v152
	v_pk_mul_f32 v[114:115], v[118:119], v[114:115]
	v_mov_b32_e32 v118, v146
	v_mov_b32_e32 v119, v148
	v_mov_b32_e32 v152, v151
	v_pk_mul_f32 v[114:115], v[118:119], v[114:115]
	v_pk_mul_f32 v[116:117], v[152:153], v[116:117]
	v_mov_b32_e32 v148, v147
	v_pk_mul_f32 v[116:117], v[148:149], v[116:117]
	v_and_b32_sdwa v111, v115, v177 dst_sel:DWORD dst_unused:UNUSED_PAD src0_sel:WORD_1 src1_sel:DWORD
	v_and_b32_sdwa v118, v114, v177 dst_sel:DWORD dst_unused:UNUSED_PAD src0_sel:WORD_1 src1_sel:DWORD
	v_add3_u32 v111, v115, v111, s28
	v_and_b32_sdwa v115, v117, v177 dst_sel:DWORD dst_unused:UNUSED_PAD src0_sel:WORD_1 src1_sel:DWORD
	v_add3_u32 v114, v114, v118, s28
	v_and_b32_sdwa v118, v116, v177 dst_sel:DWORD dst_unused:UNUSED_PAD src0_sel:WORD_1 src1_sel:DWORD
	v_add3_u32 v115, v117, v115, s28
	v_add3_u32 v116, v116, v118, s28
	v_and_b32_e32 v115, 0xffff0000, v115
	v_and_b32_e32 v116, 0xffff0000, v116
	v_or_b32_sdwa v115, v115, v111 dst_sel:DWORD dst_unused:UNUSED_PAD src0_sel:DWORD src1_sel:WORD_1
	v_mul_f32_e32 v111, 0xbfb8aa3b, v142
	v_or_b32_sdwa v114, v116, v114 dst_sel:DWORD dst_unused:UNUSED_PAD src0_sel:DWORD src1_sel:WORD_1
	v_exp_f32_e32 v111, v111
	v_mul_f32_e32 v116, 0xbfb8aa3b, v143
	v_exp_f32_e32 v116, v116
	global_store_dwordx2 v[112:113], v[114:115], off offset:32
	v_add_f32_e32 v111, 1.0, v111
	v_mul_f32_e32 v115, 0xbfb8aa3b, v144
	v_rcp_f32_e32 v114, v111
	v_add_f32_e32 v111, 1.0, v116
	v_exp_f32_e32 v115, v115
	v_mul_f32_e32 v116, 0xbfb8aa3b, v145
	v_exp_f32_e32 v117, v116
	v_rcp_f32_e32 v116, v111
	v_add_f32_e32 v111, 1.0, v115
	v_rcp_f32_e32 v115, v111
	v_add_f32_e32 v111, 1.0, v117
	v_rcp_f32_e32 v117, v111
	v_mov_b32_e32 v118, v142
	v_mov_b32_e32 v119, v144
	v_pk_mul_f32 v[114:115], v[118:119], v[114:115]
	v_mov_b32_e32 v118, v138
	v_mov_b32_e32 v119, v140
	v_mov_b32_e32 v144, v143
	v_pk_mul_f32 v[114:115], v[118:119], v[114:115]
	v_pk_mul_f32 v[116:117], v[144:145], v[116:117]
	v_mov_b32_e32 v140, v139
	v_pk_mul_f32 v[116:117], v[140:141], v[116:117]
	v_and_b32_sdwa v111, v115, v177 dst_sel:DWORD dst_unused:UNUSED_PAD src0_sel:WORD_1 src1_sel:DWORD
	v_and_b32_sdwa v118, v114, v177 dst_sel:DWORD dst_unused:UNUSED_PAD src0_sel:WORD_1 src1_sel:DWORD
	v_add3_u32 v111, v115, v111, s28
	v_and_b32_sdwa v115, v117, v177 dst_sel:DWORD dst_unused:UNUSED_PAD src0_sel:WORD_1 src1_sel:DWORD
	v_add3_u32 v114, v114, v118, s28
	v_and_b32_sdwa v118, v116, v177 dst_sel:DWORD dst_unused:UNUSED_PAD src0_sel:WORD_1 src1_sel:DWORD
	v_add3_u32 v115, v117, v115, s28
	v_add3_u32 v116, v116, v118, s28
	v_and_b32_e32 v115, 0xffff0000, v115
	v_and_b32_e32 v116, 0xffff0000, v116
	v_or_b32_sdwa v115, v115, v111 dst_sel:DWORD dst_unused:UNUSED_PAD src0_sel:DWORD src1_sel:WORD_1
	v_mul_f32_e32 v111, 0xbfb8aa3b, v102
	v_or_b32_sdwa v114, v116, v114 dst_sel:DWORD dst_unused:UNUSED_PAD src0_sel:DWORD src1_sel:WORD_1
	v_exp_f32_e32 v111, v111
	v_mul_f32_e32 v116, 0xbfb8aa3b, v103
	v_exp_f32_e32 v116, v116
	global_store_dwordx2 v[112:113], v[114:115], off offset:64
	v_add_f32_e32 v111, 1.0, v111
	v_mul_f32_e32 v115, 0xbfb8aa3b, v104
	v_rcp_f32_e32 v114, v111
	v_add_f32_e32 v111, 1.0, v116
	v_exp_f32_e32 v115, v115
	v_mul_f32_e32 v116, 0xbfb8aa3b, v105
	v_exp_f32_e32 v117, v116
	v_rcp_f32_e32 v116, v111
	v_add_f32_e32 v111, 1.0, v115
	v_rcp_f32_e32 v115, v111
	v_add_f32_e32 v111, 1.0, v117
	v_rcp_f32_e32 v117, v111
	v_mov_b32_e32 v118, v102
	v_mov_b32_e32 v119, v104
	v_mov_b32_e32 v104, v103
	v_pk_mul_f32 v[114:115], v[118:119], v[114:115]
	v_mov_b32_e32 v119, v100
	v_pk_mul_f32 v[102:103], v[104:105], v[116:117]
	v_mov_b32_e32 v100, v99
	v_mov_b32_e32 v118, v98
	v_pk_mul_f32 v[98:99], v[100:101], v[102:103]
	v_pk_mul_f32 v[114:115], v[118:119], v[114:115]
	v_and_b32_sdwa v102, v99, v177 dst_sel:DWORD dst_unused:UNUSED_PAD src0_sel:WORD_1 src1_sel:DWORD
	v_and_b32_sdwa v103, v98, v177 dst_sel:DWORD dst_unused:UNUSED_PAD src0_sel:WORD_1 src1_sel:DWORD
	v_and_b32_sdwa v100, v115, v177 dst_sel:DWORD dst_unused:UNUSED_PAD src0_sel:WORD_1 src1_sel:DWORD
	v_and_b32_sdwa v101, v114, v177 dst_sel:DWORD dst_unused:UNUSED_PAD src0_sel:WORD_1 src1_sel:DWORD
	v_add3_u32 v99, v99, v102, s28
	v_add3_u32 v98, v98, v103, s28
	v_add3_u32 v101, v114, v101, s28
	v_add3_u32 v100, v115, v100, s28
	v_and_b32_e32 v99, 0xffff0000, v99
	v_and_b32_e32 v98, 0xffff0000, v98
	v_or_b32_sdwa v99, v99, v100 dst_sel:DWORD dst_unused:UNUSED_PAD src0_sel:DWORD src1_sel:WORD_1
	v_or_b32_sdwa v98, v98, v101 dst_sel:DWORD dst_unused:UNUSED_PAD src0_sel:DWORD src1_sel:WORD_1
	global_store_dwordx2 v[112:113], v[98:99], off offset:96
	v_mul_f32_e32 v99, 0xbfb8aa3b, v94
	v_exp_f32_e32 v100, v99
	v_mul_f32_e32 v99, 0xbfb8aa3b, v95
	v_mul_f32_e32 v102, 0xbfb8aa3b, v96
	v_exp_f32_e32 v101, v99
	v_exp_f32_e32 v103, v102
	v_mul_f32_e32 v102, 0xbfb8aa3b, v97
	v_exp_f32_e32 v104, v102
	v_add_f32_e32 v101, 1.0, v101
	v_add_f32_e32 v100, 1.0, v100
	v_rcp_f32_e32 v102, v101
	v_add_f32_e32 v101, 1.0, v103
	v_add_f32_e32 v103, 1.0, v104
	v_rcp_f32_e32 v100, v100
	v_rcp_f32_e32 v101, v101
	v_rcp_f32_e32 v103, v103
	v_mov_b32_e32 v104, v94
	v_mov_b32_e32 v105, v96
	v_mov_b32_e32 v96, v95
	v_pk_mul_f32 v[100:101], v[104:105], v[100:101]
	v_mov_b32_e32 v105, v92
	v_pk_mul_f32 v[94:95], v[96:97], v[102:103]
	v_mov_b32_e32 v92, v91
	v_mov_b32_e32 v104, v90
	v_pk_mul_f32 v[90:91], v[92:93], v[94:95]
	v_pk_mul_f32 v[100:101], v[104:105], v[100:101]
	v_and_b32_sdwa v94, v91, v177 dst_sel:DWORD dst_unused:UNUSED_PAD src0_sel:WORD_1 src1_sel:DWORD
	v_and_b32_sdwa v92, v101, v177 dst_sel:DWORD dst_unused:UNUSED_PAD src0_sel:WORD_1 src1_sel:DWORD
	v_and_b32_sdwa v95, v90, v177 dst_sel:DWORD dst_unused:UNUSED_PAD src0_sel:WORD_1 src1_sel:DWORD
	v_add3_u32 v91, v91, v94, s28
	v_and_b32_sdwa v93, v100, v177 dst_sel:DWORD dst_unused:UNUSED_PAD src0_sel:WORD_1 src1_sel:DWORD
	v_add3_u32 v92, v101, v92, s28
	v_add3_u32 v90, v90, v95, s28
	v_and_b32_e32 v91, 0xffff0000, v91
	v_add3_u32 v93, v100, v93, s28
	v_and_b32_e32 v90, 0xffff0000, v90
	v_or_b32_sdwa v91, v91, v92 dst_sel:DWORD dst_unused:UNUSED_PAD src0_sel:DWORD src1_sel:WORD_1
	v_mul_f32_e32 v92, 0xbfb8aa3b, v86
	v_or_b32_sdwa v90, v90, v93 dst_sel:DWORD dst_unused:UNUSED_PAD src0_sel:DWORD src1_sel:WORD_1
	v_exp_f32_e32 v92, v92
	v_mul_f32_e32 v93, 0xbfb8aa3b, v87
	v_or_b32_e32 v98, 16, v110
	v_exp_f32_e32 v93, v93
	v_mad_i64_i32 v[98:99], s[6:7], v98, s52, v[106:107]
	v_lshl_add_u64 v[98:99], v[98:99], 0, v[108:109]
	global_store_dwordx2 v[98:99], v[90:91], off
	v_add_f32_e32 v90, 1.0, v92
	v_mul_f32_e32 v92, 0xbfb8aa3b, v88
	v_add_f32_e32 v91, 1.0, v93
	v_exp_f32_e32 v93, v92
	v_mul_f32_e32 v92, 0xbfb8aa3b, v89
	v_exp_f32_e32 v94, v92
	v_rcp_f32_e32 v92, v91
	v_add_f32_e32 v91, 1.0, v93
	v_rcp_f32_e32 v90, v90
	v_add_f32_e32 v93, 1.0, v94
	v_rcp_f32_e32 v91, v91
	v_rcp_f32_e32 v93, v93
	v_mov_b32_e32 v94, v86
	v_mov_b32_e32 v95, v88
	v_mov_b32_e32 v88, v87
	v_pk_mul_f32 v[90:91], v[94:95], v[90:91]
	v_mov_b32_e32 v95, v84
	v_pk_mul_f32 v[86:87], v[88:89], v[92:93]
	v_mov_b32_e32 v84, v83
	v_mov_b32_e32 v94, v82
	v_pk_mul_f32 v[82:83], v[84:85], v[86:87]
	v_pk_mul_f32 v[90:91], v[94:95], v[90:91]
	v_and_b32_sdwa v86, v83, v177 dst_sel:DWORD dst_unused:UNUSED_PAD src0_sel:WORD_1 src1_sel:DWORD
	v_and_b32_sdwa v84, v91, v177 dst_sel:DWORD dst_unused:UNUSED_PAD src0_sel:WORD_1 src1_sel:DWORD
	v_and_b32_sdwa v87, v82, v177 dst_sel:DWORD dst_unused:UNUSED_PAD src0_sel:WORD_1 src1_sel:DWORD
	v_add3_u32 v83, v83, v86, s28
	v_and_b32_sdwa v85, v90, v177 dst_sel:DWORD dst_unused:UNUSED_PAD src0_sel:WORD_1 src1_sel:DWORD
	v_add3_u32 v84, v91, v84, s28
	v_add3_u32 v82, v82, v87, s28
	v_and_b32_e32 v83, 0xffff0000, v83
	v_add3_u32 v85, v90, v85, s28
	v_and_b32_e32 v82, 0xffff0000, v82
	v_or_b32_sdwa v83, v83, v84 dst_sel:DWORD dst_unused:UNUSED_PAD src0_sel:DWORD src1_sel:WORD_1
	v_mul_f32_e32 v84, 0xbfb8aa3b, v78
	v_or_b32_sdwa v82, v82, v85 dst_sel:DWORD dst_unused:UNUSED_PAD src0_sel:DWORD src1_sel:WORD_1
	v_exp_f32_e32 v84, v84
	v_mul_f32_e32 v85, 0xbfb8aa3b, v79
	v_exp_f32_e32 v85, v85
	global_store_dwordx2 v[98:99], v[82:83], off offset:32
	v_add_f32_e32 v82, 1.0, v84
	v_mul_f32_e32 v84, 0xbfb8aa3b, v80
	v_add_f32_e32 v83, 1.0, v85
	v_exp_f32_e32 v85, v84
	v_mul_f32_e32 v84, 0xbfb8aa3b, v81
	v_exp_f32_e32 v86, v84
	v_rcp_f32_e32 v84, v83
	v_add_f32_e32 v83, 1.0, v85
	v_rcp_f32_e32 v82, v82
	v_add_f32_e32 v85, 1.0, v86
	v_rcp_f32_e32 v83, v83
	v_rcp_f32_e32 v85, v85
	v_mov_b32_e32 v86, v78
	v_mov_b32_e32 v87, v80
	v_mov_b32_e32 v80, v79
	v_pk_mul_f32 v[82:83], v[86:87], v[82:83]
	v_mov_b32_e32 v87, v76
	v_pk_mul_f32 v[78:79], v[80:81], v[84:85]
	v_mov_b32_e32 v76, v75
	v_mov_b32_e32 v86, v74
	v_pk_mul_f32 v[74:75], v[76:77], v[78:79]
	v_pk_mul_f32 v[82:83], v[86:87], v[82:83]
	v_and_b32_sdwa v78, v75, v177 dst_sel:DWORD dst_unused:UNUSED_PAD src0_sel:WORD_1 src1_sel:DWORD
	v_and_b32_sdwa v76, v83, v177 dst_sel:DWORD dst_unused:UNUSED_PAD src0_sel:WORD_1 src1_sel:DWORD
	v_and_b32_sdwa v79, v74, v177 dst_sel:DWORD dst_unused:UNUSED_PAD src0_sel:WORD_1 src1_sel:DWORD
	v_add3_u32 v75, v75, v78, s28
	v_and_b32_sdwa v77, v82, v177 dst_sel:DWORD dst_unused:UNUSED_PAD src0_sel:WORD_1 src1_sel:DWORD
	v_add3_u32 v76, v83, v76, s28
	v_add3_u32 v74, v74, v79, s28
	v_and_b32_e32 v75, 0xffff0000, v75
	v_add3_u32 v77, v82, v77, s28
	v_and_b32_e32 v74, 0xffff0000, v74
	v_or_b32_sdwa v75, v75, v76 dst_sel:DWORD dst_unused:UNUSED_PAD src0_sel:DWORD src1_sel:WORD_1
	v_mul_f32_e32 v76, 0xbfb8aa3b, v70
	v_or_b32_sdwa v74, v74, v77 dst_sel:DWORD dst_unused:UNUSED_PAD src0_sel:DWORD src1_sel:WORD_1
	v_exp_f32_e32 v76, v76
	v_mul_f32_e32 v77, 0xbfb8aa3b, v71
	v_exp_f32_e32 v77, v77
	global_store_dwordx2 v[98:99], v[74:75], off offset:64
	v_add_f32_e32 v74, 1.0, v76
	v_mul_f32_e32 v76, 0xbfb8aa3b, v72
	v_add_f32_e32 v75, 1.0, v77
	v_exp_f32_e32 v77, v76
	v_mul_f32_e32 v76, 0xbfb8aa3b, v73
	v_exp_f32_e32 v78, v76
	v_rcp_f32_e32 v76, v75
	v_add_f32_e32 v75, 1.0, v77
	v_rcp_f32_e32 v74, v74
	v_add_f32_e32 v77, 1.0, v78
	v_rcp_f32_e32 v75, v75
	v_rcp_f32_e32 v77, v77
	v_mov_b32_e32 v78, v70
	v_mov_b32_e32 v79, v72
	v_mov_b32_e32 v72, v71
	v_pk_mul_f32 v[74:75], v[78:79], v[74:75]
	v_mov_b32_e32 v79, v68
	v_pk_mul_f32 v[70:71], v[72:73], v[76:77]
	v_mov_b32_e32 v68, v67
	v_mov_b32_e32 v78, v66
	v_pk_mul_f32 v[66:67], v[68:69], v[70:71]
	v_pk_mul_f32 v[74:75], v[78:79], v[74:75]
	v_and_b32_sdwa v70, v67, v177 dst_sel:DWORD dst_unused:UNUSED_PAD src0_sel:WORD_1 src1_sel:DWORD
	v_and_b32_sdwa v71, v66, v177 dst_sel:DWORD dst_unused:UNUSED_PAD src0_sel:WORD_1 src1_sel:DWORD
	v_and_b32_sdwa v68, v75, v177 dst_sel:DWORD dst_unused:UNUSED_PAD src0_sel:WORD_1 src1_sel:DWORD
	v_and_b32_sdwa v69, v74, v177 dst_sel:DWORD dst_unused:UNUSED_PAD src0_sel:WORD_1 src1_sel:DWORD
	v_add3_u32 v67, v67, v70, s28
	v_add3_u32 v66, v66, v71, s28
	v_add3_u32 v69, v74, v69, s28
	v_add3_u32 v68, v75, v68, s28
	v_and_b32_e32 v67, 0xffff0000, v67
	v_and_b32_e32 v66, 0xffff0000, v66
	v_or_b32_sdwa v67, v67, v68 dst_sel:DWORD dst_unused:UNUSED_PAD src0_sel:DWORD src1_sel:WORD_1
	v_or_b32_sdwa v66, v66, v69 dst_sel:DWORD dst_unused:UNUSED_PAD src0_sel:DWORD src1_sel:WORD_1
	global_store_dwordx2 v[98:99], v[66:67], off offset:96
	v_mul_f32_e32 v67, 0xbfb8aa3b, v62
	v_exp_f32_e32 v68, v67
	v_mul_f32_e32 v67, 0xbfb8aa3b, v63
	v_mul_f32_e32 v70, 0xbfb8aa3b, v64
	v_exp_f32_e32 v69, v67
	v_exp_f32_e32 v71, v70
	v_mul_f32_e32 v70, 0xbfb8aa3b, v65
	v_exp_f32_e32 v72, v70
	v_add_f32_e32 v69, 1.0, v69
	v_add_f32_e32 v68, 1.0, v68
	v_rcp_f32_e32 v70, v69
	v_add_f32_e32 v69, 1.0, v71
	v_add_f32_e32 v71, 1.0, v72
	v_rcp_f32_e32 v68, v68
	v_rcp_f32_e32 v69, v69
	v_rcp_f32_e32 v71, v71
	v_mov_b32_e32 v72, v62
	v_mov_b32_e32 v73, v64
	v_mov_b32_e32 v64, v63
	v_pk_mul_f32 v[68:69], v[72:73], v[68:69]
	v_mov_b32_e32 v73, v60
	v_pk_mul_f32 v[62:63], v[64:65], v[70:71]
	v_mov_b32_e32 v60, v59
	v_mov_b32_e32 v72, v58
	v_pk_mul_f32 v[58:59], v[60:61], v[62:63]
	v_pk_mul_f32 v[68:69], v[72:73], v[68:69]
	v_and_b32_sdwa v62, v59, v177 dst_sel:DWORD dst_unused:UNUSED_PAD src0_sel:WORD_1 src1_sel:DWORD
	v_and_b32_sdwa v60, v69, v177 dst_sel:DWORD dst_unused:UNUSED_PAD src0_sel:WORD_1 src1_sel:DWORD
	v_and_b32_sdwa v63, v58, v177 dst_sel:DWORD dst_unused:UNUSED_PAD src0_sel:WORD_1 src1_sel:DWORD
	v_add3_u32 v59, v59, v62, s28
	v_and_b32_sdwa v61, v68, v177 dst_sel:DWORD dst_unused:UNUSED_PAD src0_sel:WORD_1 src1_sel:DWORD
	v_add3_u32 v60, v69, v60, s28
	v_add3_u32 v58, v58, v63, s28
	v_and_b32_e32 v59, 0xffff0000, v59
	v_add3_u32 v61, v68, v61, s28
	v_and_b32_e32 v58, 0xffff0000, v58
	v_or_b32_sdwa v59, v59, v60 dst_sel:DWORD dst_unused:UNUSED_PAD src0_sel:DWORD src1_sel:WORD_1
	v_mul_f32_e32 v60, 0xbfb8aa3b, v54
	v_or_b32_sdwa v58, v58, v61 dst_sel:DWORD dst_unused:UNUSED_PAD src0_sel:DWORD src1_sel:WORD_1
	v_exp_f32_e32 v60, v60
	v_mul_f32_e32 v61, 0xbfb8aa3b, v55
	v_or_b32_e32 v66, 32, v110
	v_exp_f32_e32 v61, v61
	v_mad_i64_i32 v[66:67], s[6:7], v66, s52, v[106:107]
	v_lshl_add_u64 v[66:67], v[66:67], 0, v[108:109]
	global_store_dwordx2 v[66:67], v[58:59], off
	v_add_f32_e32 v58, 1.0, v60
	v_mul_f32_e32 v60, 0xbfb8aa3b, v56
	v_add_f32_e32 v59, 1.0, v61
	v_exp_f32_e32 v61, v60
	v_mul_f32_e32 v60, 0xbfb8aa3b, v57
	v_exp_f32_e32 v62, v60
	v_rcp_f32_e32 v60, v59
	v_add_f32_e32 v59, 1.0, v61
	v_rcp_f32_e32 v58, v58
	v_add_f32_e32 v61, 1.0, v62
	v_rcp_f32_e32 v59, v59
	v_rcp_f32_e32 v61, v61
	v_mov_b32_e32 v62, v54
	v_mov_b32_e32 v63, v56
	v_mov_b32_e32 v56, v55
	v_pk_mul_f32 v[58:59], v[62:63], v[58:59]
	v_mov_b32_e32 v63, v52
	v_pk_mul_f32 v[54:55], v[56:57], v[60:61]
	v_mov_b32_e32 v52, v51
	v_mov_b32_e32 v62, v50
	v_pk_mul_f32 v[50:51], v[52:53], v[54:55]
	v_pk_mul_f32 v[58:59], v[62:63], v[58:59]
	v_and_b32_sdwa v54, v51, v177 dst_sel:DWORD dst_unused:UNUSED_PAD src0_sel:WORD_1 src1_sel:DWORD
	v_and_b32_sdwa v52, v59, v177 dst_sel:DWORD dst_unused:UNUSED_PAD src0_sel:WORD_1 src1_sel:DWORD
	v_and_b32_sdwa v55, v50, v177 dst_sel:DWORD dst_unused:UNUSED_PAD src0_sel:WORD_1 src1_sel:DWORD
	v_add3_u32 v51, v51, v54, s28
	v_and_b32_sdwa v53, v58, v177 dst_sel:DWORD dst_unused:UNUSED_PAD src0_sel:WORD_1 src1_sel:DWORD
	v_add3_u32 v52, v59, v52, s28
	v_add3_u32 v50, v50, v55, s28
	v_and_b32_e32 v51, 0xffff0000, v51
	v_add3_u32 v53, v58, v53, s28
	v_and_b32_e32 v50, 0xffff0000, v50
	v_or_b32_sdwa v51, v51, v52 dst_sel:DWORD dst_unused:UNUSED_PAD src0_sel:DWORD src1_sel:WORD_1
	v_mul_f32_e32 v52, 0xbfb8aa3b, v46
	v_or_b32_sdwa v50, v50, v53 dst_sel:DWORD dst_unused:UNUSED_PAD src0_sel:DWORD src1_sel:WORD_1
	v_exp_f32_e32 v52, v52
	v_mul_f32_e32 v53, 0xbfb8aa3b, v47
	v_exp_f32_e32 v53, v53
	global_store_dwordx2 v[66:67], v[50:51], off offset:32
	v_add_f32_e32 v50, 1.0, v52
	v_mul_f32_e32 v52, 0xbfb8aa3b, v48
	v_add_f32_e32 v51, 1.0, v53
	v_exp_f32_e32 v53, v52
	v_mul_f32_e32 v52, 0xbfb8aa3b, v49
	v_exp_f32_e32 v54, v52
	v_rcp_f32_e32 v52, v51
	v_add_f32_e32 v51, 1.0, v53
	v_rcp_f32_e32 v50, v50
	v_add_f32_e32 v53, 1.0, v54
	v_rcp_f32_e32 v51, v51
	v_rcp_f32_e32 v53, v53
	v_mov_b32_e32 v54, v46
	v_mov_b32_e32 v55, v48
	v_mov_b32_e32 v48, v47
	v_pk_mul_f32 v[50:51], v[54:55], v[50:51]
	v_mov_b32_e32 v55, v44
	v_pk_mul_f32 v[46:47], v[48:49], v[52:53]
	v_mov_b32_e32 v44, v43
	v_mov_b32_e32 v54, v42
	v_pk_mul_f32 v[42:43], v[44:45], v[46:47]
	v_pk_mul_f32 v[50:51], v[54:55], v[50:51]
	v_and_b32_sdwa v46, v43, v177 dst_sel:DWORD dst_unused:UNUSED_PAD src0_sel:WORD_1 src1_sel:DWORD
	v_and_b32_sdwa v44, v51, v177 dst_sel:DWORD dst_unused:UNUSED_PAD src0_sel:WORD_1 src1_sel:DWORD
	v_and_b32_sdwa v47, v42, v177 dst_sel:DWORD dst_unused:UNUSED_PAD src0_sel:WORD_1 src1_sel:DWORD
	v_add3_u32 v43, v43, v46, s28
	v_and_b32_sdwa v45, v50, v177 dst_sel:DWORD dst_unused:UNUSED_PAD src0_sel:WORD_1 src1_sel:DWORD
	v_add3_u32 v44, v51, v44, s28
	v_add3_u32 v42, v42, v47, s28
	v_and_b32_e32 v43, 0xffff0000, v43
	v_add3_u32 v45, v50, v45, s28
	v_and_b32_e32 v42, 0xffff0000, v42
	v_or_b32_sdwa v43, v43, v44 dst_sel:DWORD dst_unused:UNUSED_PAD src0_sel:DWORD src1_sel:WORD_1
	v_mul_f32_e32 v44, 0xbfb8aa3b, v38
	v_or_b32_sdwa v42, v42, v45 dst_sel:DWORD dst_unused:UNUSED_PAD src0_sel:DWORD src1_sel:WORD_1
	v_exp_f32_e32 v44, v44
	v_mul_f32_e32 v45, 0xbfb8aa3b, v39
	v_exp_f32_e32 v45, v45
	global_store_dwordx2 v[66:67], v[42:43], off offset:64
	v_add_f32_e32 v42, 1.0, v44
	v_mul_f32_e32 v44, 0xbfb8aa3b, v40
	v_add_f32_e32 v43, 1.0, v45
	v_exp_f32_e32 v45, v44
	v_mul_f32_e32 v44, 0xbfb8aa3b, v41
	v_exp_f32_e32 v46, v44
	v_rcp_f32_e32 v44, v43
	v_add_f32_e32 v43, 1.0, v45
	v_rcp_f32_e32 v42, v42
	v_add_f32_e32 v45, 1.0, v46
	v_rcp_f32_e32 v43, v43
	v_rcp_f32_e32 v45, v45
	v_mov_b32_e32 v46, v38
	v_mov_b32_e32 v47, v40
	v_mov_b32_e32 v40, v39
	v_pk_mul_f32 v[42:43], v[46:47], v[42:43]
	v_mov_b32_e32 v47, v36
	v_pk_mul_f32 v[38:39], v[40:41], v[44:45]
	v_mov_b32_e32 v36, v35
	v_mov_b32_e32 v46, v34
	v_pk_mul_f32 v[34:35], v[36:37], v[38:39]
	v_pk_mul_f32 v[42:43], v[46:47], v[42:43]
	v_and_b32_sdwa v38, v35, v177 dst_sel:DWORD dst_unused:UNUSED_PAD src0_sel:WORD_1 src1_sel:DWORD
	v_and_b32_sdwa v39, v34, v177 dst_sel:DWORD dst_unused:UNUSED_PAD src0_sel:WORD_1 src1_sel:DWORD
	v_and_b32_sdwa v36, v43, v177 dst_sel:DWORD dst_unused:UNUSED_PAD src0_sel:WORD_1 src1_sel:DWORD
	v_and_b32_sdwa v37, v42, v177 dst_sel:DWORD dst_unused:UNUSED_PAD src0_sel:WORD_1 src1_sel:DWORD
	v_add3_u32 v35, v35, v38, s28
	v_add3_u32 v34, v34, v39, s28
	v_add3_u32 v37, v42, v37, s28
	v_add3_u32 v36, v43, v36, s28
	v_and_b32_e32 v35, 0xffff0000, v35
	v_and_b32_e32 v34, 0xffff0000, v34
	v_or_b32_sdwa v35, v35, v36 dst_sel:DWORD dst_unused:UNUSED_PAD src0_sel:DWORD src1_sel:WORD_1
	v_or_b32_sdwa v34, v34, v37 dst_sel:DWORD dst_unused:UNUSED_PAD src0_sel:DWORD src1_sel:WORD_1
	global_store_dwordx2 v[66:67], v[34:35], off offset:96
	v_mul_f32_e32 v35, 0xbfb8aa3b, v30
	v_exp_f32_e32 v36, v35
	v_mul_f32_e32 v35, 0xbfb8aa3b, v31
	v_mul_f32_e32 v38, 0xbfb8aa3b, v32
	v_exp_f32_e32 v37, v35
	v_exp_f32_e32 v39, v38
	v_mul_f32_e32 v38, 0xbfb8aa3b, v33
	v_exp_f32_e32 v40, v38
	v_add_f32_e32 v37, 1.0, v37
	v_add_f32_e32 v36, 1.0, v36
	v_rcp_f32_e32 v38, v37
	v_add_f32_e32 v37, 1.0, v39
	v_add_f32_e32 v39, 1.0, v40
	v_rcp_f32_e32 v36, v36
	v_rcp_f32_e32 v37, v37
	v_rcp_f32_e32 v39, v39
	v_mov_b32_e32 v40, v30
	v_mov_b32_e32 v41, v32
	v_mov_b32_e32 v32, v31
	v_pk_mul_f32 v[36:37], v[40:41], v[36:37]
	v_mov_b32_e32 v41, v28
	v_pk_mul_f32 v[30:31], v[32:33], v[38:39]
	v_mov_b32_e32 v28, v27
	v_mov_b32_e32 v40, v26
	v_pk_mul_f32 v[26:27], v[28:29], v[30:31]
	v_pk_mul_f32 v[36:37], v[40:41], v[36:37]
	v_and_b32_sdwa v30, v27, v177 dst_sel:DWORD dst_unused:UNUSED_PAD src0_sel:WORD_1 src1_sel:DWORD
	v_and_b32_sdwa v28, v37, v177 dst_sel:DWORD dst_unused:UNUSED_PAD src0_sel:WORD_1 src1_sel:DWORD
	v_and_b32_sdwa v31, v26, v177 dst_sel:DWORD dst_unused:UNUSED_PAD src0_sel:WORD_1 src1_sel:DWORD
	v_add3_u32 v27, v27, v30, s28
	v_and_b32_sdwa v29, v36, v177 dst_sel:DWORD dst_unused:UNUSED_PAD src0_sel:WORD_1 src1_sel:DWORD
	v_add3_u32 v28, v37, v28, s28
	v_add3_u32 v26, v26, v31, s28
	v_and_b32_e32 v27, 0xffff0000, v27
	v_add3_u32 v29, v36, v29, s28
	v_and_b32_e32 v26, 0xffff0000, v26
	v_or_b32_sdwa v27, v27, v28 dst_sel:DWORD dst_unused:UNUSED_PAD src0_sel:DWORD src1_sel:WORD_1
	v_mul_f32_e32 v28, 0xbfb8aa3b, v22
	v_or_b32_sdwa v26, v26, v29 dst_sel:DWORD dst_unused:UNUSED_PAD src0_sel:DWORD src1_sel:WORD_1
	v_exp_f32_e32 v28, v28
	v_mul_f32_e32 v29, 0xbfb8aa3b, v23
	v_or_b32_e32 v34, 48, v110
	v_exp_f32_e32 v29, v29
	v_mad_i64_i32 v[34:35], s[6:7], v34, s52, v[106:107]
	v_lshl_add_u64 v[34:35], v[34:35], 0, v[108:109]
	global_store_dwordx2 v[34:35], v[26:27], off
	v_add_f32_e32 v26, 1.0, v28
	v_mul_f32_e32 v28, 0xbfb8aa3b, v24
	v_add_f32_e32 v27, 1.0, v29
	v_exp_f32_e32 v29, v28
	v_mul_f32_e32 v28, 0xbfb8aa3b, v25
	v_exp_f32_e32 v30, v28
	v_rcp_f32_e32 v28, v27
	v_add_f32_e32 v27, 1.0, v29
	v_rcp_f32_e32 v26, v26
	v_add_f32_e32 v29, 1.0, v30
	v_rcp_f32_e32 v27, v27
	v_rcp_f32_e32 v29, v29
	v_mov_b32_e32 v30, v22
	v_mov_b32_e32 v31, v24
	v_mov_b32_e32 v24, v23
	v_pk_mul_f32 v[26:27], v[30:31], v[26:27]
	v_mov_b32_e32 v31, v20
	v_pk_mul_f32 v[22:23], v[24:25], v[28:29]
	v_mov_b32_e32 v20, v19
	v_mov_b32_e32 v30, v18
	v_pk_mul_f32 v[18:19], v[20:21], v[22:23]
	v_pk_mul_f32 v[26:27], v[30:31], v[26:27]
	v_and_b32_sdwa v22, v19, v177 dst_sel:DWORD dst_unused:UNUSED_PAD src0_sel:WORD_1 src1_sel:DWORD
	v_and_b32_sdwa v20, v27, v177 dst_sel:DWORD dst_unused:UNUSED_PAD src0_sel:WORD_1 src1_sel:DWORD
	v_and_b32_sdwa v23, v18, v177 dst_sel:DWORD dst_unused:UNUSED_PAD src0_sel:WORD_1 src1_sel:DWORD
	v_add3_u32 v19, v19, v22, s28
	v_and_b32_sdwa v21, v26, v177 dst_sel:DWORD dst_unused:UNUSED_PAD src0_sel:WORD_1 src1_sel:DWORD
	v_add3_u32 v20, v27, v20, s28
	v_add3_u32 v18, v18, v23, s28
	v_and_b32_e32 v19, 0xffff0000, v19
	v_add3_u32 v21, v26, v21, s28
	v_and_b32_e32 v18, 0xffff0000, v18
	v_or_b32_sdwa v19, v19, v20 dst_sel:DWORD dst_unused:UNUSED_PAD src0_sel:DWORD src1_sel:WORD_1
	v_mul_f32_e32 v20, 0xbfb8aa3b, v14
	v_or_b32_sdwa v18, v18, v21 dst_sel:DWORD dst_unused:UNUSED_PAD src0_sel:DWORD src1_sel:WORD_1
	v_exp_f32_e32 v20, v20
	v_mul_f32_e32 v21, 0xbfb8aa3b, v15
	v_exp_f32_e32 v21, v21
	global_store_dwordx2 v[34:35], v[18:19], off offset:32
	v_add_f32_e32 v18, 1.0, v20
	v_mul_f32_e32 v20, 0xbfb8aa3b, v16
	v_add_f32_e32 v19, 1.0, v21
	v_exp_f32_e32 v21, v20
	v_mul_f32_e32 v20, 0xbfb8aa3b, v17
	v_exp_f32_e32 v22, v20
	v_rcp_f32_e32 v20, v19
	v_add_f32_e32 v19, 1.0, v21
	v_rcp_f32_e32 v18, v18
	v_add_f32_e32 v21, 1.0, v22
	v_rcp_f32_e32 v19, v19
	v_rcp_f32_e32 v21, v21
	v_mov_b32_e32 v22, v14
	v_mov_b32_e32 v23, v16
	v_mov_b32_e32 v16, v15
	v_pk_mul_f32 v[18:19], v[22:23], v[18:19]
	v_mov_b32_e32 v23, v12
	v_pk_mul_f32 v[14:15], v[16:17], v[20:21]
	v_mov_b32_e32 v12, v11
	v_mov_b32_e32 v22, v10
	v_pk_mul_f32 v[10:11], v[12:13], v[14:15]
	v_pk_mul_f32 v[18:19], v[22:23], v[18:19]
	v_and_b32_sdwa v14, v11, v177 dst_sel:DWORD dst_unused:UNUSED_PAD src0_sel:WORD_1 src1_sel:DWORD
	v_and_b32_sdwa v12, v19, v177 dst_sel:DWORD dst_unused:UNUSED_PAD src0_sel:WORD_1 src1_sel:DWORD
	v_and_b32_sdwa v15, v10, v177 dst_sel:DWORD dst_unused:UNUSED_PAD src0_sel:WORD_1 src1_sel:DWORD
	v_add3_u32 v11, v11, v14, s28
	v_and_b32_sdwa v13, v18, v177 dst_sel:DWORD dst_unused:UNUSED_PAD src0_sel:WORD_1 src1_sel:DWORD
	v_add3_u32 v12, v19, v12, s28
	v_add3_u32 v10, v10, v15, s28
	v_and_b32_e32 v11, 0xffff0000, v11
	v_add3_u32 v13, v18, v13, s28
	v_and_b32_e32 v10, 0xffff0000, v10
	v_or_b32_sdwa v11, v11, v12 dst_sel:DWORD dst_unused:UNUSED_PAD src0_sel:DWORD src1_sel:WORD_1
	v_mul_f32_e32 v12, 0xbfb8aa3b, v6
	v_or_b32_sdwa v10, v10, v13 dst_sel:DWORD dst_unused:UNUSED_PAD src0_sel:DWORD src1_sel:WORD_1
	v_exp_f32_e32 v12, v12
	v_mul_f32_e32 v13, 0xbfb8aa3b, v7
	v_exp_f32_e32 v13, v13
	global_store_dwordx2 v[34:35], v[10:11], off offset:64
	v_add_f32_e32 v10, 1.0, v12
	v_mul_f32_e32 v12, 0xbfb8aa3b, v8
	v_add_f32_e32 v11, 1.0, v13
	v_exp_f32_e32 v13, v12
	v_mul_f32_e32 v12, 0xbfb8aa3b, v9
	v_exp_f32_e32 v14, v12
	v_rcp_f32_e32 v12, v11
	v_add_f32_e32 v11, 1.0, v13
	v_rcp_f32_e32 v10, v10
	v_add_f32_e32 v13, 1.0, v14
	v_rcp_f32_e32 v11, v11
	v_rcp_f32_e32 v13, v13
	v_mov_b32_e32 v14, v6
	v_mov_b32_e32 v15, v8
	v_mov_b32_e32 v8, v7
	v_pk_mul_f32 v[10:11], v[14:15], v[10:11]
	v_mov_b32_e32 v15, v4
	v_pk_mul_f32 v[6:7], v[8:9], v[12:13]
	v_mov_b32_e32 v4, v3
	v_mov_b32_e32 v14, v2
	v_pk_mul_f32 v[2:3], v[4:5], v[6:7]
	v_pk_mul_f32 v[10:11], v[14:15], v[10:11]
	v_and_b32_sdwa v6, v3, v177 dst_sel:DWORD dst_unused:UNUSED_PAD src0_sel:WORD_1 src1_sel:DWORD
	v_and_b32_sdwa v7, v2, v177 dst_sel:DWORD dst_unused:UNUSED_PAD src0_sel:WORD_1 src1_sel:DWORD
	v_and_b32_sdwa v4, v11, v177 dst_sel:DWORD dst_unused:UNUSED_PAD src0_sel:WORD_1 src1_sel:DWORD
	v_and_b32_sdwa v5, v10, v177 dst_sel:DWORD dst_unused:UNUSED_PAD src0_sel:WORD_1 src1_sel:DWORD
	v_add3_u32 v3, v3, v6, s28
	v_add3_u32 v2, v2, v7, s28
	v_add3_u32 v5, v10, v5, s28
	v_add3_u32 v4, v11, v4, s28
	v_and_b32_e32 v3, 0xffff0000, v3
	v_and_b32_e32 v2, 0xffff0000, v2
	s_add_i32 s14, s14, s11
	v_or_b32_sdwa v3, v3, v4 dst_sel:DWORD dst_unused:UNUSED_PAD src0_sel:DWORD src1_sel:WORD_1
	v_or_b32_sdwa v2, v2, v5 dst_sel:DWORD dst_unused:UNUSED_PAD src0_sel:DWORD src1_sel:WORD_1
	s_cmpk_gt_i32 s14, 0x4ff
	global_store_dwordx2 v[34:35], v[2:3], off offset:96
	s_cbranch_scc0 .LBB0_1440

.LBB0_1462:
	s_bitcmp1_b32 s4, 0
	s_cselect_b32 s2, 0x12000, 0
	v_or_b32_e32 v218, s2, v206
	v_add_u32_e32 v214, v218, v0
	v_add_u32_e32 v246, v218, v167
	ds_read_b128 v[184:187], v214
	ds_read_b128 v[198:201], v214 offset:2048
	ds_read_b128 v[210:213], v214 offset:4096
	ds_read_b128 v[214:217], v214 offset:6144
	ds_read_b128 v[218:221], v246 offset:32768
	ds_read_b128 v[222:225], v246 offset:34816
	ds_read_b128 v[226:229], v246 offset:36864
	ds_read_b128 v[230:233], v246 offset:38912
	ds_read_b128 v[234:237], v246 offset:40960
	ds_read_b128 v[238:241], v246 offset:43008
	ds_read_b128 v[242:245], v246 offset:45056
	ds_read_b128 v[246:249], v246 offset:47104
	s_add_i32 s10, s4, 1
	s_bitcmp1_b32 s10, 0
	s_cselect_b32 s3, 0x12000, 0
	v_add_u32_e32 v171, s3, v166
	v_xor_b32_e32 v169, 64, v206
	v_add3_u32 v169, s2, v167, v169
	s_waitcnt lgkmcnt(7)
	v_mfma_f32_16x16x32_bf16 v[158:161], v[218:221], v[184:187], v[158:161]
	v_mfma_f32_16x16x32_bf16 v[94:97], v[218:221], v[198:201], v[94:97]
	v_mfma_f32_16x16x32_bf16 v[62:65], v[218:221], v[210:213], v[62:65]
	v_mfma_f32_16x16x32_bf16 v[30:33], v[218:221], v[214:217], v[30:33]
	ds_read_b128 v[218:221], v169 offset:32768
	s_waitcnt lgkmcnt(7)
	v_mfma_f32_16x16x32_bf16 v[154:157], v[222:225], v[184:187], v[154:157]
	v_mfma_f32_16x16x32_bf16 v[90:93], v[222:225], v[198:201], v[90:93]
	v_mfma_f32_16x16x32_bf16 v[58:61], v[222:225], v[210:213], v[58:61]
	v_mfma_f32_16x16x32_bf16 v[26:29], v[222:225], v[214:217], v[26:29]
	ds_read_b128 v[222:225], v169 offset:34816
	s_waitcnt lgkmcnt(7)
	v_mfma_f32_16x16x32_bf16 v[150:153], v[226:229], v[184:187], v[150:153]
	v_mfma_f32_16x16x32_bf16 v[86:89], v[226:229], v[198:201], v[86:89]
	v_mfma_f32_16x16x32_bf16 v[54:57], v[226:229], v[210:213], v[54:57]
	v_mfma_f32_16x16x32_bf16 v[22:25], v[226:229], v[214:217], v[22:25]
	ds_read_b128 v[226:229], v169 offset:36864
	s_waitcnt lgkmcnt(7)
	v_mfma_f32_16x16x32_bf16 v[146:149], v[230:233], v[184:187], v[146:149]
	v_mfma_f32_16x16x32_bf16 v[82:85], v[230:233], v[198:201], v[82:85]
	v_mfma_f32_16x16x32_bf16 v[50:53], v[230:233], v[210:213], v[50:53]
	v_mfma_f32_16x16x32_bf16 v[18:21], v[230:233], v[214:217], v[18:21]
	ds_read_b128 v[230:233], v169 offset:38912
	s_waitcnt lgkmcnt(7)
	v_mfma_f32_16x16x32_bf16 v[142:145], v[234:237], v[184:187], v[142:145]
	v_mfma_f32_16x16x32_bf16 v[78:81], v[234:237], v[198:201], v[78:81]
	v_mfma_f32_16x16x32_bf16 v[46:49], v[234:237], v[210:213], v[46:49]
	v_mfma_f32_16x16x32_bf16 v[14:17], v[234:237], v[214:217], v[14:17]
	ds_read_b128 v[234:237], v169 offset:40960
	s_waitcnt lgkmcnt(7)
	v_mfma_f32_16x16x32_bf16 v[138:141], v[238:241], v[184:187], v[138:141]
	v_mfma_f32_16x16x32_bf16 v[74:77], v[238:241], v[198:201], v[74:77]
	v_mfma_f32_16x16x32_bf16 v[42:45], v[238:241], v[210:213], v[42:45]
	v_mfma_f32_16x16x32_bf16 v[10:13], v[238:241], v[214:217], v[10:13]
	ds_read_b128 v[238:241], v169 offset:43008
	s_waitcnt lgkmcnt(7)
	v_mfma_f32_16x16x32_bf16 v[102:105], v[242:245], v[184:187], v[102:105]
	v_mfma_f32_16x16x32_bf16 v[70:73], v[242:245], v[198:201], v[70:73]
	v_mfma_f32_16x16x32_bf16 v[38:41], v[242:245], v[210:213], v[38:41]
	v_mfma_f32_16x16x32_bf16 v[6:9], v[242:245], v[214:217], v[6:9]
	ds_read_b128 v[242:245], v169 offset:45056
	s_waitcnt lgkmcnt(7)
	v_mfma_f32_16x16x32_bf16 v[98:101], v[246:249], v[184:187], v[98:101]
	v_mfma_f32_16x16x32_bf16 v[66:69], v[246:249], v[198:201], v[66:69]
	v_xor_b32_e32 v169, 64, v206
	v_add3_u32 v169, s2, v0, v169
	ds_read_b128 v[184:187], v169
	ds_read_b128 v[198:201], v169 offset:2048
	v_mfma_f32_16x16x32_bf16 v[34:37], v[246:249], v[210:213], v[34:37]
	ds_read_b128 v[210:213], v169 offset:4096
	v_mfma_f32_16x16x32_bf16 v[2:5], v[246:249], v[214:217], v[2:5]
	ds_read_b128 v[214:217], v169 offset:6144
	v_xor_b32_e32 v169, 64, v206
	v_add3_u32 v169, s2, v167, v169
	ds_read_b128 v[246:249], v169 offset:47104
	s_waitcnt lgkmcnt(1)
	v_mfma_f32_16x16x32_bf16 v[158:161], v[218:221], v[184:187], v[158:161]
	v_mfma_f32_16x16x32_bf16 v[94:97], v[218:221], v[198:201], v[94:97]
	v_mfma_f32_16x16x32_bf16 v[62:65], v[218:221], v[210:213], v[62:65]
	v_mfma_f32_16x16x32_bf16 v[30:33], v[218:221], v[214:217], v[30:33]
	s_waitcnt vmcnt(7)
	ds_write_b128 v171, v[114:117]
	v_mfma_f32_16x16x32_bf16 v[154:157], v[222:225], v[184:187], v[154:157]
	v_mfma_f32_16x16x32_bf16 v[90:93], v[222:225], v[198:201], v[90:93]
	global_load_dwordx4 v[114:117], v168, vcc offset:256
	v_mfma_f32_16x16x32_bf16 v[58:61], v[222:225], v[210:213], v[58:61]
	v_mfma_f32_16x16x32_bf16 v[26:29], v[222:225], v[214:217], v[26:29]
	s_waitcnt vmcnt(7)
	ds_write_b128 v171, v[106:109] offset:8192
	v_mfma_f32_16x16x32_bf16 v[150:153], v[226:229], v[184:187], v[150:153]
	v_mfma_f32_16x16x32_bf16 v[86:89], v[226:229], v[198:201], v[86:89]
	v_add_u32_e32 v106, s34, v168
	global_load_dwordx4 v[106:109], v106, vcc offset:256
	v_mfma_f32_16x16x32_bf16 v[54:57], v[226:229], v[210:213], v[54:57]
	v_mfma_f32_16x16x32_bf16 v[22:25], v[226:229], v[214:217], v[22:25]
	s_waitcnt vmcnt(7)
	ds_write_b128 v171, v[110:113] offset:16384
	v_mfma_f32_16x16x32_bf16 v[146:149], v[230:233], v[184:187], v[146:149]
	v_mfma_f32_16x16x32_bf16 v[82:85], v[230:233], v[198:201], v[82:85]
	v_add_u32_e32 v110, s35, v168
	global_load_dwordx4 v[110:113], v110, vcc offset:256
	v_mfma_f32_16x16x32_bf16 v[50:53], v[230:233], v[210:213], v[50:53]
	v_mfma_f32_16x16x32_bf16 v[18:21], v[230:233], v[214:217], v[18:21]
	s_waitcnt vmcnt(7)
	ds_write_b128 v171, v[126:129] offset:24576
	v_mfma_f32_16x16x32_bf16 v[142:145], v[234:237], v[184:187], v[142:145]
	v_mfma_f32_16x16x32_bf16 v[78:81], v[234:237], v[198:201], v[78:81]
	v_add_u32_e32 v126, s36, v168
	global_load_dwordx4 v[126:129], v126, vcc offset:256
	v_mfma_f32_16x16x32_bf16 v[46:49], v[234:237], v[210:213], v[46:49]
	v_mfma_f32_16x16x32_bf16 v[14:17], v[234:237], v[214:217], v[14:17]
	s_waitcnt vmcnt(7)
	ds_write_b128 v171, v[122:125] offset:32768
	v_mfma_f32_16x16x32_bf16 v[138:141], v[238:241], v[184:187], v[138:141]
	v_mfma_f32_16x16x32_bf16 v[74:77], v[238:241], v[198:201], v[74:77]
	global_load_dwordx4 v[122:125], v170, s[100:101] offset:256
	v_mfma_f32_16x16x32_bf16 v[42:45], v[238:241], v[210:213], v[42:45]
	v_mfma_f32_16x16x32_bf16 v[10:13], v[238:241], v[214:217], v[10:13]
	s_waitcnt vmcnt(7)
	ds_write_b128 v171, v[118:121] offset:40960
	v_mfma_f32_16x16x32_bf16 v[102:105], v[242:245], v[184:187], v[102:105]
	v_mfma_f32_16x16x32_bf16 v[70:73], v[242:245], v[198:201], v[70:73]
	v_add_u32_e32 v118, s34, v170
	global_load_dwordx4 v[118:121], v118, s[100:101] offset:256
	v_mfma_f32_16x16x32_bf16 v[38:41], v[242:245], v[210:213], v[38:41]
	v_mfma_f32_16x16x32_bf16 v[6:9], v[242:245], v[214:217], v[6:9]
	s_waitcnt vmcnt(7)
	ds_write_b128 v171, v[134:137] offset:49152
	s_waitcnt lgkmcnt(7)
	v_mfma_f32_16x16x32_bf16 v[98:101], v[246:249], v[184:187], v[98:101]
	v_mfma_f32_16x16x32_bf16 v[66:69], v[246:249], v[198:201], v[66:69]
	v_add_u32_e32 v134, s35, v170
	global_load_dwordx4 v[134:137], v134, s[100:101] offset:256
	v_mfma_f32_16x16x32_bf16 v[34:37], v[246:249], v[210:213], v[34:37]
	v_mfma_f32_16x16x32_bf16 v[2:5], v[246:249], v[214:217], v[2:5]
	s_waitcnt vmcnt(7)
	ds_write_b128 v171, v[130:133] offset:57344
	v_add_u32_e32 v130, s36, v170
	global_load_dwordx4 v[130:133], v130, s[100:101] offset:256
	v_add_u32_e32 v168, 0x80, v168
	v_add_u32_e32 v170, 0x80, v170
	s_waitcnt lgkmcnt(0)
	s_barrier
	s_cmp_eq_u32 s10, 16
	s_mov_b32 s4, s10
	s_cbranch_scc0 .LBB0_1462
	s_waitcnt vmcnt(4)
	v_mul_f32_e32 v109, 0xbfb8aa3b, v158
	v_exp_f32_e32 v109, v109
	s_waitcnt vmcnt(3)
	v_mul_f32_e32 v111, 0xbfb8aa3b, v159
	v_exp_f32_e32 v111, v111
	v_mul_f32_e32 v115, 0xbfb8aa3b, v161
	v_add_f32_e32 v109, 1.0, v109
	v_rcp_f32_e32 v114, v109
	v_add_f32_e32 v109, 1.0, v111
	v_mul_f32_e32 v111, 0xbfb8aa3b, v160
	v_exp_f32_e32 v111, v111
	v_exp_f32_e32 v117, v115
	v_rcp_f32_e32 v116, v109
	s_waitcnt vmcnt(2)
	v_mov_b32_e32 v118, v158
	v_add_f32_e32 v109, 1.0, v111
	v_rcp_f32_e32 v115, v109
	v_add_f32_e32 v109, 1.0, v117
	v_rcp_f32_e32 v117, v109
	v_mov_b32_e32 v119, v160
	v_pk_mul_f32 v[114:115], v[118:119], v[114:115]
	v_mov_b32_e32 v118, v154
	v_mov_b32_e32 v119, v156
	v_mov_b32_e32 v160, v159
	v_pk_mul_f32 v[114:115], v[118:119], v[114:115]
	v_pk_mul_f32 v[116:117], v[160:161], v[116:117]
	v_mov_b32_e32 v156, v155
	v_pk_mul_f32 v[116:117], v[156:157], v[116:117]
	v_and_b32_sdwa v111, v115, v177 dst_sel:DWORD dst_unused:UNUSED_PAD src0_sel:WORD_1 src1_sel:DWORD
	v_and_b32_sdwa v118, v114, v177 dst_sel:DWORD dst_unused:UNUSED_PAD src0_sel:WORD_1 src1_sel:DWORD
	v_add3_u32 v111, v115, v111, s28
	v_and_b32_sdwa v115, v117, v177 dst_sel:DWORD dst_unused:UNUSED_PAD src0_sel:WORD_1 src1_sel:DWORD
	v_add3_u32 v114, v114, v118, s28
	v_and_b32_sdwa v118, v116, v177 dst_sel:DWORD dst_unused:UNUSED_PAD src0_sel:WORD_1 src1_sel:DWORD
	v_add3_u32 v115, v117, v115, s28
	v_or_b32_e32 v106, s7, v207
	v_add3_u32 v116, v116, v118, s28
	v_and_b32_e32 v115, 0xffff0000, v115
	v_ashrrev_i32_e32 v106, 1, v106
	v_and_b32_e32 v116, 0xffff0000, v116
	v_or_b32_sdwa v115, v115, v111 dst_sel:DWORD dst_unused:UNUSED_PAD src0_sel:DWORD src1_sel:WORD_1
	v_mul_f32_e32 v111, 0xbfb8aa3b, v150
	v_or_b32_e32 v108, v106, v208
	v_or_b32_sdwa v114, v116, v114 dst_sel:DWORD dst_unused:UNUSED_PAD src0_sel:DWORD src1_sel:WORD_1
	v_exp_f32_e32 v111, v111
	v_mul_f32_e32 v116, 0xbfb8aa3b, v151
	v_add_u32_e32 v110, s6, v205
	v_mov_b64_e32 v[106:107], s[12:13]
	v_ashrrev_i32_e32 v109, 31, v108
	v_exp_f32_e32 v116, v116
	v_mad_i64_i32 v[112:113], s[6:7], v110, s52, v[106:107]
	v_lshlrev_b64 v[108:109], 1, v[108:109]
	v_lshl_add_u64 v[112:113], v[112:113], 0, v[108:109]
	s_waitcnt vmcnt(0)
	global_store_dwordx2 v[112:113], v[114:115], off
	v_add_f32_e32 v111, 1.0, v111
	v_mul_f32_e32 v115, 0xbfb8aa3b, v152
	v_rcp_f32_e32 v114, v111
	v_add_f32_e32 v111, 1.0, v116
	v_exp_f32_e32 v115, v115
	v_mul_f32_e32 v116, 0xbfb8aa3b, v153
	v_exp_f32_e32 v117, v116
	v_rcp_f32_e32 v116, v111
	v_add_f32_e32 v111, 1.0, v115
	v_rcp_f32_e32 v115, v111
	v_add_f32_e32 v111, 1.0, v117
	v_rcp_f32_e32 v117, v111
	v_mov_b32_e32 v118, v150
	v_mov_b32_e32 v119, v152
	v_pk_mul_f32 v[114:115], v[118:119], v[114:115]
	v_mov_b32_e32 v118, v146
	v_mov_b32_e32 v119, v148
	v_mov_b32_e32 v152, v151
	v_pk_mul_f32 v[114:115], v[118:119], v[114:115]
	v_pk_mul_f32 v[116:117], v[152:153], v[116:117]
	v_mov_b32_e32 v148, v147
	v_pk_mul_f32 v[116:117], v[148:149], v[116:117]
	v_and_b32_sdwa v111, v115, v177 dst_sel:DWORD dst_unused:UNUSED_PAD src0_sel:WORD_1 src1_sel:DWORD
	v_and_b32_sdwa v118, v114, v177 dst_sel:DWORD dst_unused:UNUSED_PAD src0_sel:WORD_1 src1_sel:DWORD
	v_add3_u32 v111, v115, v111, s28
	v_and_b32_sdwa v115, v117, v177 dst_sel:DWORD dst_unused:UNUSED_PAD src0_sel:WORD_1 src1_sel:DWORD
	v_add3_u32 v114, v114, v118, s28
	v_and_b32_sdwa v118, v116, v177 dst_sel:DWORD dst_unused:UNUSED_PAD src0_sel:WORD_1 src1_sel:DWORD
	v_add3_u32 v115, v117, v115, s28
	v_add3_u32 v116, v116, v118, s28
	v_and_b32_e32 v115, 0xffff0000, v115
	v_and_b32_e32 v116, 0xffff0000, v116
	v_or_b32_sdwa v115, v115, v111 dst_sel:DWORD dst_unused:UNUSED_PAD src0_sel:DWORD src1_sel:WORD_1
	v_mul_f32_e32 v111, 0xbfb8aa3b, v142
	v_or_b32_sdwa v114, v116, v114 dst_sel:DWORD dst_unused:UNUSED_PAD src0_sel:DWORD src1_sel:WORD_1
	v_exp_f32_e32 v111, v111
	v_mul_f32_e32 v116, 0xbfb8aa3b, v143
	v_exp_f32_e32 v116, v116
	global_store_dwordx2 v[112:113], v[114:115], off offset:32
	v_add_f32_e32 v111, 1.0, v111
	v_mul_f32_e32 v115, 0xbfb8aa3b, v144
	v_rcp_f32_e32 v114, v111
	v_add_f32_e32 v111, 1.0, v116
	v_exp_f32_e32 v115, v115
	v_mul_f32_e32 v116, 0xbfb8aa3b, v145
	v_exp_f32_e32 v117, v116
	v_rcp_f32_e32 v116, v111
	v_add_f32_e32 v111, 1.0, v115
	v_rcp_f32_e32 v115, v111
	v_add_f32_e32 v111, 1.0, v117
	v_rcp_f32_e32 v117, v111
	v_mov_b32_e32 v118, v142
	v_mov_b32_e32 v119, v144
	v_pk_mul_f32 v[114:115], v[118:119], v[114:115]
	v_mov_b32_e32 v118, v138
	v_mov_b32_e32 v119, v140
	v_mov_b32_e32 v144, v143
	v_pk_mul_f32 v[114:115], v[118:119], v[114:115]
	v_pk_mul_f32 v[116:117], v[144:145], v[116:117]
	v_mov_b32_e32 v140, v139
	v_pk_mul_f32 v[116:117], v[140:141], v[116:117]
	v_and_b32_sdwa v111, v115, v177 dst_sel:DWORD dst_unused:UNUSED_PAD src0_sel:WORD_1 src1_sel:DWORD
	v_and_b32_sdwa v118, v114, v177 dst_sel:DWORD dst_unused:UNUSED_PAD src0_sel:WORD_1 src1_sel:DWORD
	v_add3_u32 v111, v115, v111, s28
	v_and_b32_sdwa v115, v117, v177 dst_sel:DWORD dst_unused:UNUSED_PAD src0_sel:WORD_1 src1_sel:DWORD
	v_add3_u32 v114, v114, v118, s28
	v_and_b32_sdwa v118, v116, v177 dst_sel:DWORD dst_unused:UNUSED_PAD src0_sel:WORD_1 src1_sel:DWORD
	v_add3_u32 v115, v117, v115, s28
	v_add3_u32 v116, v116, v118, s28
	v_and_b32_e32 v115, 0xffff0000, v115
	v_and_b32_e32 v116, 0xffff0000, v116
	v_or_b32_sdwa v115, v115, v111 dst_sel:DWORD dst_unused:UNUSED_PAD src0_sel:DWORD src1_sel:WORD_1
	v_mul_f32_e32 v111, 0xbfb8aa3b, v102
	v_or_b32_sdwa v114, v116, v114 dst_sel:DWORD dst_unused:UNUSED_PAD src0_sel:DWORD src1_sel:WORD_1
	v_exp_f32_e32 v111, v111
	v_mul_f32_e32 v116, 0xbfb8aa3b, v103
	v_exp_f32_e32 v116, v116
	global_store_dwordx2 v[112:113], v[114:115], off offset:64
	v_add_f32_e32 v111, 1.0, v111
	v_mul_f32_e32 v115, 0xbfb8aa3b, v104
	v_rcp_f32_e32 v114, v111
	v_add_f32_e32 v111, 1.0, v116
	v_exp_f32_e32 v115, v115
	v_mul_f32_e32 v116, 0xbfb8aa3b, v105
	v_exp_f32_e32 v117, v116
	v_rcp_f32_e32 v116, v111
	v_add_f32_e32 v111, 1.0, v115
	v_rcp_f32_e32 v115, v111
	v_add_f32_e32 v111, 1.0, v117
	v_rcp_f32_e32 v117, v111
	v_mov_b32_e32 v118, v102
	v_mov_b32_e32 v119, v104
	v_mov_b32_e32 v104, v103
	v_pk_mul_f32 v[114:115], v[118:119], v[114:115]
	v_mov_b32_e32 v119, v100
	v_pk_mul_f32 v[102:103], v[104:105], v[116:117]
	v_mov_b32_e32 v100, v99
	v_mov_b32_e32 v118, v98
	v_pk_mul_f32 v[98:99], v[100:101], v[102:103]
	v_pk_mul_f32 v[114:115], v[118:119], v[114:115]
	v_and_b32_sdwa v102, v99, v177 dst_sel:DWORD dst_unused:UNUSED_PAD src0_sel:WORD_1 src1_sel:DWORD
	v_and_b32_sdwa v103, v98, v177 dst_sel:DWORD dst_unused:UNUSED_PAD src0_sel:WORD_1 src1_sel:DWORD
	v_and_b32_sdwa v100, v115, v177 dst_sel:DWORD dst_unused:UNUSED_PAD src0_sel:WORD_1 src1_sel:DWORD
	v_and_b32_sdwa v101, v114, v177 dst_sel:DWORD dst_unused:UNUSED_PAD src0_sel:WORD_1 src1_sel:DWORD
	v_add3_u32 v99, v99, v102, s28
	v_add3_u32 v98, v98, v103, s28
	v_add3_u32 v101, v114, v101, s28
	v_add3_u32 v100, v115, v100, s28
	v_and_b32_e32 v99, 0xffff0000, v99
	v_and_b32_e32 v98, 0xffff0000, v98
	v_or_b32_sdwa v99, v99, v100 dst_sel:DWORD dst_unused:UNUSED_PAD src0_sel:DWORD src1_sel:WORD_1
	v_or_b32_sdwa v98, v98, v101 dst_sel:DWORD dst_unused:UNUSED_PAD src0_sel:DWORD src1_sel:WORD_1
	global_store_dwordx2 v[112:113], v[98:99], off offset:96
	v_mul_f32_e32 v99, 0xbfb8aa3b, v94
	v_exp_f32_e32 v100, v99
	v_mul_f32_e32 v99, 0xbfb8aa3b, v95
	v_mul_f32_e32 v102, 0xbfb8aa3b, v96
	v_exp_f32_e32 v101, v99
	v_exp_f32_e32 v103, v102
	v_mul_f32_e32 v102, 0xbfb8aa3b, v97
	v_exp_f32_e32 v104, v102
	v_add_f32_e32 v101, 1.0, v101
	v_add_f32_e32 v100, 1.0, v100
	v_rcp_f32_e32 v102, v101
	v_add_f32_e32 v101, 1.0, v103
	v_add_f32_e32 v103, 1.0, v104
	v_rcp_f32_e32 v100, v100
	v_rcp_f32_e32 v101, v101
	v_rcp_f32_e32 v103, v103
	v_mov_b32_e32 v104, v94
	v_mov_b32_e32 v105, v96
	v_mov_b32_e32 v96, v95
	v_pk_mul_f32 v[100:101], v[104:105], v[100:101]
	v_mov_b32_e32 v105, v92
	v_pk_mul_f32 v[94:95], v[96:97], v[102:103]
	v_mov_b32_e32 v92, v91
	v_mov_b32_e32 v104, v90
	v_pk_mul_f32 v[90:91], v[92:93], v[94:95]
	v_pk_mul_f32 v[100:101], v[104:105], v[100:101]
	v_and_b32_sdwa v94, v91, v177 dst_sel:DWORD dst_unused:UNUSED_PAD src0_sel:WORD_1 src1_sel:DWORD
	v_and_b32_sdwa v92, v101, v177 dst_sel:DWORD dst_unused:UNUSED_PAD src0_sel:WORD_1 src1_sel:DWORD
	v_and_b32_sdwa v95, v90, v177 dst_sel:DWORD dst_unused:UNUSED_PAD src0_sel:WORD_1 src1_sel:DWORD
	v_add3_u32 v91, v91, v94, s28
	v_and_b32_sdwa v93, v100, v177 dst_sel:DWORD dst_unused:UNUSED_PAD src0_sel:WORD_1 src1_sel:DWORD
	v_add3_u32 v92, v101, v92, s28
	v_add3_u32 v90, v90, v95, s28
	v_and_b32_e32 v91, 0xffff0000, v91
	v_add3_u32 v93, v100, v93, s28
	v_and_b32_e32 v90, 0xffff0000, v90
	v_or_b32_sdwa v91, v91, v92 dst_sel:DWORD dst_unused:UNUSED_PAD src0_sel:DWORD src1_sel:WORD_1
	v_mul_f32_e32 v92, 0xbfb8aa3b, v86
	v_or_b32_sdwa v90, v90, v93 dst_sel:DWORD dst_unused:UNUSED_PAD src0_sel:DWORD src1_sel:WORD_1
	v_exp_f32_e32 v92, v92
	v_mul_f32_e32 v93, 0xbfb8aa3b, v87
	v_or_b32_e32 v98, 16, v110
	v_exp_f32_e32 v93, v93
	v_mad_i64_i32 v[98:99], s[6:7], v98, s52, v[106:107]
	v_lshl_add_u64 v[98:99], v[98:99], 0, v[108:109]
	global_store_dwordx2 v[98:99], v[90:91], off
	v_add_f32_e32 v90, 1.0, v92
	v_mul_f32_e32 v92, 0xbfb8aa3b, v88
	v_add_f32_e32 v91, 1.0, v93
	v_exp_f32_e32 v93, v92
	v_mul_f32_e32 v92, 0xbfb8aa3b, v89
	v_exp_f32_e32 v94, v92
	v_rcp_f32_e32 v92, v91
	v_add_f32_e32 v91, 1.0, v93
	v_rcp_f32_e32 v90, v90
	v_add_f32_e32 v93, 1.0, v94
	v_rcp_f32_e32 v91, v91
	v_rcp_f32_e32 v93, v93
	v_mov_b32_e32 v94, v86
	v_mov_b32_e32 v95, v88
	v_mov_b32_e32 v88, v87
	v_pk_mul_f32 v[90:91], v[94:95], v[90:91]
	v_mov_b32_e32 v95, v84
	v_pk_mul_f32 v[86:87], v[88:89], v[92:93]
	v_mov_b32_e32 v84, v83
	v_mov_b32_e32 v94, v82
	v_pk_mul_f32 v[82:83], v[84:85], v[86:87]
	v_pk_mul_f32 v[90:91], v[94:95], v[90:91]
	v_and_b32_sdwa v86, v83, v177 dst_sel:DWORD dst_unused:UNUSED_PAD src0_sel:WORD_1 src1_sel:DWORD
	v_and_b32_sdwa v84, v91, v177 dst_sel:DWORD dst_unused:UNUSED_PAD src0_sel:WORD_1 src1_sel:DWORD
	v_and_b32_sdwa v87, v82, v177 dst_sel:DWORD dst_unused:UNUSED_PAD src0_sel:WORD_1 src1_sel:DWORD
	v_add3_u32 v83, v83, v86, s28
	v_and_b32_sdwa v85, v90, v177 dst_sel:DWORD dst_unused:UNUSED_PAD src0_sel:WORD_1 src1_sel:DWORD
	v_add3_u32 v84, v91, v84, s28
	v_add3_u32 v82, v82, v87, s28
	v_and_b32_e32 v83, 0xffff0000, v83
	v_add3_u32 v85, v90, v85, s28
	v_and_b32_e32 v82, 0xffff0000, v82
	v_or_b32_sdwa v83, v83, v84 dst_sel:DWORD dst_unused:UNUSED_PAD src0_sel:DWORD src1_sel:WORD_1
	v_mul_f32_e32 v84, 0xbfb8aa3b, v78
	v_or_b32_sdwa v82, v82, v85 dst_sel:DWORD dst_unused:UNUSED_PAD src0_sel:DWORD src1_sel:WORD_1
	v_exp_f32_e32 v84, v84
	v_mul_f32_e32 v85, 0xbfb8aa3b, v79
	v_exp_f32_e32 v85, v85
	global_store_dwordx2 v[98:99], v[82:83], off offset:32
	v_add_f32_e32 v82, 1.0, v84
	v_mul_f32_e32 v84, 0xbfb8aa3b, v80
	v_add_f32_e32 v83, 1.0, v85
	v_exp_f32_e32 v85, v84
	v_mul_f32_e32 v84, 0xbfb8aa3b, v81
	v_exp_f32_e32 v86, v84
	v_rcp_f32_e32 v84, v83
	v_add_f32_e32 v83, 1.0, v85
	v_rcp_f32_e32 v82, v82
	v_add_f32_e32 v85, 1.0, v86
	v_rcp_f32_e32 v83, v83
	v_rcp_f32_e32 v85, v85
	v_mov_b32_e32 v86, v78
	v_mov_b32_e32 v87, v80
	v_mov_b32_e32 v80, v79
	v_pk_mul_f32 v[82:83], v[86:87], v[82:83]
	v_mov_b32_e32 v87, v76
	v_pk_mul_f32 v[78:79], v[80:81], v[84:85]
	v_mov_b32_e32 v76, v75
	v_mov_b32_e32 v86, v74
	v_pk_mul_f32 v[74:75], v[76:77], v[78:79]
	v_pk_mul_f32 v[82:83], v[86:87], v[82:83]
	v_and_b32_sdwa v78, v75, v177 dst_sel:DWORD dst_unused:UNUSED_PAD src0_sel:WORD_1 src1_sel:DWORD
	v_and_b32_sdwa v76, v83, v177 dst_sel:DWORD dst_unused:UNUSED_PAD src0_sel:WORD_1 src1_sel:DWORD
	v_and_b32_sdwa v79, v74, v177 dst_sel:DWORD dst_unused:UNUSED_PAD src0_sel:WORD_1 src1_sel:DWORD
	v_add3_u32 v75, v75, v78, s28
	v_and_b32_sdwa v77, v82, v177 dst_sel:DWORD dst_unused:UNUSED_PAD src0_sel:WORD_1 src1_sel:DWORD
	v_add3_u32 v76, v83, v76, s28
	v_add3_u32 v74, v74, v79, s28
	v_and_b32_e32 v75, 0xffff0000, v75
	v_add3_u32 v77, v82, v77, s28
	v_and_b32_e32 v74, 0xffff0000, v74
	v_or_b32_sdwa v75, v75, v76 dst_sel:DWORD dst_unused:UNUSED_PAD src0_sel:DWORD src1_sel:WORD_1
	v_mul_f32_e32 v76, 0xbfb8aa3b, v70
	v_or_b32_sdwa v74, v74, v77 dst_sel:DWORD dst_unused:UNUSED_PAD src0_sel:DWORD src1_sel:WORD_1
	v_exp_f32_e32 v76, v76
	v_mul_f32_e32 v77, 0xbfb8aa3b, v71
	v_exp_f32_e32 v77, v77
	global_store_dwordx2 v[98:99], v[74:75], off offset:64
	v_add_f32_e32 v74, 1.0, v76
	v_mul_f32_e32 v76, 0xbfb8aa3b, v72
	v_add_f32_e32 v75, 1.0, v77
	v_exp_f32_e32 v77, v76
	v_mul_f32_e32 v76, 0xbfb8aa3b, v73
	v_exp_f32_e32 v78, v76
	v_rcp_f32_e32 v76, v75
	v_add_f32_e32 v75, 1.0, v77
	v_rcp_f32_e32 v74, v74
	v_add_f32_e32 v77, 1.0, v78
	v_rcp_f32_e32 v75, v75
	v_rcp_f32_e32 v77, v77
	v_mov_b32_e32 v78, v70
	v_mov_b32_e32 v79, v72
	v_mov_b32_e32 v72, v71
	v_pk_mul_f32 v[74:75], v[78:79], v[74:75]
	v_mov_b32_e32 v79, v68
	v_pk_mul_f32 v[70:71], v[72:73], v[76:77]
	v_mov_b32_e32 v68, v67
	v_mov_b32_e32 v78, v66
	v_pk_mul_f32 v[66:67], v[68:69], v[70:71]
	v_pk_mul_f32 v[74:75], v[78:79], v[74:75]
	v_and_b32_sdwa v70, v67, v177 dst_sel:DWORD dst_unused:UNUSED_PAD src0_sel:WORD_1 src1_sel:DWORD
	v_and_b32_sdwa v71, v66, v177 dst_sel:DWORD dst_unused:UNUSED_PAD src0_sel:WORD_1 src1_sel:DWORD
	v_and_b32_sdwa v68, v75, v177 dst_sel:DWORD dst_unused:UNUSED_PAD src0_sel:WORD_1 src1_sel:DWORD
	v_and_b32_sdwa v69, v74, v177 dst_sel:DWORD dst_unused:UNUSED_PAD src0_sel:WORD_1 src1_sel:DWORD
	v_add3_u32 v67, v67, v70, s28
	v_add3_u32 v66, v66, v71, s28
	v_add3_u32 v69, v74, v69, s28
	v_add3_u32 v68, v75, v68, s28
	v_and_b32_e32 v67, 0xffff0000, v67
	v_and_b32_e32 v66, 0xffff0000, v66
	v_or_b32_sdwa v67, v67, v68 dst_sel:DWORD dst_unused:UNUSED_PAD src0_sel:DWORD src1_sel:WORD_1
	v_or_b32_sdwa v66, v66, v69 dst_sel:DWORD dst_unused:UNUSED_PAD src0_sel:DWORD src1_sel:WORD_1
	global_store_dwordx2 v[98:99], v[66:67], off offset:96
	v_mul_f32_e32 v67, 0xbfb8aa3b, v62
	v_exp_f32_e32 v68, v67
	v_mul_f32_e32 v67, 0xbfb8aa3b, v63
	v_mul_f32_e32 v70, 0xbfb8aa3b, v64
	v_exp_f32_e32 v69, v67
	v_exp_f32_e32 v71, v70
	v_mul_f32_e32 v70, 0xbfb8aa3b, v65
	v_exp_f32_e32 v72, v70
	v_add_f32_e32 v69, 1.0, v69
	v_add_f32_e32 v68, 1.0, v68
	v_rcp_f32_e32 v70, v69
	v_add_f32_e32 v69, 1.0, v71
	v_add_f32_e32 v71, 1.0, v72
	v_rcp_f32_e32 v68, v68
	v_rcp_f32_e32 v69, v69
	v_rcp_f32_e32 v71, v71
	v_mov_b32_e32 v72, v62
	v_mov_b32_e32 v73, v64
	v_mov_b32_e32 v64, v63
	v_pk_mul_f32 v[68:69], v[72:73], v[68:69]
	v_mov_b32_e32 v73, v60
	v_pk_mul_f32 v[62:63], v[64:65], v[70:71]
	v_mov_b32_e32 v60, v59
	v_mov_b32_e32 v72, v58
	v_pk_mul_f32 v[58:59], v[60:61], v[62:63]
	v_pk_mul_f32 v[68:69], v[72:73], v[68:69]
	v_and_b32_sdwa v62, v59, v177 dst_sel:DWORD dst_unused:UNUSED_PAD src0_sel:WORD_1 src1_sel:DWORD
	v_and_b32_sdwa v60, v69, v177 dst_sel:DWORD dst_unused:UNUSED_PAD src0_sel:WORD_1 src1_sel:DWORD
	v_and_b32_sdwa v63, v58, v177 dst_sel:DWORD dst_unused:UNUSED_PAD src0_sel:WORD_1 src1_sel:DWORD
	v_add3_u32 v59, v59, v62, s28
	v_and_b32_sdwa v61, v68, v177 dst_sel:DWORD dst_unused:UNUSED_PAD src0_sel:WORD_1 src1_sel:DWORD
	v_add3_u32 v60, v69, v60, s28
	v_add3_u32 v58, v58, v63, s28
	v_and_b32_e32 v59, 0xffff0000, v59
	v_add3_u32 v61, v68, v61, s28
	v_and_b32_e32 v58, 0xffff0000, v58
	v_or_b32_sdwa v59, v59, v60 dst_sel:DWORD dst_unused:UNUSED_PAD src0_sel:DWORD src1_sel:WORD_1
	v_mul_f32_e32 v60, 0xbfb8aa3b, v54
	v_or_b32_sdwa v58, v58, v61 dst_sel:DWORD dst_unused:UNUSED_PAD src0_sel:DWORD src1_sel:WORD_1
	v_exp_f32_e32 v60, v60
	v_mul_f32_e32 v61, 0xbfb8aa3b, v55
	v_or_b32_e32 v66, 32, v110
	v_exp_f32_e32 v61, v61
	v_mad_i64_i32 v[66:67], s[6:7], v66, s52, v[106:107]
	v_lshl_add_u64 v[66:67], v[66:67], 0, v[108:109]
	global_store_dwordx2 v[66:67], v[58:59], off
	v_add_f32_e32 v58, 1.0, v60
	v_mul_f32_e32 v60, 0xbfb8aa3b, v56
	v_add_f32_e32 v59, 1.0, v61
	v_exp_f32_e32 v61, v60
	v_mul_f32_e32 v60, 0xbfb8aa3b, v57
	v_exp_f32_e32 v62, v60
	v_rcp_f32_e32 v60, v59
	v_add_f32_e32 v59, 1.0, v61
	v_rcp_f32_e32 v58, v58
	v_add_f32_e32 v61, 1.0, v62
	v_rcp_f32_e32 v59, v59
	v_rcp_f32_e32 v61, v61
	v_mov_b32_e32 v62, v54
	v_mov_b32_e32 v63, v56
	v_mov_b32_e32 v56, v55
	v_pk_mul_f32 v[58:59], v[62:63], v[58:59]
	v_mov_b32_e32 v63, v52
	v_pk_mul_f32 v[54:55], v[56:57], v[60:61]
	v_mov_b32_e32 v52, v51
	v_mov_b32_e32 v62, v50
	v_pk_mul_f32 v[50:51], v[52:53], v[54:55]
	v_pk_mul_f32 v[58:59], v[62:63], v[58:59]
	v_and_b32_sdwa v54, v51, v177 dst_sel:DWORD dst_unused:UNUSED_PAD src0_sel:WORD_1 src1_sel:DWORD
	v_and_b32_sdwa v52, v59, v177 dst_sel:DWORD dst_unused:UNUSED_PAD src0_sel:WORD_1 src1_sel:DWORD
	v_and_b32_sdwa v55, v50, v177 dst_sel:DWORD dst_unused:UNUSED_PAD src0_sel:WORD_1 src1_sel:DWORD
	v_add3_u32 v51, v51, v54, s28
	v_and_b32_sdwa v53, v58, v177 dst_sel:DWORD dst_unused:UNUSED_PAD src0_sel:WORD_1 src1_sel:DWORD
	v_add3_u32 v52, v59, v52, s28
	v_add3_u32 v50, v50, v55, s28
	v_and_b32_e32 v51, 0xffff0000, v51
	v_add3_u32 v53, v58, v53, s28
	v_and_b32_e32 v50, 0xffff0000, v50
	v_or_b32_sdwa v51, v51, v52 dst_sel:DWORD dst_unused:UNUSED_PAD src0_sel:DWORD src1_sel:WORD_1
	v_mul_f32_e32 v52, 0xbfb8aa3b, v46
	v_or_b32_sdwa v50, v50, v53 dst_sel:DWORD dst_unused:UNUSED_PAD src0_sel:DWORD src1_sel:WORD_1
	v_exp_f32_e32 v52, v52
	v_mul_f32_e32 v53, 0xbfb8aa3b, v47
	v_exp_f32_e32 v53, v53
	global_store_dwordx2 v[66:67], v[50:51], off offset:32
	v_add_f32_e32 v50, 1.0, v52
	v_mul_f32_e32 v52, 0xbfb8aa3b, v48
	v_add_f32_e32 v51, 1.0, v53
	v_exp_f32_e32 v53, v52
	v_mul_f32_e32 v52, 0xbfb8aa3b, v49
	v_exp_f32_e32 v54, v52
	v_rcp_f32_e32 v52, v51
	v_add_f32_e32 v51, 1.0, v53
	v_rcp_f32_e32 v50, v50
	v_add_f32_e32 v53, 1.0, v54
	v_rcp_f32_e32 v51, v51
	v_rcp_f32_e32 v53, v53
	v_mov_b32_e32 v54, v46
	v_mov_b32_e32 v55, v48
	v_mov_b32_e32 v48, v47
	v_pk_mul_f32 v[50:51], v[54:55], v[50:51]
	v_mov_b32_e32 v55, v44
	v_pk_mul_f32 v[46:47], v[48:49], v[52:53]
	v_mov_b32_e32 v44, v43
	v_mov_b32_e32 v54, v42
	v_pk_mul_f32 v[42:43], v[44:45], v[46:47]
	v_pk_mul_f32 v[50:51], v[54:55], v[50:51]
	v_and_b32_sdwa v46, v43, v177 dst_sel:DWORD dst_unused:UNUSED_PAD src0_sel:WORD_1 src1_sel:DWORD
	v_and_b32_sdwa v44, v51, v177 dst_sel:DWORD dst_unused:UNUSED_PAD src0_sel:WORD_1 src1_sel:DWORD
	v_and_b32_sdwa v47, v42, v177 dst_sel:DWORD dst_unused:UNUSED_PAD src0_sel:WORD_1 src1_sel:DWORD
	v_add3_u32 v43, v43, v46, s28
	v_and_b32_sdwa v45, v50, v177 dst_sel:DWORD dst_unused:UNUSED_PAD src0_sel:WORD_1 src1_sel:DWORD
	v_add3_u32 v44, v51, v44, s28
	v_add3_u32 v42, v42, v47, s28
	v_and_b32_e32 v43, 0xffff0000, v43
	v_add3_u32 v45, v50, v45, s28
	v_and_b32_e32 v42, 0xffff0000, v42
	v_or_b32_sdwa v43, v43, v44 dst_sel:DWORD dst_unused:UNUSED_PAD src0_sel:DWORD src1_sel:WORD_1
	v_mul_f32_e32 v44, 0xbfb8aa3b, v38
	v_or_b32_sdwa v42, v42, v45 dst_sel:DWORD dst_unused:UNUSED_PAD src0_sel:DWORD src1_sel:WORD_1
	v_exp_f32_e32 v44, v44
	v_mul_f32_e32 v45, 0xbfb8aa3b, v39
	v_exp_f32_e32 v45, v45
	global_store_dwordx2 v[66:67], v[42:43], off offset:64
	v_add_f32_e32 v42, 1.0, v44
	v_mul_f32_e32 v44, 0xbfb8aa3b, v40
	v_add_f32_e32 v43, 1.0, v45
	v_exp_f32_e32 v45, v44
	v_mul_f32_e32 v44, 0xbfb8aa3b, v41
	v_exp_f32_e32 v46, v44
	v_rcp_f32_e32 v44, v43
	v_add_f32_e32 v43, 1.0, v45
	v_rcp_f32_e32 v42, v42
	v_add_f32_e32 v45, 1.0, v46
	v_rcp_f32_e32 v43, v43
	v_rcp_f32_e32 v45, v45
	v_mov_b32_e32 v46, v38
	v_mov_b32_e32 v47, v40
	v_mov_b32_e32 v40, v39
	v_pk_mul_f32 v[42:43], v[46:47], v[42:43]
	v_mov_b32_e32 v47, v36
	v_pk_mul_f32 v[38:39], v[40:41], v[44:45]
	v_mov_b32_e32 v36, v35
	v_mov_b32_e32 v46, v34
	v_pk_mul_f32 v[34:35], v[36:37], v[38:39]
	v_pk_mul_f32 v[42:43], v[46:47], v[42:43]
	v_and_b32_sdwa v38, v35, v177 dst_sel:DWORD dst_unused:UNUSED_PAD src0_sel:WORD_1 src1_sel:DWORD
	v_and_b32_sdwa v39, v34, v177 dst_sel:DWORD dst_unused:UNUSED_PAD src0_sel:WORD_1 src1_sel:DWORD
	v_and_b32_sdwa v36, v43, v177 dst_sel:DWORD dst_unused:UNUSED_PAD src0_sel:WORD_1 src1_sel:DWORD
	v_and_b32_sdwa v37, v42, v177 dst_sel:DWORD dst_unused:UNUSED_PAD src0_sel:WORD_1 src1_sel:DWORD
	v_add3_u32 v35, v35, v38, s28
	v_add3_u32 v34, v34, v39, s28
	v_add3_u32 v37, v42, v37, s28
	v_add3_u32 v36, v43, v36, s28
	v_and_b32_e32 v35, 0xffff0000, v35
	v_and_b32_e32 v34, 0xffff0000, v34
	v_or_b32_sdwa v35, v35, v36 dst_sel:DWORD dst_unused:UNUSED_PAD src0_sel:DWORD src1_sel:WORD_1
	v_or_b32_sdwa v34, v34, v37 dst_sel:DWORD dst_unused:UNUSED_PAD src0_sel:DWORD src1_sel:WORD_1
	global_store_dwordx2 v[66:67], v[34:35], off offset:96
	v_mul_f32_e32 v35, 0xbfb8aa3b, v30
	v_exp_f32_e32 v36, v35
	v_mul_f32_e32 v35, 0xbfb8aa3b, v31
	v_mul_f32_e32 v38, 0xbfb8aa3b, v32
	v_exp_f32_e32 v37, v35
	v_exp_f32_e32 v39, v38
	v_mul_f32_e32 v38, 0xbfb8aa3b, v33
	v_exp_f32_e32 v40, v38
	v_add_f32_e32 v37, 1.0, v37
	v_add_f32_e32 v36, 1.0, v36
	v_rcp_f32_e32 v38, v37
	v_add_f32_e32 v37, 1.0, v39
	v_add_f32_e32 v39, 1.0, v40
	v_rcp_f32_e32 v36, v36
	v_rcp_f32_e32 v37, v37
	v_rcp_f32_e32 v39, v39
	v_mov_b32_e32 v40, v30
	v_mov_b32_e32 v41, v32
	v_mov_b32_e32 v32, v31
	v_pk_mul_f32 v[36:37], v[40:41], v[36:37]
	v_mov_b32_e32 v41, v28
	v_pk_mul_f32 v[30:31], v[32:33], v[38:39]
	v_mov_b32_e32 v28, v27
	v_mov_b32_e32 v40, v26
	v_pk_mul_f32 v[26:27], v[28:29], v[30:31]
	v_pk_mul_f32 v[36:37], v[40:41], v[36:37]
	v_and_b32_sdwa v30, v27, v177 dst_sel:DWORD dst_unused:UNUSED_PAD src0_sel:WORD_1 src1_sel:DWORD
	v_and_b32_sdwa v28, v37, v177 dst_sel:DWORD dst_unused:UNUSED_PAD src0_sel:WORD_1 src1_sel:DWORD
	v_and_b32_sdwa v31, v26, v177 dst_sel:DWORD dst_unused:UNUSED_PAD src0_sel:WORD_1 src1_sel:DWORD
	v_add3_u32 v27, v27, v30, s28
	v_and_b32_sdwa v29, v36, v177 dst_sel:DWORD dst_unused:UNUSED_PAD src0_sel:WORD_1 src1_sel:DWORD
	v_add3_u32 v28, v37, v28, s28
	v_add3_u32 v26, v26, v31, s28
	v_and_b32_e32 v27, 0xffff0000, v27
	v_add3_u32 v29, v36, v29, s28
	v_and_b32_e32 v26, 0xffff0000, v26
	v_or_b32_sdwa v27, v27, v28 dst_sel:DWORD dst_unused:UNUSED_PAD src0_sel:DWORD src1_sel:WORD_1
	v_mul_f32_e32 v28, 0xbfb8aa3b, v22
	v_or_b32_sdwa v26, v26, v29 dst_sel:DWORD dst_unused:UNUSED_PAD src0_sel:DWORD src1_sel:WORD_1
	v_exp_f32_e32 v28, v28
	v_mul_f32_e32 v29, 0xbfb8aa3b, v23
	v_or_b32_e32 v34, 48, v110
	v_exp_f32_e32 v29, v29
	v_mad_i64_i32 v[34:35], s[6:7], v34, s52, v[106:107]
	v_lshl_add_u64 v[34:35], v[34:35], 0, v[108:109]
	global_store_dwordx2 v[34:35], v[26:27], off
	v_add_f32_e32 v26, 1.0, v28
	v_mul_f32_e32 v28, 0xbfb8aa3b, v24
	v_add_f32_e32 v27, 1.0, v29
	v_exp_f32_e32 v29, v28
	v_mul_f32_e32 v28, 0xbfb8aa3b, v25
	v_exp_f32_e32 v30, v28
	v_rcp_f32_e32 v28, v27
	v_add_f32_e32 v27, 1.0, v29
	v_rcp_f32_e32 v26, v26
	v_add_f32_e32 v29, 1.0, v30
	v_rcp_f32_e32 v27, v27
	v_rcp_f32_e32 v29, v29
	v_mov_b32_e32 v30, v22
	v_mov_b32_e32 v31, v24
	v_mov_b32_e32 v24, v23
	v_pk_mul_f32 v[26:27], v[30:31], v[26:27]
	v_mov_b32_e32 v31, v20
	v_pk_mul_f32 v[22:23], v[24:25], v[28:29]
	v_mov_b32_e32 v20, v19
	v_mov_b32_e32 v30, v18
	v_pk_mul_f32 v[18:19], v[20:21], v[22:23]
	v_pk_mul_f32 v[26:27], v[30:31], v[26:27]
	v_and_b32_sdwa v22, v19, v177 dst_sel:DWORD dst_unused:UNUSED_PAD src0_sel:WORD_1 src1_sel:DWORD
	v_and_b32_sdwa v20, v27, v177 dst_sel:DWORD dst_unused:UNUSED_PAD src0_sel:WORD_1 src1_sel:DWORD
	v_and_b32_sdwa v23, v18, v177 dst_sel:DWORD dst_unused:UNUSED_PAD src0_sel:WORD_1 src1_sel:DWORD
	v_add3_u32 v19, v19, v22, s28
	v_and_b32_sdwa v21, v26, v177 dst_sel:DWORD dst_unused:UNUSED_PAD src0_sel:WORD_1 src1_sel:DWORD
	v_add3_u32 v20, v27, v20, s28
	v_add3_u32 v18, v18, v23, s28
	v_and_b32_e32 v19, 0xffff0000, v19
	v_add3_u32 v21, v26, v21, s28
	v_and_b32_e32 v18, 0xffff0000, v18
	v_or_b32_sdwa v19, v19, v20 dst_sel:DWORD dst_unused:UNUSED_PAD src0_sel:DWORD src1_sel:WORD_1
	v_mul_f32_e32 v20, 0xbfb8aa3b, v14
	v_or_b32_sdwa v18, v18, v21 dst_sel:DWORD dst_unused:UNUSED_PAD src0_sel:DWORD src1_sel:WORD_1
	v_exp_f32_e32 v20, v20
	v_mul_f32_e32 v21, 0xbfb8aa3b, v15
	v_exp_f32_e32 v21, v21
	global_store_dwordx2 v[34:35], v[18:19], off offset:32
	v_add_f32_e32 v18, 1.0, v20
	v_mul_f32_e32 v20, 0xbfb8aa3b, v16
	v_add_f32_e32 v19, 1.0, v21
	v_exp_f32_e32 v21, v20
	v_mul_f32_e32 v20, 0xbfb8aa3b, v17
	v_exp_f32_e32 v22, v20
	v_rcp_f32_e32 v20, v19
	v_add_f32_e32 v19, 1.0, v21
	v_rcp_f32_e32 v18, v18
	v_add_f32_e32 v21, 1.0, v22
	v_rcp_f32_e32 v19, v19
	v_rcp_f32_e32 v21, v21
	v_mov_b32_e32 v22, v14
	v_mov_b32_e32 v23, v16
	v_mov_b32_e32 v16, v15
	v_pk_mul_f32 v[18:19], v[22:23], v[18:19]
	v_mov_b32_e32 v23, v12
	v_pk_mul_f32 v[14:15], v[16:17], v[20:21]
	v_mov_b32_e32 v12, v11
	v_mov_b32_e32 v22, v10
	v_pk_mul_f32 v[10:11], v[12:13], v[14:15]
	v_pk_mul_f32 v[18:19], v[22:23], v[18:19]
	v_and_b32_sdwa v14, v11, v177 dst_sel:DWORD dst_unused:UNUSED_PAD src0_sel:WORD_1 src1_sel:DWORD
	v_and_b32_sdwa v12, v19, v177 dst_sel:DWORD dst_unused:UNUSED_PAD src0_sel:WORD_1 src1_sel:DWORD
	v_and_b32_sdwa v15, v10, v177 dst_sel:DWORD dst_unused:UNUSED_PAD src0_sel:WORD_1 src1_sel:DWORD
	v_add3_u32 v11, v11, v14, s28
	v_and_b32_sdwa v13, v18, v177 dst_sel:DWORD dst_unused:UNUSED_PAD src0_sel:WORD_1 src1_sel:DWORD
	v_add3_u32 v12, v19, v12, s28
	v_add3_u32 v10, v10, v15, s28
	v_and_b32_e32 v11, 0xffff0000, v11
	v_add3_u32 v13, v18, v13, s28
	v_and_b32_e32 v10, 0xffff0000, v10
	v_or_b32_sdwa v11, v11, v12 dst_sel:DWORD dst_unused:UNUSED_PAD src0_sel:DWORD src1_sel:WORD_1
	v_mul_f32_e32 v12, 0xbfb8aa3b, v6
	v_or_b32_sdwa v10, v10, v13 dst_sel:DWORD dst_unused:UNUSED_PAD src0_sel:DWORD src1_sel:WORD_1
	v_exp_f32_e32 v12, v12
	v_mul_f32_e32 v13, 0xbfb8aa3b, v7
	v_exp_f32_e32 v13, v13
	global_store_dwordx2 v[34:35], v[10:11], off offset:64
	v_add_f32_e32 v10, 1.0, v12
	v_mul_f32_e32 v12, 0xbfb8aa3b, v8
	v_add_f32_e32 v11, 1.0, v13
	v_exp_f32_e32 v13, v12
	v_mul_f32_e32 v12, 0xbfb8aa3b, v9
	v_exp_f32_e32 v14, v12
	v_rcp_f32_e32 v12, v11
	v_add_f32_e32 v11, 1.0, v13
	v_rcp_f32_e32 v10, v10
	v_add_f32_e32 v13, 1.0, v14
	v_rcp_f32_e32 v11, v11
	v_rcp_f32_e32 v13, v13
	v_mov_b32_e32 v14, v6
	v_mov_b32_e32 v15, v8
	v_mov_b32_e32 v8, v7
	v_pk_mul_f32 v[10:11], v[14:15], v[10:11]
	v_mov_b32_e32 v15, v4
	v_pk_mul_f32 v[6:7], v[8:9], v[12:13]
	v_mov_b32_e32 v4, v3
	v_mov_b32_e32 v14, v2
	v_pk_mul_f32 v[2:3], v[4:5], v[6:7]
	v_pk_mul_f32 v[10:11], v[14:15], v[10:11]
	v_and_b32_sdwa v6, v3, v177 dst_sel:DWORD dst_unused:UNUSED_PAD src0_sel:WORD_1 src1_sel:DWORD
	v_and_b32_sdwa v7, v2, v177 dst_sel:DWORD dst_unused:UNUSED_PAD src0_sel:WORD_1 src1_sel:DWORD
	v_and_b32_sdwa v4, v11, v177 dst_sel:DWORD dst_unused:UNUSED_PAD src0_sel:WORD_1 src1_sel:DWORD
	v_and_b32_sdwa v5, v10, v177 dst_sel:DWORD dst_unused:UNUSED_PAD src0_sel:WORD_1 src1_sel:DWORD
	v_add3_u32 v3, v3, v6, s28
	v_add3_u32 v2, v2, v7, s28
	v_add3_u32 v5, v10, v5, s28
	v_add3_u32 v4, v11, v4, s28
	v_and_b32_e32 v3, 0xffff0000, v3
	v_and_b32_e32 v2, 0xffff0000, v2
	s_add_i32 s14, s14, s11
	v_or_b32_sdwa v3, v3, v4 dst_sel:DWORD dst_unused:UNUSED_PAD src0_sel:DWORD src1_sel:WORD_1
	v_or_b32_sdwa v2, v2, v5 dst_sel:DWORD dst_unused:UNUSED_PAD src0_sel:DWORD src1_sel:WORD_1
	s_cmpk_gt_i32 s14, 0x5ff
	global_store_dwordx2 v[34:35], v[2:3], off offset:96
	s_cbranch_scc0 .LBB0_1461

.LBB0_1528:
	s_bitcmp1_b32 s4, 0
	s_cselect_b32 s2, 0x12000, 0
	v_or_b32_e32 v218, s2, v207
	v_add_u32_e32 v214, v218, v0
	v_add_u32_e32 v246, v218, v167
	ds_read_b128 v[184:187], v214
	ds_read_b128 v[198:201], v214 offset:2048
	ds_read_b128 v[210:213], v214 offset:4096
	ds_read_b128 v[214:217], v214 offset:6144
	ds_read_b128 v[218:221], v246 offset:32768
	ds_read_b128 v[222:225], v246 offset:34816
	ds_read_b128 v[226:229], v246 offset:36864
	ds_read_b128 v[230:233], v246 offset:38912
	ds_read_b128 v[234:237], v246 offset:40960
	ds_read_b128 v[238:241], v246 offset:43008
	ds_read_b128 v[242:245], v246 offset:45056
	ds_read_b128 v[246:249], v246 offset:47104
	s_add_i32 s10, s4, 1
	s_bitcmp1_b32 s10, 0
	s_cselect_b32 s3, 0x12000, 0
	v_add_u32_e32 v171, s3, v166
	v_xor_b32_e32 v169, 64, v207
	v_add3_u32 v169, s2, v167, v169
	s_waitcnt lgkmcnt(7)
	v_mfma_f32_16x16x32_bf16 v[158:161], v[218:221], v[184:187], v[158:161]
	v_mfma_f32_16x16x32_bf16 v[94:97], v[218:221], v[198:201], v[94:97]
	v_mfma_f32_16x16x32_bf16 v[62:65], v[218:221], v[210:213], v[62:65]
	v_mfma_f32_16x16x32_bf16 v[30:33], v[218:221], v[214:217], v[30:33]
	ds_read_b128 v[218:221], v169 offset:32768
	s_waitcnt lgkmcnt(7)
	v_mfma_f32_16x16x32_bf16 v[154:157], v[222:225], v[184:187], v[154:157]
	v_mfma_f32_16x16x32_bf16 v[90:93], v[222:225], v[198:201], v[90:93]
	v_mfma_f32_16x16x32_bf16 v[58:61], v[222:225], v[210:213], v[58:61]
	v_mfma_f32_16x16x32_bf16 v[26:29], v[222:225], v[214:217], v[26:29]
	ds_read_b128 v[222:225], v169 offset:34816
	s_waitcnt lgkmcnt(7)
	v_mfma_f32_16x16x32_bf16 v[150:153], v[226:229], v[184:187], v[150:153]
	v_mfma_f32_16x16x32_bf16 v[86:89], v[226:229], v[198:201], v[86:89]
	v_mfma_f32_16x16x32_bf16 v[54:57], v[226:229], v[210:213], v[54:57]
	v_mfma_f32_16x16x32_bf16 v[22:25], v[226:229], v[214:217], v[22:25]
	ds_read_b128 v[226:229], v169 offset:36864
	s_waitcnt lgkmcnt(7)
	v_mfma_f32_16x16x32_bf16 v[146:149], v[230:233], v[184:187], v[146:149]
	v_mfma_f32_16x16x32_bf16 v[82:85], v[230:233], v[198:201], v[82:85]
	v_mfma_f32_16x16x32_bf16 v[50:53], v[230:233], v[210:213], v[50:53]
	v_mfma_f32_16x16x32_bf16 v[18:21], v[230:233], v[214:217], v[18:21]
	ds_read_b128 v[230:233], v169 offset:38912
	s_waitcnt lgkmcnt(7)
	v_mfma_f32_16x16x32_bf16 v[134:137], v[234:237], v[184:187], v[134:137]
	v_mfma_f32_16x16x32_bf16 v[78:81], v[234:237], v[198:201], v[78:81]
	v_mfma_f32_16x16x32_bf16 v[46:49], v[234:237], v[210:213], v[46:49]
	v_mfma_f32_16x16x32_bf16 v[14:17], v[234:237], v[214:217], v[14:17]
	ds_read_b128 v[234:237], v169 offset:40960
	s_waitcnt lgkmcnt(7)
	v_mfma_f32_16x16x32_bf16 v[106:109], v[238:241], v[184:187], v[106:109]
	v_mfma_f32_16x16x32_bf16 v[74:77], v[238:241], v[198:201], v[74:77]
	v_mfma_f32_16x16x32_bf16 v[42:45], v[238:241], v[210:213], v[42:45]
	v_mfma_f32_16x16x32_bf16 v[10:13], v[238:241], v[214:217], v[10:13]
	ds_read_b128 v[238:241], v169 offset:43008
	s_waitcnt lgkmcnt(7)
	v_mfma_f32_16x16x32_bf16 v[102:105], v[242:245], v[184:187], v[102:105]
	v_mfma_f32_16x16x32_bf16 v[70:73], v[242:245], v[198:201], v[70:73]
	v_mfma_f32_16x16x32_bf16 v[38:41], v[242:245], v[210:213], v[38:41]
	v_mfma_f32_16x16x32_bf16 v[6:9], v[242:245], v[214:217], v[6:9]
	ds_read_b128 v[242:245], v169 offset:45056
	s_waitcnt lgkmcnt(7)
	v_mfma_f32_16x16x32_bf16 v[98:101], v[246:249], v[184:187], v[98:101]
	v_mfma_f32_16x16x32_bf16 v[66:69], v[246:249], v[198:201], v[66:69]
	v_xor_b32_e32 v169, 64, v207
	v_add3_u32 v169, s2, v0, v169
	ds_read_b128 v[184:187], v169
	ds_read_b128 v[198:201], v169 offset:2048
	v_mfma_f32_16x16x32_bf16 v[34:37], v[246:249], v[210:213], v[34:37]
	ds_read_b128 v[210:213], v169 offset:4096
	v_mfma_f32_16x16x32_bf16 v[2:5], v[246:249], v[214:217], v[2:5]
	ds_read_b128 v[214:217], v169 offset:6144
	v_xor_b32_e32 v169, 64, v207
	v_add3_u32 v169, s2, v167, v169
	ds_read_b128 v[246:249], v169 offset:47104
	s_waitcnt lgkmcnt(1)
	v_mfma_f32_16x16x32_bf16 v[158:161], v[218:221], v[184:187], v[158:161]
	v_mfma_f32_16x16x32_bf16 v[94:97], v[218:221], v[198:201], v[94:97]
	v_mfma_f32_16x16x32_bf16 v[62:65], v[218:221], v[210:213], v[62:65]
	v_mfma_f32_16x16x32_bf16 v[30:33], v[218:221], v[214:217], v[30:33]
	s_waitcnt vmcnt(7)
	ds_write_b128 v171, v[118:121]
	v_mfma_f32_16x16x32_bf16 v[154:157], v[222:225], v[184:187], v[154:157]
	v_mfma_f32_16x16x32_bf16 v[90:93], v[222:225], v[198:201], v[90:93]
	global_load_dwordx4 v[118:121], v168, vcc offset:256
	v_mfma_f32_16x16x32_bf16 v[58:61], v[222:225], v[210:213], v[58:61]
	v_mfma_f32_16x16x32_bf16 v[26:29], v[222:225], v[214:217], v[26:29]
	s_waitcnt vmcnt(7)
	ds_write_b128 v171, v[110:113] offset:8192
	v_mfma_f32_16x16x32_bf16 v[150:153], v[226:229], v[184:187], v[150:153]
	v_mfma_f32_16x16x32_bf16 v[86:89], v[226:229], v[198:201], v[86:89]
	v_add_u32_e32 v110, 0x58000, v168
	global_load_dwordx4 v[110:113], v110, vcc offset:256
	v_mfma_f32_16x16x32_bf16 v[54:57], v[226:229], v[210:213], v[54:57]
	v_mfma_f32_16x16x32_bf16 v[22:25], v[226:229], v[214:217], v[22:25]
	s_waitcnt vmcnt(7)
	ds_write_b128 v171, v[114:117] offset:16384
	v_mfma_f32_16x16x32_bf16 v[146:149], v[230:233], v[184:187], v[146:149]
	v_mfma_f32_16x16x32_bf16 v[82:85], v[230:233], v[198:201], v[82:85]
	v_add_u32_e32 v114, 0xb0000, v168
	global_load_dwordx4 v[114:117], v114, vcc offset:256
	v_mfma_f32_16x16x32_bf16 v[50:53], v[230:233], v[210:213], v[50:53]
	v_mfma_f32_16x16x32_bf16 v[18:21], v[230:233], v[214:217], v[18:21]
	s_waitcnt vmcnt(7)
	ds_write_b128 v171, v[130:133] offset:24576
	v_mfma_f32_16x16x32_bf16 v[134:137], v[234:237], v[184:187], v[134:137]
	v_mfma_f32_16x16x32_bf16 v[78:81], v[234:237], v[198:201], v[78:81]
	v_add_u32_e32 v130, 0x108000, v168
	global_load_dwordx4 v[130:133], v130, vcc offset:256
	v_mfma_f32_16x16x32_bf16 v[46:49], v[234:237], v[210:213], v[46:49]
	v_mfma_f32_16x16x32_bf16 v[14:17], v[234:237], v[214:217], v[14:17]
	s_waitcnt vmcnt(7)
	ds_write_b128 v171, v[126:129] offset:32768
	v_mfma_f32_16x16x32_bf16 v[106:109], v[238:241], v[184:187], v[106:109]
	v_mfma_f32_16x16x32_bf16 v[74:77], v[238:241], v[198:201], v[74:77]
	global_load_dwordx4 v[126:129], v170, s[100:101] offset:256
	v_mfma_f32_16x16x32_bf16 v[42:45], v[238:241], v[210:213], v[42:45]
	v_mfma_f32_16x16x32_bf16 v[10:13], v[238:241], v[214:217], v[10:13]
	s_waitcnt vmcnt(7)
	ds_write_b128 v171, v[122:125] offset:40960
	v_mfma_f32_16x16x32_bf16 v[102:105], v[242:245], v[184:187], v[102:105]
	v_mfma_f32_16x16x32_bf16 v[70:73], v[242:245], v[198:201], v[70:73]
	v_add_u32_e32 v122, 0x58000, v170
	global_load_dwordx4 v[122:125], v122, s[100:101] offset:256
	v_mfma_f32_16x16x32_bf16 v[38:41], v[242:245], v[210:213], v[38:41]
	v_mfma_f32_16x16x32_bf16 v[6:9], v[242:245], v[214:217], v[6:9]
	s_waitcnt vmcnt(7)
	ds_write_b128 v171, v[142:145] offset:49152
	s_waitcnt lgkmcnt(7)
	v_mfma_f32_16x16x32_bf16 v[98:101], v[246:249], v[184:187], v[98:101]
	v_mfma_f32_16x16x32_bf16 v[66:69], v[246:249], v[198:201], v[66:69]
	v_add_u32_e32 v142, 0xb0000, v170
	global_load_dwordx4 v[142:145], v142, s[100:101] offset:256
	v_mfma_f32_16x16x32_bf16 v[34:37], v[246:249], v[210:213], v[34:37]
	v_mfma_f32_16x16x32_bf16 v[2:5], v[246:249], v[214:217], v[2:5]
	s_waitcnt vmcnt(7)
	ds_write_b128 v171, v[138:141] offset:57344
	v_add_u32_e32 v138, 0x108000, v170
	global_load_dwordx4 v[138:141], v138, s[100:101] offset:256
	v_add_u32_e32 v168, 0x80, v168
	v_add_u32_e32 v170, 0x80, v170
	s_waitcnt lgkmcnt(0)
	s_barrier
	s_cmp_eq_u32 s10, 44
	s_mov_b32 s4, s10
	s_cbranch_scc0 .LBB0_1528
	s_waitcnt vmcnt(4)
	v_add_u32_e32 v110, s7, v206
	s_waitcnt vmcnt(3)
	v_or_b32_e32 v114, v110, v205
	v_cmp_lt_i32_e32 vcc, s97, v114
	v_ashrrev_i32_e32 v112, 31, v114
	v_add_u32_e32 v116, 0xffffc000, v114
	v_ashrrev_i32_e32 v115, 11, v110
	v_cndmask_b32_e64 v113, v112, 0, vcc
	v_cndmask_b32_e32 v112, v114, v116, vcc
	v_mov_b32_e32 v116, s45
	v_mov_b32_e32 v117, s13
	v_mov_b32_e32 v118, s44
	v_mov_b32_e32 v119, s12
	v_or_b32_e32 v110, s6, v208
	s_waitcnt vmcnt(2)
	v_cndmask_b32_e64 v122, v115, 8, vcc
	v_cndmask_b32_e32 v121, v116, v117, vcc
	v_cndmask_b32_e32 v120, v118, v119, vcc
	v_lshlrev_b64 v[112:113], 12, v[112:113]
	v_ashrrev_i32_e32 v111, 31, v110
	v_lshl_add_u64 v[112:113], v[120:121], 0, v[112:113]
	v_mul_hi_i32_i24_e32 v121, 0x9000, v122
	v_mul_i32_i24_e32 v120, 0x9000, v122
	v_lshl_add_u64 v[120:121], s[14:15], 0, v[120:121]
	v_lshlrev_b64 v[110:111], 2, v[110:111]
	s_waitcnt vmcnt(0)
	v_lshl_add_u64 v[128:129], v[120:121], 0, v[110:111]
	global_load_dwordx4 v[120:123], v[128:129], off
	v_lshl_add_u64 v[112:113], v[112:113], 0, v[110:111]
	global_load_dwordx4 v[124:127], v[112:113], off
	s_waitcnt vmcnt(1)
	v_pk_mul_f32 v[120:121], v[120:121], 0.5 op_sel_hi:[1,0]
	v_pk_mul_f32 v[122:123], v[122:123], 0.5 op_sel_hi:[1,0]
	s_waitcnt vmcnt(0)
	v_pk_fma_f32 v[120:121], v[158:159], v[120:121], v[124:125]
	v_pk_fma_f32 v[122:123], v[160:161], v[122:123], v[126:127]
	global_store_dwordx4 v[112:113], v[120:123], off
	global_load_dwordx4 v[120:123], v[128:129], off offset:64
	s_nop 0
	global_load_dwordx4 v[124:127], v[112:113], off offset:64
	s_waitcnt vmcnt(1)
	v_pk_mul_f32 v[120:121], v[120:121], 0.5 op_sel_hi:[1,0]
	v_pk_mul_f32 v[122:123], v[122:123], 0.5 op_sel_hi:[1,0]
	s_waitcnt vmcnt(0)
	v_pk_fma_f32 v[120:121], v[154:155], v[120:121], v[124:125]
	v_pk_fma_f32 v[122:123], v[156:157], v[122:123], v[126:127]
	global_store_dwordx4 v[112:113], v[120:123], off offset:64
	global_load_dwordx4 v[120:123], v[128:129], off offset:128
	s_nop 0
	global_load_dwordx4 v[124:127], v[112:113], off offset:128
	s_waitcnt vmcnt(1)
	v_pk_mul_f32 v[120:121], v[120:121], 0.5 op_sel_hi:[1,0]
	v_pk_mul_f32 v[122:123], v[122:123], 0.5 op_sel_hi:[1,0]
	s_waitcnt vmcnt(0)
	v_pk_fma_f32 v[120:121], v[150:151], v[120:121], v[124:125]
	v_pk_fma_f32 v[122:123], v[152:153], v[122:123], v[126:127]
	global_store_dwordx4 v[112:113], v[120:123], off offset:128
	global_load_dwordx4 v[120:123], v[128:129], off offset:192
	s_nop 0
	global_load_dwordx4 v[124:127], v[112:113], off offset:192
	s_waitcnt vmcnt(1)
	v_pk_mul_f32 v[120:121], v[120:121], 0.5 op_sel_hi:[1,0]
	v_pk_mul_f32 v[122:123], v[122:123], 0.5 op_sel_hi:[1,0]
	s_waitcnt vmcnt(0)
	v_pk_fma_f32 v[120:121], v[146:147], v[120:121], v[124:125]
	v_pk_fma_f32 v[122:123], v[148:149], v[122:123], v[126:127]
	global_store_dwordx4 v[112:113], v[120:123], off offset:192
	global_load_dwordx4 v[120:123], v[128:129], off offset:256
	s_nop 0
	global_load_dwordx4 v[124:127], v[112:113], off offset:256
	s_waitcnt vmcnt(1)
	v_pk_mul_f32 v[120:121], v[120:121], 0.5 op_sel_hi:[1,0]
	v_pk_mul_f32 v[122:123], v[122:123], 0.5 op_sel_hi:[1,0]
	s_waitcnt vmcnt(0)
	v_pk_fma_f32 v[120:121], v[134:135], v[120:121], v[124:125]
	v_pk_fma_f32 v[122:123], v[136:137], v[122:123], v[126:127]
	global_store_dwordx4 v[112:113], v[120:123], off offset:256
	global_load_dwordx4 v[120:123], v[128:129], off offset:320
	s_nop 0
	global_load_dwordx4 v[124:127], v[112:113], off offset:320
	s_waitcnt vmcnt(1)
	v_pk_mul_f32 v[120:121], v[120:121], 0.5 op_sel_hi:[1,0]
	v_pk_mul_f32 v[122:123], v[122:123], 0.5 op_sel_hi:[1,0]
	s_waitcnt vmcnt(0)
	v_pk_fma_f32 v[106:107], v[106:107], v[120:121], v[124:125]
	v_pk_fma_f32 v[108:109], v[108:109], v[122:123], v[126:127]
	global_store_dwordx4 v[112:113], v[106:109], off offset:320
	global_load_dwordx4 v[106:109], v[128:129], off offset:384
	s_nop 0
	global_load_dwordx4 v[120:123], v[112:113], off offset:384
	s_waitcnt vmcnt(1)
	v_pk_mul_f32 v[106:107], v[106:107], 0.5 op_sel_hi:[1,0]
	v_pk_mul_f32 v[108:109], v[108:109], 0.5 op_sel_hi:[1,0]
	s_waitcnt vmcnt(0)
	v_pk_fma_f32 v[102:103], v[102:103], v[106:107], v[120:121]
	v_pk_fma_f32 v[104:105], v[104:105], v[108:109], v[122:123]
	global_store_dwordx4 v[112:113], v[102:105], off offset:384
	global_load_dwordx4 v[102:105], v[128:129], off offset:448
	s_nop 0
	global_load_dwordx4 v[106:109], v[112:113], off offset:448
	s_waitcnt vmcnt(1)
	v_pk_mul_f32 v[102:103], v[102:103], 0.5 op_sel_hi:[1,0]
	v_pk_mul_f32 v[104:105], v[104:105], 0.5 op_sel_hi:[1,0]
	s_waitcnt vmcnt(0)
	v_pk_fma_f32 v[98:99], v[98:99], v[102:103], v[106:107]
	v_pk_fma_f32 v[100:101], v[100:101], v[104:105], v[108:109]
	global_store_dwordx4 v[112:113], v[98:101], off offset:448
	s_nop 1
	v_or_b32_e32 v98, 16, v114
	v_cmp_lt_i32_e32 vcc, s97, v98
	v_add_u32_e32 v100, 0xffffc010, v114
	v_ashrrev_i32_e32 v99, 31, v98
	v_cndmask_b32_e64 v99, v99, 0, vcc
	v_cndmask_b32_e32 v98, v98, v100, vcc
	v_cndmask_b32_e64 v102, v115, 8, vcc
	v_cndmask_b32_e32 v101, v116, v117, vcc
	v_cndmask_b32_e32 v100, v118, v119, vcc
	v_lshlrev_b64 v[98:99], 12, v[98:99]
	v_lshl_add_u64 v[98:99], v[100:101], 0, v[98:99]
	v_mul_hi_i32_i24_e32 v101, 0x9000, v102
	v_mul_i32_i24_e32 v100, 0x9000, v102
	v_lshl_add_u64 v[100:101], s[14:15], 0, v[100:101]
	v_lshl_add_u64 v[108:109], v[100:101], 0, v[110:111]
	global_load_dwordx4 v[100:103], v[108:109], off
	v_lshl_add_u64 v[98:99], v[98:99], 0, v[110:111]
	global_load_dwordx4 v[104:107], v[98:99], off
	s_waitcnt vmcnt(1)
	v_pk_mul_f32 v[100:101], v[100:101], 0.5 op_sel_hi:[1,0]
	v_pk_mul_f32 v[102:103], v[102:103], 0.5 op_sel_hi:[1,0]
	s_waitcnt vmcnt(0)
	v_pk_fma_f32 v[94:95], v[94:95], v[100:101], v[104:105]
	v_pk_fma_f32 v[96:97], v[96:97], v[102:103], v[106:107]
	global_store_dwordx4 v[98:99], v[94:97], off
	global_load_dwordx4 v[94:97], v[108:109], off offset:64
	s_nop 0
	global_load_dwordx4 v[100:103], v[98:99], off offset:64
	s_waitcnt vmcnt(1)
	v_pk_mul_f32 v[94:95], v[94:95], 0.5 op_sel_hi:[1,0]
	v_pk_mul_f32 v[96:97], v[96:97], 0.5 op_sel_hi:[1,0]
	s_waitcnt vmcnt(0)
	v_pk_fma_f32 v[90:91], v[90:91], v[94:95], v[100:101]
	v_pk_fma_f32 v[92:93], v[92:93], v[96:97], v[102:103]
	global_store_dwordx4 v[98:99], v[90:93], off offset:64
	global_load_dwordx4 v[90:93], v[108:109], off offset:128
	s_nop 0
	global_load_dwordx4 v[94:97], v[98:99], off offset:128
	s_waitcnt vmcnt(1)
	v_pk_mul_f32 v[90:91], v[90:91], 0.5 op_sel_hi:[1,0]
	v_pk_mul_f32 v[92:93], v[92:93], 0.5 op_sel_hi:[1,0]
	s_waitcnt vmcnt(0)
	v_pk_fma_f32 v[86:87], v[86:87], v[90:91], v[94:95]
	v_pk_fma_f32 v[88:89], v[88:89], v[92:93], v[96:97]
	global_store_dwordx4 v[98:99], v[86:89], off offset:128
	global_load_dwordx4 v[86:89], v[108:109], off offset:192
	s_nop 0
	global_load_dwordx4 v[90:93], v[98:99], off offset:192
	s_waitcnt vmcnt(1)
	v_pk_mul_f32 v[86:87], v[86:87], 0.5 op_sel_hi:[1,0]
	v_pk_mul_f32 v[88:89], v[88:89], 0.5 op_sel_hi:[1,0]
	s_waitcnt vmcnt(0)
	v_pk_fma_f32 v[82:83], v[82:83], v[86:87], v[90:91]
	v_pk_fma_f32 v[84:85], v[84:85], v[88:89], v[92:93]
	global_store_dwordx4 v[98:99], v[82:85], off offset:192
	global_load_dwordx4 v[82:85], v[108:109], off offset:256
	s_nop 0
	global_load_dwordx4 v[86:89], v[98:99], off offset:256
	s_waitcnt vmcnt(1)
	v_pk_mul_f32 v[82:83], v[82:83], 0.5 op_sel_hi:[1,0]
	v_pk_mul_f32 v[84:85], v[84:85], 0.5 op_sel_hi:[1,0]
	s_waitcnt vmcnt(0)
	v_pk_fma_f32 v[78:79], v[78:79], v[82:83], v[86:87]
	v_pk_fma_f32 v[80:81], v[80:81], v[84:85], v[88:89]
	global_store_dwordx4 v[98:99], v[78:81], off offset:256
	global_load_dwordx4 v[78:81], v[108:109], off offset:320
	s_nop 0
	global_load_dwordx4 v[82:85], v[98:99], off offset:320
	s_waitcnt vmcnt(1)
	v_pk_mul_f32 v[78:79], v[78:79], 0.5 op_sel_hi:[1,0]
	v_pk_mul_f32 v[80:81], v[80:81], 0.5 op_sel_hi:[1,0]
	s_waitcnt vmcnt(0)
	v_pk_fma_f32 v[74:75], v[74:75], v[78:79], v[82:83]
	v_pk_fma_f32 v[76:77], v[76:77], v[80:81], v[84:85]
	global_store_dwordx4 v[98:99], v[74:77], off offset:320
	global_load_dwordx4 v[74:77], v[108:109], off offset:384
	s_nop 0
	global_load_dwordx4 v[78:81], v[98:99], off offset:384
	s_waitcnt vmcnt(1)
	v_pk_mul_f32 v[74:75], v[74:75], 0.5 op_sel_hi:[1,0]
	v_pk_mul_f32 v[76:77], v[76:77], 0.5 op_sel_hi:[1,0]
	s_waitcnt vmcnt(0)
	v_pk_fma_f32 v[70:71], v[70:71], v[74:75], v[78:79]
	v_pk_fma_f32 v[72:73], v[72:73], v[76:77], v[80:81]
	global_store_dwordx4 v[98:99], v[70:73], off offset:384
	global_load_dwordx4 v[70:73], v[108:109], off offset:448
	s_nop 0
	global_load_dwordx4 v[74:77], v[98:99], off offset:448
	s_waitcnt vmcnt(1)
	v_pk_mul_f32 v[70:71], v[70:71], 0.5 op_sel_hi:[1,0]
	v_pk_mul_f32 v[72:73], v[72:73], 0.5 op_sel_hi:[1,0]
	s_waitcnt vmcnt(0)
	v_pk_fma_f32 v[66:67], v[66:67], v[70:71], v[74:75]
	v_pk_fma_f32 v[68:69], v[68:69], v[72:73], v[76:77]
	global_store_dwordx4 v[98:99], v[66:69], off offset:448
	s_nop 1
	v_or_b32_e32 v66, 32, v114
	v_cmp_lt_i32_e32 vcc, s97, v66
	v_add_u32_e32 v68, 0xffffc020, v114
	v_ashrrev_i32_e32 v67, 31, v66
	v_cndmask_b32_e64 v67, v67, 0, vcc
	v_cndmask_b32_e32 v66, v66, v68, vcc
	v_cndmask_b32_e64 v70, v115, 8, vcc
	v_cndmask_b32_e32 v69, v116, v117, vcc
	v_cndmask_b32_e32 v68, v118, v119, vcc
	v_lshlrev_b64 v[66:67], 12, v[66:67]
	v_lshl_add_u64 v[66:67], v[68:69], 0, v[66:67]
	v_mul_hi_i32_i24_e32 v69, 0x9000, v70
	v_mul_i32_i24_e32 v68, 0x9000, v70
	v_lshl_add_u64 v[68:69], s[14:15], 0, v[68:69]
	v_lshl_add_u64 v[76:77], v[68:69], 0, v[110:111]
	global_load_dwordx4 v[68:71], v[76:77], off
	v_lshl_add_u64 v[66:67], v[66:67], 0, v[110:111]
	global_load_dwordx4 v[72:75], v[66:67], off
	s_waitcnt vmcnt(1)
	v_pk_mul_f32 v[68:69], v[68:69], 0.5 op_sel_hi:[1,0]
	v_pk_mul_f32 v[70:71], v[70:71], 0.5 op_sel_hi:[1,0]
	s_waitcnt vmcnt(0)
	v_pk_fma_f32 v[62:63], v[62:63], v[68:69], v[72:73]
	v_pk_fma_f32 v[64:65], v[64:65], v[70:71], v[74:75]
	global_store_dwordx4 v[66:67], v[62:65], off
	global_load_dwordx4 v[62:65], v[76:77], off offset:64
	s_nop 0
	global_load_dwordx4 v[68:71], v[66:67], off offset:64
	s_waitcnt vmcnt(1)
	v_pk_mul_f32 v[62:63], v[62:63], 0.5 op_sel_hi:[1,0]
	v_pk_mul_f32 v[64:65], v[64:65], 0.5 op_sel_hi:[1,0]
	s_waitcnt vmcnt(0)
	v_pk_fma_f32 v[58:59], v[58:59], v[62:63], v[68:69]
	v_pk_fma_f32 v[60:61], v[60:61], v[64:65], v[70:71]
	global_store_dwordx4 v[66:67], v[58:61], off offset:64
	global_load_dwordx4 v[58:61], v[76:77], off offset:128
	s_nop 0
	global_load_dwordx4 v[62:65], v[66:67], off offset:128
	s_waitcnt vmcnt(1)
	v_pk_mul_f32 v[58:59], v[58:59], 0.5 op_sel_hi:[1,0]
	v_pk_mul_f32 v[60:61], v[60:61], 0.5 op_sel_hi:[1,0]
	s_waitcnt vmcnt(0)
	v_pk_fma_f32 v[54:55], v[54:55], v[58:59], v[62:63]
	v_pk_fma_f32 v[56:57], v[56:57], v[60:61], v[64:65]
	global_store_dwordx4 v[66:67], v[54:57], off offset:128
	global_load_dwordx4 v[54:57], v[76:77], off offset:192
	s_nop 0
	global_load_dwordx4 v[58:61], v[66:67], off offset:192
	s_waitcnt vmcnt(1)
	v_pk_mul_f32 v[54:55], v[54:55], 0.5 op_sel_hi:[1,0]
	v_pk_mul_f32 v[56:57], v[56:57], 0.5 op_sel_hi:[1,0]
	s_waitcnt vmcnt(0)
	v_pk_fma_f32 v[50:51], v[50:51], v[54:55], v[58:59]
	v_pk_fma_f32 v[52:53], v[52:53], v[56:57], v[60:61]
	global_store_dwordx4 v[66:67], v[50:53], off offset:192
	global_load_dwordx4 v[50:53], v[76:77], off offset:256
	s_nop 0
	global_load_dwordx4 v[54:57], v[66:67], off offset:256
	s_waitcnt vmcnt(1)
	v_pk_mul_f32 v[50:51], v[50:51], 0.5 op_sel_hi:[1,0]
	v_pk_mul_f32 v[52:53], v[52:53], 0.5 op_sel_hi:[1,0]
	s_waitcnt vmcnt(0)
	v_pk_fma_f32 v[46:47], v[46:47], v[50:51], v[54:55]
	v_pk_fma_f32 v[48:49], v[48:49], v[52:53], v[56:57]
	global_store_dwordx4 v[66:67], v[46:49], off offset:256
	global_load_dwordx4 v[46:49], v[76:77], off offset:320
	s_nop 0
	global_load_dwordx4 v[50:53], v[66:67], off offset:320
	s_waitcnt vmcnt(1)
	v_pk_mul_f32 v[46:47], v[46:47], 0.5 op_sel_hi:[1,0]
	v_pk_mul_f32 v[48:49], v[48:49], 0.5 op_sel_hi:[1,0]
	s_waitcnt vmcnt(0)
	v_pk_fma_f32 v[42:43], v[42:43], v[46:47], v[50:51]
	v_pk_fma_f32 v[44:45], v[44:45], v[48:49], v[52:53]
	global_store_dwordx4 v[66:67], v[42:45], off offset:320
	global_load_dwordx4 v[42:45], v[76:77], off offset:384
	s_nop 0
	global_load_dwordx4 v[46:49], v[66:67], off offset:384
	s_waitcnt vmcnt(1)
	v_pk_mul_f32 v[42:43], v[42:43], 0.5 op_sel_hi:[1,0]
	v_pk_mul_f32 v[44:45], v[44:45], 0.5 op_sel_hi:[1,0]
	s_waitcnt vmcnt(0)
	v_pk_fma_f32 v[38:39], v[38:39], v[42:43], v[46:47]
	v_pk_fma_f32 v[40:41], v[40:41], v[44:45], v[48:49]
	global_store_dwordx4 v[66:67], v[38:41], off offset:384
	global_load_dwordx4 v[38:41], v[76:77], off offset:448
	s_nop 0
	global_load_dwordx4 v[42:45], v[66:67], off offset:448
	s_waitcnt vmcnt(1)
	v_pk_mul_f32 v[38:39], v[38:39], 0.5 op_sel_hi:[1,0]
	v_pk_mul_f32 v[40:41], v[40:41], 0.5 op_sel_hi:[1,0]
	s_waitcnt vmcnt(0)
	v_pk_fma_f32 v[34:35], v[34:35], v[38:39], v[42:43]
	v_pk_fma_f32 v[36:37], v[36:37], v[40:41], v[44:45]
	global_store_dwordx4 v[66:67], v[34:37], off offset:448
	s_nop 1
	v_or_b32_e32 v34, 48, v114
	v_cmp_lt_i32_e32 vcc, s97, v34
	v_add_u32_e32 v36, 0xffffc030, v114
	v_ashrrev_i32_e32 v35, 31, v34
	v_cndmask_b32_e64 v35, v35, 0, vcc
	v_cndmask_b32_e32 v34, v34, v36, vcc
	v_cndmask_b32_e64 v38, v115, 8, vcc
	v_cndmask_b32_e32 v37, v116, v117, vcc
	v_cndmask_b32_e32 v36, v118, v119, vcc
	v_lshlrev_b64 v[34:35], 12, v[34:35]
	v_lshl_add_u64 v[34:35], v[36:37], 0, v[34:35]
	v_mul_hi_i32_i24_e32 v37, 0x9000, v38
	v_mul_i32_i24_e32 v36, 0x9000, v38
	v_lshl_add_u64 v[36:37], s[14:15], 0, v[36:37]
	v_lshl_add_u64 v[44:45], v[36:37], 0, v[110:111]
	global_load_dwordx4 v[36:39], v[44:45], off
	v_lshl_add_u64 v[34:35], v[34:35], 0, v[110:111]
	global_load_dwordx4 v[40:43], v[34:35], off
	s_waitcnt vmcnt(1)
	v_pk_mul_f32 v[36:37], v[36:37], 0.5 op_sel_hi:[1,0]
	v_pk_mul_f32 v[38:39], v[38:39], 0.5 op_sel_hi:[1,0]
	s_waitcnt vmcnt(0)
	v_pk_fma_f32 v[30:31], v[30:31], v[36:37], v[40:41]
	v_pk_fma_f32 v[32:33], v[32:33], v[38:39], v[42:43]
	global_store_dwordx4 v[34:35], v[30:33], off
	global_load_dwordx4 v[30:33], v[44:45], off offset:64
	s_nop 0
	global_load_dwordx4 v[36:39], v[34:35], off offset:64
	s_waitcnt vmcnt(1)
	v_pk_mul_f32 v[30:31], v[30:31], 0.5 op_sel_hi:[1,0]
	v_pk_mul_f32 v[32:33], v[32:33], 0.5 op_sel_hi:[1,0]
	s_waitcnt vmcnt(0)
	v_pk_fma_f32 v[26:27], v[26:27], v[30:31], v[36:37]
	v_pk_fma_f32 v[28:29], v[28:29], v[32:33], v[38:39]
	global_store_dwordx4 v[34:35], v[26:29], off offset:64
	global_load_dwordx4 v[26:29], v[44:45], off offset:128
	s_nop 0
	global_load_dwordx4 v[30:33], v[34:35], off offset:128
	s_waitcnt vmcnt(1)
	v_pk_mul_f32 v[26:27], v[26:27], 0.5 op_sel_hi:[1,0]
	v_pk_mul_f32 v[28:29], v[28:29], 0.5 op_sel_hi:[1,0]
	s_waitcnt vmcnt(0)
	v_pk_fma_f32 v[22:23], v[22:23], v[26:27], v[30:31]
	v_pk_fma_f32 v[24:25], v[24:25], v[28:29], v[32:33]
	global_store_dwordx4 v[34:35], v[22:25], off offset:128
	global_load_dwordx4 v[22:25], v[44:45], off offset:192
	s_nop 0
	global_load_dwordx4 v[26:29], v[34:35], off offset:192
	s_waitcnt vmcnt(1)
	v_pk_mul_f32 v[22:23], v[22:23], 0.5 op_sel_hi:[1,0]
	v_pk_mul_f32 v[24:25], v[24:25], 0.5 op_sel_hi:[1,0]
	s_waitcnt vmcnt(0)
	v_pk_fma_f32 v[18:19], v[18:19], v[22:23], v[26:27]
	v_pk_fma_f32 v[20:21], v[20:21], v[24:25], v[28:29]
	global_store_dwordx4 v[34:35], v[18:21], off offset:192
	global_load_dwordx4 v[18:21], v[44:45], off offset:256
	s_nop 0
	global_load_dwordx4 v[22:25], v[34:35], off offset:256
	s_waitcnt vmcnt(1)
	v_pk_mul_f32 v[18:19], v[18:19], 0.5 op_sel_hi:[1,0]
	v_pk_mul_f32 v[20:21], v[20:21], 0.5 op_sel_hi:[1,0]
	s_waitcnt vmcnt(0)
	v_pk_fma_f32 v[14:15], v[14:15], v[18:19], v[22:23]
	v_pk_fma_f32 v[16:17], v[16:17], v[20:21], v[24:25]
	global_store_dwordx4 v[34:35], v[14:17], off offset:256
	global_load_dwordx4 v[14:17], v[44:45], off offset:320
	s_nop 0
	global_load_dwordx4 v[18:21], v[34:35], off offset:320
	s_waitcnt vmcnt(1)
	v_pk_mul_f32 v[14:15], v[14:15], 0.5 op_sel_hi:[1,0]
	v_pk_mul_f32 v[16:17], v[16:17], 0.5 op_sel_hi:[1,0]
	s_waitcnt vmcnt(0)
	v_pk_fma_f32 v[10:11], v[10:11], v[14:15], v[18:19]
	v_pk_fma_f32 v[12:13], v[12:13], v[16:17], v[20:21]
	global_store_dwordx4 v[34:35], v[10:13], off offset:320
	global_load_dwordx4 v[10:13], v[44:45], off offset:384
	s_nop 0
	global_load_dwordx4 v[14:17], v[34:35], off offset:384
	s_waitcnt vmcnt(1)
	v_pk_mul_f32 v[10:11], v[10:11], 0.5 op_sel_hi:[1,0]
	v_pk_mul_f32 v[12:13], v[12:13], 0.5 op_sel_hi:[1,0]
	s_waitcnt vmcnt(0)
	v_pk_fma_f32 v[6:7], v[6:7], v[10:11], v[14:15]
	v_pk_fma_f32 v[8:9], v[8:9], v[12:13], v[16:17]
	global_store_dwordx4 v[34:35], v[6:9], off offset:384
	global_load_dwordx4 v[6:9], v[44:45], off offset:448
	s_nop 0
	global_load_dwordx4 v[10:13], v[34:35], off offset:448
	s_waitcnt vmcnt(1)
	v_pk_mul_f32 v[6:7], v[6:7], 0.5 op_sel_hi:[1,0]
	v_pk_mul_f32 v[8:9], v[8:9], 0.5 op_sel_hi:[1,0]
	s_waitcnt vmcnt(0)
	v_pk_fma_f32 v[2:3], v[2:3], v[6:7], v[10:11]
	v_pk_fma_f32 v[4:5], v[4:5], v[8:9], v[12:13]
	global_store_dwordx4 v[34:35], v[2:5], off offset:448
	s_add_i32 s18, s18, s11
	s_cmpk_gt_i32 s18, 0xff
	s_cbranch_scc0 .LBB0_1527
